# peer_out LN3: two 5-step wsum butterflies (ds_bpermute) replaced by DPP reduce + readlane broadcast
# baseline (speedup 1.0000x reference)
; DI void phase_peer_out(const Params& p, char* lds) {
;     ...
;     float coefv[2];
; #pragma unroll
;     for (int grp = 0; grp < 2; ++grp) {
;       const float dt = sw[grp * 64 + lane] * USC[el[grp]];
;       const float ge = 0.5f * dt * (1.f + erff(dt * 0.7071067811865476f));
;       coefv[grp] = gl[grp] * ge * VSC[el[grp]];
;     }
;     f32x2 o2[16];
; #pragma unroll
;     for (int i = 0; i < 16; ++i) o2[i] = f32x2{0.f, 0.f};
; #pragma unroll
;     for (int kb = 0; kb < 8; ++kb) {
;       v6u qb[8];
; #pragma unroll
;       for (int k = 0; k < 8; ++k) {
;         const int e0 = __builtin_amdgcn_readlane(el[0], kb * 8 + k), e1 = __builtin_amdgcn_readlane(el[1], kb * 8 + k);
;         qb[k] = load6(V6 + (size_t)(hb ? e1 : e0) * 768);
;       }
; #pragma unroll
;       for (int k = 0; k < 8; ++k) {
;         const float c0 = __uint_as_float(__builtin_amdgcn_readlane(__float_as_uint(coefv[0]), kb * 8 + k)), c1 = __uint_as_float(__builtin_amdgcn_readlane(__float_as_uint(coefv[1]), kb * 8 + k));
;         const float cf = hb ? c1 : c0;
;         const f32x2 c2 = {cf, cf};
;         const v32f f = __builtin_amdgcn_cvt_scalef32_pk32_f32_fp6(qb[k], 1.0f);
; #pragma unroll
;         for (int i = 0; i < 16; ++i) o2[i] = f32x2{f[2 * i], f[2 * i + 1]} * c2 + o2[i];
.LBB0_1186:
	s_or_b64 exec, exec, s[12:13]
	v_lshl_add_u64 v[0:1], v[0:1], 2, s[56:57]
	global_load_dword v12, v[0:1], off
	v_readlane_b32 s12, v108, 0
	v_readlane_b32 s13, v107, 0
	v_readlane_b32 s16, v108, 1
	v_mov_b32_e32 v1, s12
	v_mov_b32_e32 v0, s13
	v_cndmask_b32_e64 v0, v0, v1, s[0:1]
	v_mad_i64_i32 v[0:1], s[12:13], v0, s23, v[64:65]
	v_readlane_b32 s12, v107, 1
	v_add_f32_e32 v5, v128, v5
	global_load_dwordx2 v[132:133], v[0:1], off offset:16
	global_load_dwordx4 v[128:131], v[0:1], off
	v_mov_b32_e32 v0, s12
	v_mov_b32_e32 v1, s16
	v_cndmask_b32_e64 v0, v0, v1, s[0:1]
	v_readlane_b32 s17, v108, 2
	v_readlane_b32 s37, v107, 2
	v_mad_i64_i32 v[0:1], s[12:13], v0, s23, v[64:65]
	global_load_dwordx2 v[138:139], v[0:1], off offset:16
	global_load_dwordx4 v[134:137], v[0:1], off
	v_mov_b32_e32 v0, s37
	v_mov_b32_e32 v1, s17
	v_cndmask_b32_e64 v0, v0, v1, s[0:1]
	v_add_f32_e32 v3, v3, v4
	v_mad_i64_i32 v[0:1], s[12:13], v0, s23, v[64:65]
	v_bfi_b32 v7, s34, v8, v7
	v_mul_f32_e32 v8, 0.5, v10
	v_bfi_b32 v4, s34, v11, v9
	v_readlane_b32 s38, v108, 3
	v_readlane_b32 s39, v107, 3
	v_rcp_f32_e32 v10, v5
	v_rcp_f32_e32 v3, v3
	global_load_dwordx2 v[144:145], v[0:1], off offset:16
	global_load_dwordx4 v[140:143], v[0:1], off
	v_readlane_b32 s40, v108, 4
	v_readlane_b32 s41, v107, 4
	v_readlane_b32 s42, v108, 5
	v_readlane_b32 s43, v107, 5
	v_readlane_b32 s44, v108, 6
	v_readlane_b32 s45, v107, 6
	v_add_f32_e32 v5, 1.0, v7
	v_add_f32_e32 v4, 1.0, v4
	v_mov_b32_e32 v7, s39
	v_mov_b32_e32 v9, s38
	v_mul_f32_e32 v6, 0.5, v6
	v_mov_b32_e32 v11, s41
	v_mov_b32_e32 v13, s40
	v_mov_b32_e32 v14, s43
	v_mov_b32_e32 v15, s42
	v_mov_b32_e32 v16, s45
	v_mov_b32_e32 v17, s44
	v_mul_f32_e32 v19, v8, v4
	v_cndmask_b32_e64 v4, v7, v9, s[0:1]
	v_mul_f32_e32 v18, v6, v5
	v_cndmask_b32_e64 v5, v11, v13, s[0:1]
	v_cndmask_b32_e64 v6, v14, v15, s[0:1]
	v_cndmask_b32_e64 v8, v16, v17, s[0:1]
	v_mad_i64_i32 v[0:1], s[12:13], v4, s23, v[64:65]
	v_mad_i64_i32 v[4:5], s[12:13], v5, s23, v[64:65]
	v_mad_i64_i32 v[6:7], s[12:13], v6, s23, v[64:65]
	v_mad_i64_i32 v[8:9], s[12:13], v8, s23, v[64:65]
	global_load_dwordx4 v[146:149], v[0:1], off
	global_load_dwordx2 v[150:151], v[0:1], off offset:16
	global_load_dwordx4 v[50:53], v[4:5], off
	global_load_dwordx2 v[54:55], v[4:5], off offset:16
	global_load_dwordx4 v[44:47], v[6:7], off
	global_load_dwordx2 v[48:49], v[6:7], off offset:16
	global_load_dwordx4 v[38:41], v[8:9], off
	v_mul_f32_e32 v0, v126, v10
	v_mul_f32_e32 v1, v127, v3
	v_mul_f32_e32 v0, v0, v18
	v_mul_f32_e32 v1, v1, v19
	v_readlane_b32 s12, v108, 7
	v_readlane_b32 s13, v107, 7
	s_waitcnt vmcnt(14)
	v_mul_f32_e32 v106, v2, v0
	s_waitcnt vmcnt(13)
	v_mul_f32_e32 v109, v12, v1
	v_mov_b32_e32 v0, s13
	v_mov_b32_e32 v1, s12
	v_cndmask_b32_e64 v0, v0, v1, s[0:1]
	v_mad_i64_i32 v[0:1], s[12:13], v0, s23, v[64:65]
	global_load_dwordx2 v[36:37], v[0:1], off offset:16
	global_load_dwordx2 v[42:43], v[8:9], off offset:16
	global_load_dwordx4 v[32:35], v[0:1], off
	v_readlane_b32 s12, v106, 0
	v_readlane_b32 s13, v109, 0
	s_nop 0
	v_mov_b32_e32 v1, s12
	v_mov_b32_e32 v0, s13
	v_cndmask_b32_e64 v126, v0, v1, s[0:1]
	s_waitcnt vmcnt(14)
	v_cvt_scalef32_pk32_f32_fp6 v[0:31], v[128:133], 1.0
	v_readlane_b32 s12, v106, 1
	v_readlane_b32 s13, v109, 1
	v_pk_fma_f32 v[128:129], v[0:1], v[126:127], 0 op_sel_hi:[1,0,0]
	v_mov_b32_e32 v1, s12
	v_mov_b32_e32 v0, s13
	v_pk_fma_f32 v[130:131], v[2:3], v[126:127], 0 op_sel_hi:[1,0,0]
	v_pk_fma_f32 v[132:133], v[4:5], v[126:127], 0 op_sel_hi:[1,0,0]
	v_pk_fma_f32 v[152:153], v[6:7], v[126:127], 0 op_sel_hi:[1,0,0]
	v_pk_fma_f32 v[154:155], v[8:9], v[126:127], 0 op_sel_hi:[1,0,0]
	v_pk_fma_f32 v[156:157], v[10:11], v[126:127], 0 op_sel_hi:[1,0,0]
	v_pk_fma_f32 v[158:159], v[12:13], v[126:127], 0 op_sel_hi:[1,0,0]
	v_pk_fma_f32 v[160:161], v[14:15], v[126:127], 0 op_sel_hi:[1,0,0]
	v_pk_fma_f32 v[162:163], v[16:17], v[126:127], 0 op_sel_hi:[1,0,0]
	v_pk_fma_f32 v[164:165], v[18:19], v[126:127], 0 op_sel_hi:[1,0,0]
	v_pk_fma_f32 v[166:167], v[20:21], v[126:127], 0 op_sel_hi:[1,0,0]
	v_pk_fma_f32 v[168:169], v[22:23], v[126:127], 0 op_sel_hi:[1,0,0]
	v_pk_fma_f32 v[170:171], v[24:25], v[126:127], 0 op_sel_hi:[1,0,0]
	v_pk_fma_f32 v[172:173], v[26:27], v[126:127], 0 op_sel_hi:[1,0,0]
	v_pk_fma_f32 v[174:175], v[28:29], v[126:127], 0 op_sel_hi:[1,0,0]
	v_pk_fma_f32 v[126:127], v[30:31], v[126:127], 0 op_sel_hi:[1,0,0]
	v_cndmask_b32_e64 v176, v0, v1, s[0:1]
	s_waitcnt vmcnt(12)
	v_cvt_scalef32_pk32_f32_fp6 v[0:31], v[134:139], 1.0
	v_readlane_b32 s12, v106, 2
	v_readlane_b32 s13, v109, 2
	v_pk_fma_f32 v[128:129], v[0:1], v[176:177], v[128:129] op_sel_hi:[1,0,1]
	v_mov_b32_e32 v1, s12
	v_mov_b32_e32 v0, s13
	v_pk_fma_f32 v[130:131], v[2:3], v[176:177], v[130:131] op_sel_hi:[1,0,1]
	v_pk_fma_f32 v[132:133], v[4:5], v[176:177], v[132:133] op_sel_hi:[1,0,1]
	v_pk_fma_f32 v[134:135], v[6:7], v[176:177], v[152:153] op_sel_hi:[1,0,1]
	v_pk_fma_f32 v[136:137], v[8:9], v[176:177], v[154:155] op_sel_hi:[1,0,1]
	v_pk_fma_f32 v[138:139], v[10:11], v[176:177], v[156:157] op_sel_hi:[1,0,1]
	v_pk_fma_f32 v[152:153], v[12:13], v[176:177], v[158:159] op_sel_hi:[1,0,1]
	v_pk_fma_f32 v[154:155], v[14:15], v[176:177], v[160:161] op_sel_hi:[1,0,1]
	v_pk_fma_f32 v[156:157], v[16:17], v[176:177], v[162:163] op_sel_hi:[1,0,1]
	v_pk_fma_f32 v[158:159], v[18:19], v[176:177], v[164:165] op_sel_hi:[1,0,1]
	v_pk_fma_f32 v[160:161], v[20:21], v[176:177], v[166:167] op_sel_hi:[1,0,1]
	v_pk_fma_f32 v[162:163], v[22:23], v[176:177], v[168:169] op_sel_hi:[1,0,1]
	v_pk_fma_f32 v[164:165], v[24:25], v[176:177], v[170:171] op_sel_hi:[1,0,1]
	v_pk_fma_f32 v[166:167], v[26:27], v[176:177], v[172:173] op_sel_hi:[1,0,1]
	v_pk_fma_f32 v[168:169], v[28:29], v[176:177], v[174:175] op_sel_hi:[1,0,1]
	v_pk_fma_f32 v[126:127], v[30:31], v[176:177], v[126:127] op_sel_hi:[1,0,1]
	v_cndmask_b32_e64 v170, v0, v1, s[0:1]
	s_waitcnt vmcnt(10)
; DI void phase_peer_out(const Params& p, char* lds) {
;     ...
; #pragma unroll
;     for (int kb = 0; kb < 8; ++kb) {
;       v6u qb[8];
; #pragma unroll
;       for (int k = 0; k < 8; ++k) {
;         const int e0 = __builtin_amdgcn_readlane(el[0], kb * 8 + k), e1 = __builtin_amdgcn_readlane(el[1], kb * 8 + k);
;         qb[k] = load6(V6 + (size_t)(hb ? e1 : e0) * 768);
;       }
; #pragma unroll
;       for (int k = 0; k < 8; ++k) {
;         const float c0 = __uint_as_float(__builtin_amdgcn_readlane(__float_as_uint(coefv[0]), kb * 8 + k)), c1 = __uint_as_float(__builtin_amdgcn_readlane(__float_as_uint(coefv[1]), kb * 8 + k));
;         const float cf = hb ? c1 : c0;
;         const f32x2 c2 = {cf, cf};
;         const v32f f = __builtin_amdgcn_cvt_scalef32_pk32_f32_fp6(qb[k], 1.0f);
; #pragma unroll
;         for (int i = 0; i < 16; ++i) o2[i] = f32x2{f[2 * i], f[2 * i + 1]} * c2 + o2[i];
;       }
;     }
	v_cvt_scalef32_pk32_f32_fp6 v[0:31], v[140:145], 1.0
	v_readlane_b32 s12, v106, 3
	v_readlane_b32 s13, v109, 3
	v_pk_fma_f32 v[128:129], v[0:1], v[170:171], v[128:129] op_sel_hi:[1,0,1]
	v_mov_b32_e32 v1, s12
	v_mov_b32_e32 v0, s13
	v_pk_fma_f32 v[130:131], v[2:3], v[170:171], v[130:131] op_sel_hi:[1,0,1]
	v_pk_fma_f32 v[132:133], v[4:5], v[170:171], v[132:133] op_sel_hi:[1,0,1]
	v_pk_fma_f32 v[134:135], v[6:7], v[170:171], v[134:135] op_sel_hi:[1,0,1]
	v_pk_fma_f32 v[136:137], v[8:9], v[170:171], v[136:137] op_sel_hi:[1,0,1]
	v_pk_fma_f32 v[138:139], v[10:11], v[170:171], v[138:139] op_sel_hi:[1,0,1]
	v_pk_fma_f32 v[140:141], v[12:13], v[170:171], v[152:153] op_sel_hi:[1,0,1]
	v_pk_fma_f32 v[142:143], v[14:15], v[170:171], v[154:155] op_sel_hi:[1,0,1]
	v_pk_fma_f32 v[144:145], v[16:17], v[170:171], v[156:157] op_sel_hi:[1,0,1]
	v_pk_fma_f32 v[152:153], v[18:19], v[170:171], v[158:159] op_sel_hi:[1,0,1]
	v_pk_fma_f32 v[154:155], v[20:21], v[170:171], v[160:161] op_sel_hi:[1,0,1]
	v_pk_fma_f32 v[156:157], v[22:23], v[170:171], v[162:163] op_sel_hi:[1,0,1]
	v_pk_fma_f32 v[158:159], v[24:25], v[170:171], v[164:165] op_sel_hi:[1,0,1]
	v_pk_fma_f32 v[160:161], v[26:27], v[170:171], v[166:167] op_sel_hi:[1,0,1]
	v_pk_fma_f32 v[162:163], v[28:29], v[170:171], v[168:169] op_sel_hi:[1,0,1]
	v_pk_fma_f32 v[126:127], v[30:31], v[170:171], v[126:127] op_sel_hi:[1,0,1]
	v_cndmask_b32_e64 v164, v0, v1, s[0:1]
	s_waitcnt vmcnt(8)
	v_cvt_scalef32_pk32_f32_fp6 v[0:31], v[146:151], 1.0
	v_readlane_b32 s12, v106, 4
	v_readlane_b32 s13, v109, 4
	v_pk_fma_f32 v[128:129], v[0:1], v[164:165], v[128:129] op_sel_hi:[1,0,1]
	v_mov_b32_e32 v1, s12
	v_mov_b32_e32 v0, s13
	v_pk_fma_f32 v[130:131], v[2:3], v[164:165], v[130:131] op_sel_hi:[1,0,1]
	v_pk_fma_f32 v[132:133], v[4:5], v[164:165], v[132:133] op_sel_hi:[1,0,1]
	v_pk_fma_f32 v[134:135], v[6:7], v[164:165], v[134:135] op_sel_hi:[1,0,1]
	v_pk_fma_f32 v[136:137], v[8:9], v[164:165], v[136:137] op_sel_hi:[1,0,1]
	v_pk_fma_f32 v[138:139], v[10:11], v[164:165], v[138:139] op_sel_hi:[1,0,1]
	v_pk_fma_f32 v[140:141], v[12:13], v[164:165], v[140:141] op_sel_hi:[1,0,1]
	v_pk_fma_f32 v[142:143], v[14:15], v[164:165], v[142:143] op_sel_hi:[1,0,1]
	v_pk_fma_f32 v[144:145], v[16:17], v[164:165], v[144:145] op_sel_hi:[1,0,1]
	v_pk_fma_f32 v[146:147], v[18:19], v[164:165], v[152:153] op_sel_hi:[1,0,1]
	v_pk_fma_f32 v[148:149], v[20:21], v[164:165], v[154:155] op_sel_hi:[1,0,1]
	v_pk_fma_f32 v[150:151], v[22:23], v[164:165], v[156:157] op_sel_hi:[1,0,1]
	v_pk_fma_f32 v[152:153], v[24:25], v[164:165], v[158:159] op_sel_hi:[1,0,1]
	v_pk_fma_f32 v[154:155], v[26:27], v[164:165], v[160:161] op_sel_hi:[1,0,1]
	v_pk_fma_f32 v[156:157], v[28:29], v[164:165], v[162:163] op_sel_hi:[1,0,1]
	v_pk_fma_f32 v[126:127], v[30:31], v[164:165], v[126:127] op_sel_hi:[1,0,1]
	v_cndmask_b32_e64 v158, v0, v1, s[0:1]
	s_waitcnt vmcnt(6)
	v_cvt_scalef32_pk32_f32_fp6 v[0:31], v[50:55], 1.0
	v_readlane_b32 s12, v106, 5
	v_readlane_b32 s13, v109, 5
	v_pk_fma_f32 v[50:51], v[0:1], v[158:159], v[128:129] op_sel_hi:[1,0,1]
	v_mov_b32_e32 v1, s12
	v_mov_b32_e32 v0, s13
	v_pk_fma_f32 v[52:53], v[2:3], v[158:159], v[130:131] op_sel_hi:[1,0,1]
	v_pk_fma_f32 v[54:55], v[4:5], v[158:159], v[132:133] op_sel_hi:[1,0,1]
	v_pk_fma_f32 v[128:129], v[6:7], v[158:159], v[134:135] op_sel_hi:[1,0,1]
	v_pk_fma_f32 v[130:131], v[8:9], v[158:159], v[136:137] op_sel_hi:[1,0,1]
	v_pk_fma_f32 v[132:133], v[10:11], v[158:159], v[138:139] op_sel_hi:[1,0,1]
	v_pk_fma_f32 v[134:135], v[12:13], v[158:159], v[140:141] op_sel_hi:[1,0,1]
	v_pk_fma_f32 v[136:137], v[14:15], v[158:159], v[142:143] op_sel_hi:[1,0,1]
	v_pk_fma_f32 v[138:139], v[16:17], v[158:159], v[144:145] op_sel_hi:[1,0,1]
	v_pk_fma_f32 v[140:141], v[18:19], v[158:159], v[146:147] op_sel_hi:[1,0,1]
	v_pk_fma_f32 v[142:143], v[20:21], v[158:159], v[148:149] op_sel_hi:[1,0,1]
	v_pk_fma_f32 v[144:145], v[22:23], v[158:159], v[150:151] op_sel_hi:[1,0,1]
	v_pk_fma_f32 v[146:147], v[24:25], v[158:159], v[152:153] op_sel_hi:[1,0,1]
	v_pk_fma_f32 v[148:149], v[26:27], v[158:159], v[154:155] op_sel_hi:[1,0,1]
	v_pk_fma_f32 v[150:151], v[28:29], v[158:159], v[156:157] op_sel_hi:[1,0,1]
	v_pk_fma_f32 v[126:127], v[30:31], v[158:159], v[126:127] op_sel_hi:[1,0,1]
	v_cndmask_b32_e64 v152, v0, v1, s[0:1]
	s_waitcnt vmcnt(4)
	v_cvt_scalef32_pk32_f32_fp6 v[0:31], v[44:49], 1.0
	v_readlane_b32 s12, v106, 6
	v_readlane_b32 s13, v109, 6
	v_pk_fma_f32 v[44:45], v[0:1], v[152:153], v[50:51] op_sel_hi:[1,0,1]
	v_mov_b32_e32 v1, s12
	v_mov_b32_e32 v0, s13
	v_pk_fma_f32 v[46:47], v[2:3], v[152:153], v[52:53] op_sel_hi:[1,0,1]
	v_pk_fma_f32 v[48:49], v[4:5], v[152:153], v[54:55] op_sel_hi:[1,0,1]
	v_pk_fma_f32 v[50:51], v[6:7], v[152:153], v[128:129] op_sel_hi:[1,0,1]
	v_pk_fma_f32 v[52:53], v[8:9], v[152:153], v[130:131] op_sel_hi:[1,0,1]
	v_pk_fma_f32 v[54:55], v[10:11], v[152:153], v[132:133] op_sel_hi:[1,0,1]
	v_pk_fma_f32 v[128:129], v[12:13], v[152:153], v[134:135] op_sel_hi:[1,0,1]
	v_pk_fma_f32 v[130:131], v[14:15], v[152:153], v[136:137] op_sel_hi:[1,0,1]
	v_pk_fma_f32 v[132:133], v[16:17], v[152:153], v[138:139] op_sel_hi:[1,0,1]
	v_pk_fma_f32 v[134:135], v[18:19], v[152:153], v[140:141] op_sel_hi:[1,0,1]
	v_pk_fma_f32 v[136:137], v[20:21], v[152:153], v[142:143] op_sel_hi:[1,0,1]
	v_pk_fma_f32 v[138:139], v[22:23], v[152:153], v[144:145] op_sel_hi:[1,0,1]
	v_pk_fma_f32 v[140:141], v[24:25], v[152:153], v[146:147] op_sel_hi:[1,0,1]
	v_pk_fma_f32 v[142:143], v[26:27], v[152:153], v[148:149] op_sel_hi:[1,0,1]
	v_pk_fma_f32 v[144:145], v[28:29], v[152:153], v[150:151] op_sel_hi:[1,0,1]
	v_pk_fma_f32 v[126:127], v[30:31], v[152:153], v[126:127] op_sel_hi:[1,0,1]
	v_cndmask_b32_e64 v146, v0, v1, s[0:1]
	s_waitcnt vmcnt(1)
; DI void phase_peer_out(const Params& p, char* lds) {
;     ...
; #pragma unroll
;     for (int kb = 0; kb < 8; ++kb) {
;       v6u qb[8];
; #pragma unroll
;       for (int k = 0; k < 8; ++k) {
;         const int e0 = __builtin_amdgcn_readlane(el[0], kb * 8 + k), e1 = __builtin_amdgcn_readlane(el[1], kb * 8 + k);
;         qb[k] = load6(V6 + (size_t)(hb ? e1 : e0) * 768);
;       }
; #pragma unroll
;       for (int k = 0; k < 8; ++k) {
;         const float c0 = __uint_as_float(__builtin_amdgcn_readlane(__float_as_uint(coefv[0]), kb * 8 + k)), c1 = __uint_as_float(__builtin_amdgcn_readlane(__float_as_uint(coefv[1]), kb * 8 + k));
;         const float cf = hb ? c1 : c0;
;         const f32x2 c2 = {cf, cf};
;         const v32f f = __builtin_amdgcn_cvt_scalef32_pk32_f32_fp6(qb[k], 1.0f);
; #pragma unroll
;         for (int i = 0; i < 16; ++i) o2[i] = f32x2{f[2 * i], f[2 * i + 1]} * c2 + o2[i];
;       }
;     }
	v_cvt_scalef32_pk32_f32_fp6 v[0:31], v[38:43], 1.0
	v_readlane_b32 s12, v106, 7
	v_readlane_b32 s13, v109, 7
	v_pk_fma_f32 v[38:39], v[0:1], v[146:147], v[44:45] op_sel_hi:[1,0,1]
	v_mov_b32_e32 v1, s12
	v_mov_b32_e32 v0, s13
	v_readlane_b32 s12, v108, 8
	v_readlane_b32 s13, v107, 8
	v_pk_fma_f32 v[40:41], v[2:3], v[146:147], v[46:47] op_sel_hi:[1,0,1]
	v_pk_fma_f32 v[42:43], v[4:5], v[146:147], v[48:49] op_sel_hi:[1,0,1]
	v_pk_fma_f32 v[44:45], v[6:7], v[146:147], v[50:51] op_sel_hi:[1,0,1]
	v_pk_fma_f32 v[46:47], v[8:9], v[146:147], v[52:53] op_sel_hi:[1,0,1]
	v_pk_fma_f32 v[48:49], v[10:11], v[146:147], v[54:55] op_sel_hi:[1,0,1]
	v_pk_fma_f32 v[50:51], v[12:13], v[146:147], v[128:129] op_sel_hi:[1,0,1]
	v_pk_fma_f32 v[52:53], v[14:15], v[146:147], v[130:131] op_sel_hi:[1,0,1]
	v_pk_fma_f32 v[54:55], v[16:17], v[146:147], v[132:133] op_sel_hi:[1,0,1]
	v_pk_fma_f32 v[132:133], v[18:19], v[146:147], v[134:135] op_sel_hi:[1,0,1]
	v_pk_fma_f32 v[134:135], v[20:21], v[146:147], v[136:137] op_sel_hi:[1,0,1]
	v_pk_fma_f32 v[136:137], v[22:23], v[146:147], v[138:139] op_sel_hi:[1,0,1]
	v_pk_fma_f32 v[138:139], v[24:25], v[146:147], v[140:141] op_sel_hi:[1,0,1]
	v_pk_fma_f32 v[140:141], v[26:27], v[146:147], v[142:143] op_sel_hi:[1,0,1]
	v_pk_fma_f32 v[142:143], v[28:29], v[146:147], v[144:145] op_sel_hi:[1,0,1]
	v_pk_fma_f32 v[144:145], v[30:31], v[146:147], v[126:127] op_sel_hi:[1,0,1]
	v_cndmask_b32_e64 v146, v0, v1, s[0:1]
	v_mov_b32_e32 v0, s13
	v_mov_b32_e32 v1, s12
	v_cndmask_b32_e64 v0, v0, v1, s[0:1]
	v_mad_i64_i32 v[130:131], s[12:13], v0, s23, v[64:65]
	s_waitcnt vmcnt(0)
	v_cvt_scalef32_pk32_f32_fp6 v[0:31], v[32:37], 1.0
	v_readlane_b32 s12, v108, 9
	v_readlane_b32 s13, v107, 9
	v_pk_fma_f32 v[150:151], v[0:1], v[146:147], v[38:39] op_sel_hi:[1,0,1]
	v_mov_b32_e32 v1, s12
	v_mov_b32_e32 v0, s13
	v_cndmask_b32_e64 v0, v0, v1, s[0:1]
	v_mad_i64_i32 v[0:1], s[12:13], v0, s23, v[64:65]
	v_readlane_b32 s12, v108, 10
	v_readlane_b32 s13, v107, 10
	global_load_dwordx4 v[126:129], v[130:131], off
	v_pk_fma_f32 v[168:169], v[18:19], v[146:147], v[132:133] op_sel_hi:[1,0,1]
	global_load_dwordx2 v[130:131], v[130:131], off offset:16
	v_pk_fma_f32 v[170:171], v[20:21], v[146:147], v[134:135] op_sel_hi:[1,0,1]
	v_pk_fma_f32 v[172:173], v[22:23], v[146:147], v[136:137] op_sel_hi:[1,0,1]
	global_load_dwordx2 v[136:137], v[0:1], off offset:16
	global_load_dwordx4 v[132:135], v[0:1], off
	v_mov_b32_e32 v0, s13
	v_mov_b32_e32 v1, s12
	v_cndmask_b32_e64 v0, v0, v1, s[0:1]
	v_mad_i64_i32 v[0:1], s[12:13], v0, s23, v[64:65]
	v_readlane_b32 s12, v108, 11
	v_readlane_b32 s13, v107, 11
	v_pk_fma_f32 v[152:153], v[2:3], v[146:147], v[40:41] op_sel_hi:[1,0,1]
	v_mov_b32_e32 v3, s12
	v_mov_b32_e32 v2, s13
	v_cndmask_b32_e64 v2, v2, v3, s[0:1]
	v_mad_i64_i32 v[2:3], s[12:13], v2, s23, v[64:65]
	v_readlane_b32 s12, v108, 12
	v_readlane_b32 s13, v107, 12
	v_pk_fma_f32 v[154:155], v[4:5], v[146:147], v[42:43] op_sel_hi:[1,0,1]
	v_pk_fma_f32 v[156:157], v[6:7], v[146:147], v[44:45] op_sel_hi:[1,0,1]
	v_pk_fma_f32 v[158:159], v[8:9], v[146:147], v[46:47] op_sel_hi:[1,0,1]
	v_pk_fma_f32 v[160:161], v[10:11], v[146:147], v[48:49] op_sel_hi:[1,0,1]
	v_pk_fma_f32 v[162:163], v[12:13], v[146:147], v[50:51] op_sel_hi:[1,0,1]
	v_pk_fma_f32 v[164:165], v[14:15], v[146:147], v[52:53] op_sel_hi:[1,0,1]
	v_pk_fma_f32 v[166:167], v[16:17], v[146:147], v[54:55] op_sel_hi:[1,0,1]
	v_pk_fma_f32 v[174:175], v[24:25], v[146:147], v[138:139] op_sel_hi:[1,0,1]
	v_pk_fma_f32 v[176:177], v[26:27], v[146:147], v[140:141] op_sel_hi:[1,0,1]
	v_pk_fma_f32 v[178:179], v[28:29], v[146:147], v[142:143] op_sel_hi:[1,0,1]
	v_pk_fma_f32 v[180:181], v[30:31], v[146:147], v[144:145] op_sel_hi:[1,0,1]
	global_load_dwordx4 v[138:141], v[0:1], off
	global_load_dwordx2 v[142:143], v[0:1], off offset:16
	global_load_dwordx4 v[144:147], v[2:3], off
	v_mov_b32_e32 v0, s13
	v_mov_b32_e32 v1, s12
	v_cndmask_b32_e64 v0, v0, v1, s[0:1]
	v_mad_i64_i32 v[0:1], s[12:13], v0, s23, v[64:65]
	v_readlane_b32 s12, v108, 13
	v_readlane_b32 s13, v107, 13
	global_load_dwordx2 v[148:149], v[2:3], off offset:16
	global_load_dwordx4 v[50:53], v[0:1], off
	v_mov_b32_e32 v2, s13
	v_mov_b32_e32 v3, s12
	v_cndmask_b32_e64 v2, v2, v3, s[0:1]
	v_mad_i64_i32 v[2:3], s[12:13], v2, s23, v[64:65]
	v_readlane_b32 s12, v108, 14
	v_readlane_b32 s13, v107, 14
	global_load_dwordx2 v[54:55], v[0:1], off offset:16
	global_load_dwordx4 v[44:47], v[2:3], off
	v_mov_b32_e32 v0, s13
	v_mov_b32_e32 v1, s12
	v_cndmask_b32_e64 v0, v0, v1, s[0:1]
	v_mad_i64_i32 v[0:1], s[12:13], v0, s23, v[64:65]
	v_readlane_b32 s12, v108, 15
	v_readlane_b32 s13, v107, 15
	global_load_dwordx2 v[48:49], v[2:3], off offset:16
	global_load_dwordx4 v[38:41], v[0:1], off
	v_mov_b32_e32 v2, s13
	v_mov_b32_e32 v3, s12
	v_cndmask_b32_e64 v2, v2, v3, s[0:1]
	v_mad_i64_i32 v[2:3], s[12:13], v2, s23, v[64:65]
	global_load_dwordx2 v[36:37], v[2:3], off offset:16
	global_load_dwordx2 v[42:43], v[0:1], off offset:16
	global_load_dwordx4 v[32:35], v[2:3], off
	v_readlane_b32 s12, v106, 8
	v_readlane_b32 s13, v109, 8
	s_nop 0
	v_mov_b32_e32 v1, s12
	v_mov_b32_e32 v0, s13
	v_cndmask_b32_e64 v182, v0, v1, s[0:1]
	v_readlane_b32 s12, v106, 9
	v_readlane_b32 s13, v109, 9
	s_waitcnt vmcnt(14)
; DI void phase_peer_out(const Params& p, char* lds) {
;     ...
; #pragma unroll
;     for (int kb = 0; kb < 8; ++kb) {
;       v6u qb[8];
; #pragma unroll
;       for (int k = 0; k < 8; ++k) {
;         const int e0 = __builtin_amdgcn_readlane(el[0], kb * 8 + k), e1 = __builtin_amdgcn_readlane(el[1], kb * 8 + k);
;         qb[k] = load6(V6 + (size_t)(hb ? e1 : e0) * 768);
;       }
; #pragma unroll
;       for (int k = 0; k < 8; ++k) {
;         const float c0 = __uint_as_float(__builtin_amdgcn_readlane(__float_as_uint(coefv[0]), kb * 8 + k)), c1 = __uint_as_float(__builtin_amdgcn_readlane(__float_as_uint(coefv[1]), kb * 8 + k));
;         const float cf = hb ? c1 : c0;
;         const f32x2 c2 = {cf, cf};
;         const v32f f = __builtin_amdgcn_cvt_scalef32_pk32_f32_fp6(qb[k], 1.0f);
; #pragma unroll
;         for (int i = 0; i < 16; ++i) o2[i] = f32x2{f[2 * i], f[2 * i + 1]} * c2 + o2[i];
;       }
;     }
	v_cvt_scalef32_pk32_f32_fp6 v[0:31], v[126:131], 1.0
	v_pk_fma_f32 v[126:127], v[0:1], v[182:183], v[150:151] op_sel_hi:[1,0,1]
	v_mov_b32_e32 v0, s13
	v_mov_b32_e32 v1, s12
	v_pk_fma_f32 v[128:129], v[2:3], v[182:183], v[152:153] op_sel_hi:[1,0,1]
	v_pk_fma_f32 v[130:131], v[4:5], v[182:183], v[154:155] op_sel_hi:[1,0,1]
	v_pk_fma_f32 v[150:151], v[6:7], v[182:183], v[156:157] op_sel_hi:[1,0,1]
	v_pk_fma_f32 v[152:153], v[8:9], v[182:183], v[158:159] op_sel_hi:[1,0,1]
	v_pk_fma_f32 v[154:155], v[10:11], v[182:183], v[160:161] op_sel_hi:[1,0,1]
	v_pk_fma_f32 v[156:157], v[12:13], v[182:183], v[162:163] op_sel_hi:[1,0,1]
	v_pk_fma_f32 v[158:159], v[14:15], v[182:183], v[164:165] op_sel_hi:[1,0,1]
	v_pk_fma_f32 v[160:161], v[16:17], v[182:183], v[166:167] op_sel_hi:[1,0,1]
	v_pk_fma_f32 v[162:163], v[18:19], v[182:183], v[168:169] op_sel_hi:[1,0,1]
	v_pk_fma_f32 v[164:165], v[20:21], v[182:183], v[170:171] op_sel_hi:[1,0,1]
	v_pk_fma_f32 v[166:167], v[22:23], v[182:183], v[172:173] op_sel_hi:[1,0,1]
	v_pk_fma_f32 v[168:169], v[24:25], v[182:183], v[174:175] op_sel_hi:[1,0,1]
	v_pk_fma_f32 v[170:171], v[26:27], v[182:183], v[176:177] op_sel_hi:[1,0,1]
	v_pk_fma_f32 v[172:173], v[28:29], v[182:183], v[178:179] op_sel_hi:[1,0,1]
	v_pk_fma_f32 v[174:175], v[30:31], v[182:183], v[180:181] op_sel_hi:[1,0,1]
	v_cndmask_b32_e64 v176, v0, v1, s[0:1]
	s_waitcnt vmcnt(12)
	v_cvt_scalef32_pk32_f32_fp6 v[0:31], v[132:137], 1.0
	v_readlane_b32 s12, v106, 10
	v_readlane_b32 s13, v109, 10
	v_pk_fma_f32 v[126:127], v[0:1], v[176:177], v[126:127] op_sel_hi:[1,0,1]
	v_mov_b32_e32 v1, s12
	v_mov_b32_e32 v0, s13
	v_pk_fma_f32 v[128:129], v[2:3], v[176:177], v[128:129] op_sel_hi:[1,0,1]
	v_pk_fma_f32 v[130:131], v[4:5], v[176:177], v[130:131] op_sel_hi:[1,0,1]
	v_pk_fma_f32 v[132:133], v[6:7], v[176:177], v[150:151] op_sel_hi:[1,0,1]
	v_pk_fma_f32 v[134:135], v[8:9], v[176:177], v[152:153] op_sel_hi:[1,0,1]
	v_pk_fma_f32 v[136:137], v[10:11], v[176:177], v[154:155] op_sel_hi:[1,0,1]
	v_pk_fma_f32 v[150:151], v[12:13], v[176:177], v[156:157] op_sel_hi:[1,0,1]
	v_pk_fma_f32 v[152:153], v[14:15], v[176:177], v[158:159] op_sel_hi:[1,0,1]
	v_pk_fma_f32 v[154:155], v[16:17], v[176:177], v[160:161] op_sel_hi:[1,0,1]
	v_pk_fma_f32 v[156:157], v[18:19], v[176:177], v[162:163] op_sel_hi:[1,0,1]
	v_pk_fma_f32 v[158:159], v[20:21], v[176:177], v[164:165] op_sel_hi:[1,0,1]
	v_pk_fma_f32 v[160:161], v[22:23], v[176:177], v[166:167] op_sel_hi:[1,0,1]
	v_pk_fma_f32 v[162:163], v[24:25], v[176:177], v[168:169] op_sel_hi:[1,0,1]
	v_pk_fma_f32 v[164:165], v[26:27], v[176:177], v[170:171] op_sel_hi:[1,0,1]
	v_pk_fma_f32 v[166:167], v[28:29], v[176:177], v[172:173] op_sel_hi:[1,0,1]
	v_pk_fma_f32 v[168:169], v[30:31], v[176:177], v[174:175] op_sel_hi:[1,0,1]
	v_cndmask_b32_e64 v170, v0, v1, s[0:1]
	s_waitcnt vmcnt(10)
	v_cvt_scalef32_pk32_f32_fp6 v[0:31], v[138:143], 1.0
	v_readlane_b32 s12, v106, 11
	v_readlane_b32 s13, v109, 11
	v_pk_fma_f32 v[126:127], v[0:1], v[170:171], v[126:127] op_sel_hi:[1,0,1]
	v_mov_b32_e32 v1, s12
	v_mov_b32_e32 v0, s13
	v_pk_fma_f32 v[128:129], v[2:3], v[170:171], v[128:129] op_sel_hi:[1,0,1]
	v_pk_fma_f32 v[130:131], v[4:5], v[170:171], v[130:131] op_sel_hi:[1,0,1]
	v_pk_fma_f32 v[132:133], v[6:7], v[170:171], v[132:133] op_sel_hi:[1,0,1]
	v_pk_fma_f32 v[134:135], v[8:9], v[170:171], v[134:135] op_sel_hi:[1,0,1]
	v_pk_fma_f32 v[136:137], v[10:11], v[170:171], v[136:137] op_sel_hi:[1,0,1]
	v_pk_fma_f32 v[138:139], v[12:13], v[170:171], v[150:151] op_sel_hi:[1,0,1]
	v_pk_fma_f32 v[140:141], v[14:15], v[170:171], v[152:153] op_sel_hi:[1,0,1]
	v_pk_fma_f32 v[142:143], v[16:17], v[170:171], v[154:155] op_sel_hi:[1,0,1]
	v_pk_fma_f32 v[150:151], v[18:19], v[170:171], v[156:157] op_sel_hi:[1,0,1]
	v_pk_fma_f32 v[152:153], v[20:21], v[170:171], v[158:159] op_sel_hi:[1,0,1]
	v_pk_fma_f32 v[154:155], v[22:23], v[170:171], v[160:161] op_sel_hi:[1,0,1]
	v_pk_fma_f32 v[156:157], v[24:25], v[170:171], v[162:163] op_sel_hi:[1,0,1]
	v_pk_fma_f32 v[158:159], v[26:27], v[170:171], v[164:165] op_sel_hi:[1,0,1]
	v_pk_fma_f32 v[160:161], v[28:29], v[170:171], v[166:167] op_sel_hi:[1,0,1]
	v_pk_fma_f32 v[162:163], v[30:31], v[170:171], v[168:169] op_sel_hi:[1,0,1]
	v_cndmask_b32_e64 v164, v0, v1, s[0:1]
	s_waitcnt vmcnt(8)
	v_cvt_scalef32_pk32_f32_fp6 v[0:31], v[144:149], 1.0
	v_readlane_b32 s12, v106, 12
	v_readlane_b32 s13, v109, 12
	v_pk_fma_f32 v[126:127], v[0:1], v[164:165], v[126:127] op_sel_hi:[1,0,1]
	v_mov_b32_e32 v1, s12
	v_mov_b32_e32 v0, s13
	v_pk_fma_f32 v[128:129], v[2:3], v[164:165], v[128:129] op_sel_hi:[1,0,1]
	v_pk_fma_f32 v[130:131], v[4:5], v[164:165], v[130:131] op_sel_hi:[1,0,1]
	v_pk_fma_f32 v[132:133], v[6:7], v[164:165], v[132:133] op_sel_hi:[1,0,1]
	v_pk_fma_f32 v[134:135], v[8:9], v[164:165], v[134:135] op_sel_hi:[1,0,1]
	v_pk_fma_f32 v[136:137], v[10:11], v[164:165], v[136:137] op_sel_hi:[1,0,1]
	v_pk_fma_f32 v[138:139], v[12:13], v[164:165], v[138:139] op_sel_hi:[1,0,1]
	v_pk_fma_f32 v[140:141], v[14:15], v[164:165], v[140:141] op_sel_hi:[1,0,1]
	v_pk_fma_f32 v[142:143], v[16:17], v[164:165], v[142:143] op_sel_hi:[1,0,1]
	v_pk_fma_f32 v[144:145], v[18:19], v[164:165], v[150:151] op_sel_hi:[1,0,1]
	v_pk_fma_f32 v[146:147], v[20:21], v[164:165], v[152:153] op_sel_hi:[1,0,1]
	v_pk_fma_f32 v[148:149], v[22:23], v[164:165], v[154:155] op_sel_hi:[1,0,1]
	v_pk_fma_f32 v[150:151], v[24:25], v[164:165], v[156:157] op_sel_hi:[1,0,1]
	v_pk_fma_f32 v[152:153], v[26:27], v[164:165], v[158:159] op_sel_hi:[1,0,1]
	v_pk_fma_f32 v[154:155], v[28:29], v[164:165], v[160:161] op_sel_hi:[1,0,1]
	v_pk_fma_f32 v[156:157], v[30:31], v[164:165], v[162:163] op_sel_hi:[1,0,1]
	v_cndmask_b32_e64 v158, v0, v1, s[0:1]
	s_waitcnt vmcnt(6)
; DI void phase_peer_out(const Params& p, char* lds) {
;     ...
; #pragma unroll
;     for (int kb = 0; kb < 8; ++kb) {
;       v6u qb[8];
; #pragma unroll
;       for (int k = 0; k < 8; ++k) {
;         const int e0 = __builtin_amdgcn_readlane(el[0], kb * 8 + k), e1 = __builtin_amdgcn_readlane(el[1], kb * 8 + k);
;         qb[k] = load6(V6 + (size_t)(hb ? e1 : e0) * 768);
;       }
; #pragma unroll
;       for (int k = 0; k < 8; ++k) {
;         const float c0 = __uint_as_float(__builtin_amdgcn_readlane(__float_as_uint(coefv[0]), kb * 8 + k)), c1 = __uint_as_float(__builtin_amdgcn_readlane(__float_as_uint(coefv[1]), kb * 8 + k));
;         const float cf = hb ? c1 : c0;
;         const f32x2 c2 = {cf, cf};
;         const v32f f = __builtin_amdgcn_cvt_scalef32_pk32_f32_fp6(qb[k], 1.0f);
; #pragma unroll
;         for (int i = 0; i < 16; ++i) o2[i] = f32x2{f[2 * i], f[2 * i + 1]} * c2 + o2[i];
;       }
;     }
	v_cvt_scalef32_pk32_f32_fp6 v[0:31], v[50:55], 1.0
	v_readlane_b32 s12, v106, 13
	v_readlane_b32 s13, v109, 13
	v_pk_fma_f32 v[50:51], v[0:1], v[158:159], v[126:127] op_sel_hi:[1,0,1]
	v_mov_b32_e32 v1, s12
	v_mov_b32_e32 v0, s13
	v_pk_fma_f32 v[52:53], v[2:3], v[158:159], v[128:129] op_sel_hi:[1,0,1]
	v_pk_fma_f32 v[54:55], v[4:5], v[158:159], v[130:131] op_sel_hi:[1,0,1]
	v_pk_fma_f32 v[126:127], v[6:7], v[158:159], v[132:133] op_sel_hi:[1,0,1]
	v_pk_fma_f32 v[128:129], v[8:9], v[158:159], v[134:135] op_sel_hi:[1,0,1]
	v_pk_fma_f32 v[130:131], v[10:11], v[158:159], v[136:137] op_sel_hi:[1,0,1]
	v_pk_fma_f32 v[132:133], v[12:13], v[158:159], v[138:139] op_sel_hi:[1,0,1]
	v_pk_fma_f32 v[134:135], v[14:15], v[158:159], v[140:141] op_sel_hi:[1,0,1]
	v_pk_fma_f32 v[136:137], v[16:17], v[158:159], v[142:143] op_sel_hi:[1,0,1]
	v_pk_fma_f32 v[138:139], v[18:19], v[158:159], v[144:145] op_sel_hi:[1,0,1]
	v_pk_fma_f32 v[140:141], v[20:21], v[158:159], v[146:147] op_sel_hi:[1,0,1]
	v_pk_fma_f32 v[142:143], v[22:23], v[158:159], v[148:149] op_sel_hi:[1,0,1]
	v_pk_fma_f32 v[144:145], v[24:25], v[158:159], v[150:151] op_sel_hi:[1,0,1]
	v_pk_fma_f32 v[146:147], v[26:27], v[158:159], v[152:153] op_sel_hi:[1,0,1]
	v_pk_fma_f32 v[148:149], v[28:29], v[158:159], v[154:155] op_sel_hi:[1,0,1]
	v_pk_fma_f32 v[150:151], v[30:31], v[158:159], v[156:157] op_sel_hi:[1,0,1]
	v_cndmask_b32_e64 v152, v0, v1, s[0:1]
	s_waitcnt vmcnt(4)
	v_cvt_scalef32_pk32_f32_fp6 v[0:31], v[44:49], 1.0
	v_readlane_b32 s12, v106, 14
	v_readlane_b32 s13, v109, 14
	v_pk_fma_f32 v[44:45], v[0:1], v[152:153], v[50:51] op_sel_hi:[1,0,1]
	v_mov_b32_e32 v1, s12
	v_mov_b32_e32 v0, s13
	v_pk_fma_f32 v[46:47], v[2:3], v[152:153], v[52:53] op_sel_hi:[1,0,1]
	v_pk_fma_f32 v[48:49], v[4:5], v[152:153], v[54:55] op_sel_hi:[1,0,1]
	v_pk_fma_f32 v[50:51], v[6:7], v[152:153], v[126:127] op_sel_hi:[1,0,1]
	v_pk_fma_f32 v[52:53], v[8:9], v[152:153], v[128:129] op_sel_hi:[1,0,1]
	v_pk_fma_f32 v[54:55], v[10:11], v[152:153], v[130:131] op_sel_hi:[1,0,1]
	v_pk_fma_f32 v[126:127], v[12:13], v[152:153], v[132:133] op_sel_hi:[1,0,1]
	v_pk_fma_f32 v[128:129], v[14:15], v[152:153], v[134:135] op_sel_hi:[1,0,1]
	v_pk_fma_f32 v[130:131], v[16:17], v[152:153], v[136:137] op_sel_hi:[1,0,1]
	v_pk_fma_f32 v[132:133], v[18:19], v[152:153], v[138:139] op_sel_hi:[1,0,1]
	v_pk_fma_f32 v[134:135], v[20:21], v[152:153], v[140:141] op_sel_hi:[1,0,1]
	v_pk_fma_f32 v[136:137], v[22:23], v[152:153], v[142:143] op_sel_hi:[1,0,1]
	v_pk_fma_f32 v[138:139], v[24:25], v[152:153], v[144:145] op_sel_hi:[1,0,1]
	v_pk_fma_f32 v[140:141], v[26:27], v[152:153], v[146:147] op_sel_hi:[1,0,1]
	v_pk_fma_f32 v[142:143], v[28:29], v[152:153], v[148:149] op_sel_hi:[1,0,1]
	v_pk_fma_f32 v[144:145], v[30:31], v[152:153], v[150:151] op_sel_hi:[1,0,1]
	v_cndmask_b32_e64 v146, v0, v1, s[0:1]
	s_waitcnt vmcnt(1)
	v_cvt_scalef32_pk32_f32_fp6 v[0:31], v[38:43], 1.0
	v_readlane_b32 s12, v106, 15
	v_readlane_b32 s13, v109, 15
	v_pk_fma_f32 v[38:39], v[0:1], v[146:147], v[44:45] op_sel_hi:[1,0,1]
	v_mov_b32_e32 v1, s12
	v_mov_b32_e32 v0, s13
	v_readlane_b32 s12, v108, 16
	v_readlane_b32 s13, v107, 16
	v_pk_fma_f32 v[40:41], v[2:3], v[146:147], v[46:47] op_sel_hi:[1,0,1]
	v_pk_fma_f32 v[42:43], v[4:5], v[146:147], v[48:49] op_sel_hi:[1,0,1]
	v_pk_fma_f32 v[44:45], v[6:7], v[146:147], v[50:51] op_sel_hi:[1,0,1]
	v_pk_fma_f32 v[46:47], v[8:9], v[146:147], v[52:53] op_sel_hi:[1,0,1]
	v_pk_fma_f32 v[48:49], v[10:11], v[146:147], v[54:55] op_sel_hi:[1,0,1]
	v_pk_fma_f32 v[50:51], v[12:13], v[146:147], v[126:127] op_sel_hi:[1,0,1]
	v_pk_fma_f32 v[52:53], v[14:15], v[146:147], v[128:129] op_sel_hi:[1,0,1]
	v_pk_fma_f32 v[54:55], v[16:17], v[146:147], v[130:131] op_sel_hi:[1,0,1]
	v_pk_fma_f32 v[132:133], v[18:19], v[146:147], v[132:133] op_sel_hi:[1,0,1]
	v_pk_fma_f32 v[134:135], v[20:21], v[146:147], v[134:135] op_sel_hi:[1,0,1]
	v_pk_fma_f32 v[136:137], v[22:23], v[146:147], v[136:137] op_sel_hi:[1,0,1]
	v_pk_fma_f32 v[138:139], v[24:25], v[146:147], v[138:139] op_sel_hi:[1,0,1]
	v_pk_fma_f32 v[140:141], v[26:27], v[146:147], v[140:141] op_sel_hi:[1,0,1]
	v_pk_fma_f32 v[142:143], v[28:29], v[146:147], v[142:143] op_sel_hi:[1,0,1]
	v_pk_fma_f32 v[144:145], v[30:31], v[146:147], v[144:145] op_sel_hi:[1,0,1]
	v_cndmask_b32_e64 v146, v0, v1, s[0:1]
	v_mov_b32_e32 v0, s13
	v_mov_b32_e32 v1, s12
	v_cndmask_b32_e64 v0, v0, v1, s[0:1]
	v_mad_i64_i32 v[130:131], s[12:13], v0, s23, v[64:65]
	s_waitcnt vmcnt(0)
; DI void phase_peer_out(const Params& p, char* lds) {
;     ...
; #pragma unroll
;     for (int kb = 0; kb < 8; ++kb) {
;       v6u qb[8];
; #pragma unroll
;       for (int k = 0; k < 8; ++k) {
;         const int e0 = __builtin_amdgcn_readlane(el[0], kb * 8 + k), e1 = __builtin_amdgcn_readlane(el[1], kb * 8 + k);
;         qb[k] = load6(V6 + (size_t)(hb ? e1 : e0) * 768);
;       }
; #pragma unroll
;       for (int k = 0; k < 8; ++k) {
;         const float c0 = __uint_as_float(__builtin_amdgcn_readlane(__float_as_uint(coefv[0]), kb * 8 + k)), c1 = __uint_as_float(__builtin_amdgcn_readlane(__float_as_uint(coefv[1]), kb * 8 + k));
;         const float cf = hb ? c1 : c0;
;         const f32x2 c2 = {cf, cf};
;         const v32f f = __builtin_amdgcn_cvt_scalef32_pk32_f32_fp6(qb[k], 1.0f);
; #pragma unroll
;         for (int i = 0; i < 16; ++i) o2[i] = f32x2{f[2 * i], f[2 * i + 1]} * c2 + o2[i];
;       }
;     }
	v_cvt_scalef32_pk32_f32_fp6 v[0:31], v[32:37], 1.0
	v_readlane_b32 s12, v108, 17
	v_readlane_b32 s13, v107, 17
	v_pk_fma_f32 v[150:151], v[0:1], v[146:147], v[38:39] op_sel_hi:[1,0,1]
	v_mov_b32_e32 v1, s12
	v_mov_b32_e32 v0, s13
	v_cndmask_b32_e64 v0, v0, v1, s[0:1]
	v_mad_i64_i32 v[0:1], s[12:13], v0, s23, v[64:65]
	v_readlane_b32 s12, v108, 18
	v_readlane_b32 s13, v107, 18
	global_load_dwordx4 v[126:129], v[130:131], off
	v_pk_fma_f32 v[168:169], v[18:19], v[146:147], v[132:133] op_sel_hi:[1,0,1]
	global_load_dwordx2 v[130:131], v[130:131], off offset:16
	v_pk_fma_f32 v[170:171], v[20:21], v[146:147], v[134:135] op_sel_hi:[1,0,1]
	v_pk_fma_f32 v[172:173], v[22:23], v[146:147], v[136:137] op_sel_hi:[1,0,1]
	global_load_dwordx2 v[136:137], v[0:1], off offset:16
	global_load_dwordx4 v[132:135], v[0:1], off
	v_mov_b32_e32 v0, s13
	v_mov_b32_e32 v1, s12
	v_cndmask_b32_e64 v0, v0, v1, s[0:1]
	v_mad_i64_i32 v[0:1], s[12:13], v0, s23, v[64:65]
	v_readlane_b32 s12, v108, 19
	v_readlane_b32 s13, v107, 19
	v_pk_fma_f32 v[152:153], v[2:3], v[146:147], v[40:41] op_sel_hi:[1,0,1]
	v_mov_b32_e32 v3, s12
	v_mov_b32_e32 v2, s13
	v_cndmask_b32_e64 v2, v2, v3, s[0:1]
	v_mad_i64_i32 v[2:3], s[12:13], v2, s23, v[64:65]
	v_readlane_b32 s12, v108, 20
	v_readlane_b32 s13, v107, 20
	v_pk_fma_f32 v[154:155], v[4:5], v[146:147], v[42:43] op_sel_hi:[1,0,1]
	v_pk_fma_f32 v[156:157], v[6:7], v[146:147], v[44:45] op_sel_hi:[1,0,1]
	v_pk_fma_f32 v[158:159], v[8:9], v[146:147], v[46:47] op_sel_hi:[1,0,1]
	v_pk_fma_f32 v[160:161], v[10:11], v[146:147], v[48:49] op_sel_hi:[1,0,1]
	v_pk_fma_f32 v[162:163], v[12:13], v[146:147], v[50:51] op_sel_hi:[1,0,1]
	v_pk_fma_f32 v[164:165], v[14:15], v[146:147], v[52:53] op_sel_hi:[1,0,1]
	v_pk_fma_f32 v[166:167], v[16:17], v[146:147], v[54:55] op_sel_hi:[1,0,1]
	v_pk_fma_f32 v[174:175], v[24:25], v[146:147], v[138:139] op_sel_hi:[1,0,1]
	v_pk_fma_f32 v[176:177], v[26:27], v[146:147], v[140:141] op_sel_hi:[1,0,1]
	v_pk_fma_f32 v[178:179], v[28:29], v[146:147], v[142:143] op_sel_hi:[1,0,1]
	v_pk_fma_f32 v[180:181], v[30:31], v[146:147], v[144:145] op_sel_hi:[1,0,1]
	global_load_dwordx4 v[138:141], v[0:1], off
	global_load_dwordx2 v[142:143], v[0:1], off offset:16
	global_load_dwordx4 v[144:147], v[2:3], off
	v_mov_b32_e32 v0, s13
	v_mov_b32_e32 v1, s12
	v_cndmask_b32_e64 v0, v0, v1, s[0:1]
	v_mad_i64_i32 v[0:1], s[12:13], v0, s23, v[64:65]
	v_readlane_b32 s12, v108, 21
	v_readlane_b32 s13, v107, 21
	global_load_dwordx2 v[148:149], v[2:3], off offset:16
	global_load_dwordx4 v[50:53], v[0:1], off
	v_mov_b32_e32 v2, s13
	v_mov_b32_e32 v3, s12
	v_cndmask_b32_e64 v2, v2, v3, s[0:1]
	v_mad_i64_i32 v[2:3], s[12:13], v2, s23, v[64:65]
	v_readlane_b32 s12, v108, 22
	v_readlane_b32 s13, v107, 22
	global_load_dwordx2 v[54:55], v[0:1], off offset:16
	global_load_dwordx4 v[44:47], v[2:3], off
	v_mov_b32_e32 v0, s13
	v_mov_b32_e32 v1, s12
	v_cndmask_b32_e64 v0, v0, v1, s[0:1]
	v_mad_i64_i32 v[0:1], s[12:13], v0, s23, v[64:65]
	v_readlane_b32 s12, v108, 23
	v_readlane_b32 s13, v107, 23
	global_load_dwordx2 v[48:49], v[2:3], off offset:16
	global_load_dwordx4 v[38:41], v[0:1], off
	v_mov_b32_e32 v2, s13
	v_mov_b32_e32 v3, s12
	v_cndmask_b32_e64 v2, v2, v3, s[0:1]
	v_mad_i64_i32 v[2:3], s[12:13], v2, s23, v[64:65]
	global_load_dwordx2 v[36:37], v[2:3], off offset:16
	global_load_dwordx2 v[42:43], v[0:1], off offset:16
	global_load_dwordx4 v[32:35], v[2:3], off
	v_readlane_b32 s12, v106, 16
	v_readlane_b32 s13, v109, 16
	s_nop 0
	v_mov_b32_e32 v1, s12
	v_mov_b32_e32 v0, s13
	v_cndmask_b32_e64 v182, v0, v1, s[0:1]
	v_readlane_b32 s12, v106, 17
	v_readlane_b32 s13, v109, 17
	s_waitcnt vmcnt(14)
	v_cvt_scalef32_pk32_f32_fp6 v[0:31], v[126:131], 1.0
	v_pk_fma_f32 v[126:127], v[0:1], v[182:183], v[150:151] op_sel_hi:[1,0,1]
	v_mov_b32_e32 v0, s13
	v_mov_b32_e32 v1, s12
	v_pk_fma_f32 v[128:129], v[2:3], v[182:183], v[152:153] op_sel_hi:[1,0,1]
	v_pk_fma_f32 v[130:131], v[4:5], v[182:183], v[154:155] op_sel_hi:[1,0,1]
	v_pk_fma_f32 v[150:151], v[6:7], v[182:183], v[156:157] op_sel_hi:[1,0,1]
	v_pk_fma_f32 v[152:153], v[8:9], v[182:183], v[158:159] op_sel_hi:[1,0,1]
	v_pk_fma_f32 v[154:155], v[10:11], v[182:183], v[160:161] op_sel_hi:[1,0,1]
	v_pk_fma_f32 v[156:157], v[12:13], v[182:183], v[162:163] op_sel_hi:[1,0,1]
	v_pk_fma_f32 v[158:159], v[14:15], v[182:183], v[164:165] op_sel_hi:[1,0,1]
	v_pk_fma_f32 v[160:161], v[16:17], v[182:183], v[166:167] op_sel_hi:[1,0,1]
	v_pk_fma_f32 v[162:163], v[18:19], v[182:183], v[168:169] op_sel_hi:[1,0,1]
	v_pk_fma_f32 v[164:165], v[20:21], v[182:183], v[170:171] op_sel_hi:[1,0,1]
	v_pk_fma_f32 v[166:167], v[22:23], v[182:183], v[172:173] op_sel_hi:[1,0,1]
	v_pk_fma_f32 v[168:169], v[24:25], v[182:183], v[174:175] op_sel_hi:[1,0,1]
	v_pk_fma_f32 v[170:171], v[26:27], v[182:183], v[176:177] op_sel_hi:[1,0,1]
	v_pk_fma_f32 v[172:173], v[28:29], v[182:183], v[178:179] op_sel_hi:[1,0,1]
	v_pk_fma_f32 v[174:175], v[30:31], v[182:183], v[180:181] op_sel_hi:[1,0,1]
	v_cndmask_b32_e64 v176, v0, v1, s[0:1]
	s_waitcnt vmcnt(12)
; DI void phase_peer_out(const Params& p, char* lds) {
;     ...
; #pragma unroll
;     for (int kb = 0; kb < 8; ++kb) {
;       v6u qb[8];
; #pragma unroll
;       for (int k = 0; k < 8; ++k) {
;         const int e0 = __builtin_amdgcn_readlane(el[0], kb * 8 + k), e1 = __builtin_amdgcn_readlane(el[1], kb * 8 + k);
;         qb[k] = load6(V6 + (size_t)(hb ? e1 : e0) * 768);
;       }
; #pragma unroll
;       for (int k = 0; k < 8; ++k) {
;         const float c0 = __uint_as_float(__builtin_amdgcn_readlane(__float_as_uint(coefv[0]), kb * 8 + k)), c1 = __uint_as_float(__builtin_amdgcn_readlane(__float_as_uint(coefv[1]), kb * 8 + k));
;         const float cf = hb ? c1 : c0;
;         const f32x2 c2 = {cf, cf};
;         const v32f f = __builtin_amdgcn_cvt_scalef32_pk32_f32_fp6(qb[k], 1.0f);
; #pragma unroll
;         for (int i = 0; i < 16; ++i) o2[i] = f32x2{f[2 * i], f[2 * i + 1]} * c2 + o2[i];
;       }
;     }
	v_cvt_scalef32_pk32_f32_fp6 v[0:31], v[132:137], 1.0
	v_readlane_b32 s12, v106, 18
	v_readlane_b32 s13, v109, 18
	v_pk_fma_f32 v[126:127], v[0:1], v[176:177], v[126:127] op_sel_hi:[1,0,1]
	v_mov_b32_e32 v1, s12
	v_mov_b32_e32 v0, s13
	v_pk_fma_f32 v[128:129], v[2:3], v[176:177], v[128:129] op_sel_hi:[1,0,1]
	v_pk_fma_f32 v[130:131], v[4:5], v[176:177], v[130:131] op_sel_hi:[1,0,1]
	v_pk_fma_f32 v[132:133], v[6:7], v[176:177], v[150:151] op_sel_hi:[1,0,1]
	v_pk_fma_f32 v[134:135], v[8:9], v[176:177], v[152:153] op_sel_hi:[1,0,1]
	v_pk_fma_f32 v[136:137], v[10:11], v[176:177], v[154:155] op_sel_hi:[1,0,1]
	v_pk_fma_f32 v[150:151], v[12:13], v[176:177], v[156:157] op_sel_hi:[1,0,1]
	v_pk_fma_f32 v[152:153], v[14:15], v[176:177], v[158:159] op_sel_hi:[1,0,1]
	v_pk_fma_f32 v[154:155], v[16:17], v[176:177], v[160:161] op_sel_hi:[1,0,1]
	v_pk_fma_f32 v[156:157], v[18:19], v[176:177], v[162:163] op_sel_hi:[1,0,1]
	v_pk_fma_f32 v[158:159], v[20:21], v[176:177], v[164:165] op_sel_hi:[1,0,1]
	v_pk_fma_f32 v[160:161], v[22:23], v[176:177], v[166:167] op_sel_hi:[1,0,1]
	v_pk_fma_f32 v[162:163], v[24:25], v[176:177], v[168:169] op_sel_hi:[1,0,1]
	v_pk_fma_f32 v[164:165], v[26:27], v[176:177], v[170:171] op_sel_hi:[1,0,1]
	v_pk_fma_f32 v[166:167], v[28:29], v[176:177], v[172:173] op_sel_hi:[1,0,1]
	v_pk_fma_f32 v[168:169], v[30:31], v[176:177], v[174:175] op_sel_hi:[1,0,1]
	v_cndmask_b32_e64 v170, v0, v1, s[0:1]
	s_waitcnt vmcnt(10)
	v_cvt_scalef32_pk32_f32_fp6 v[0:31], v[138:143], 1.0
	v_readlane_b32 s12, v106, 19
	v_readlane_b32 s13, v109, 19
	v_pk_fma_f32 v[126:127], v[0:1], v[170:171], v[126:127] op_sel_hi:[1,0,1]
	v_mov_b32_e32 v1, s12
	v_mov_b32_e32 v0, s13
	v_pk_fma_f32 v[128:129], v[2:3], v[170:171], v[128:129] op_sel_hi:[1,0,1]
	v_pk_fma_f32 v[130:131], v[4:5], v[170:171], v[130:131] op_sel_hi:[1,0,1]
	v_pk_fma_f32 v[132:133], v[6:7], v[170:171], v[132:133] op_sel_hi:[1,0,1]
	v_pk_fma_f32 v[134:135], v[8:9], v[170:171], v[134:135] op_sel_hi:[1,0,1]
	v_pk_fma_f32 v[136:137], v[10:11], v[170:171], v[136:137] op_sel_hi:[1,0,1]
	v_pk_fma_f32 v[138:139], v[12:13], v[170:171], v[150:151] op_sel_hi:[1,0,1]
	v_pk_fma_f32 v[140:141], v[14:15], v[170:171], v[152:153] op_sel_hi:[1,0,1]
	v_pk_fma_f32 v[142:143], v[16:17], v[170:171], v[154:155] op_sel_hi:[1,0,1]
	v_pk_fma_f32 v[150:151], v[18:19], v[170:171], v[156:157] op_sel_hi:[1,0,1]
	v_pk_fma_f32 v[152:153], v[20:21], v[170:171], v[158:159] op_sel_hi:[1,0,1]
	v_pk_fma_f32 v[154:155], v[22:23], v[170:171], v[160:161] op_sel_hi:[1,0,1]
	v_pk_fma_f32 v[156:157], v[24:25], v[170:171], v[162:163] op_sel_hi:[1,0,1]
	v_pk_fma_f32 v[158:159], v[26:27], v[170:171], v[164:165] op_sel_hi:[1,0,1]
	v_pk_fma_f32 v[160:161], v[28:29], v[170:171], v[166:167] op_sel_hi:[1,0,1]
	v_pk_fma_f32 v[162:163], v[30:31], v[170:171], v[168:169] op_sel_hi:[1,0,1]
	v_cndmask_b32_e64 v164, v0, v1, s[0:1]
	s_waitcnt vmcnt(8)
	v_cvt_scalef32_pk32_f32_fp6 v[0:31], v[144:149], 1.0
	v_readlane_b32 s12, v106, 20
	v_readlane_b32 s13, v109, 20
	v_pk_fma_f32 v[126:127], v[0:1], v[164:165], v[126:127] op_sel_hi:[1,0,1]
	v_mov_b32_e32 v1, s12
	v_mov_b32_e32 v0, s13
	v_pk_fma_f32 v[128:129], v[2:3], v[164:165], v[128:129] op_sel_hi:[1,0,1]
	v_pk_fma_f32 v[130:131], v[4:5], v[164:165], v[130:131] op_sel_hi:[1,0,1]
	v_pk_fma_f32 v[132:133], v[6:7], v[164:165], v[132:133] op_sel_hi:[1,0,1]
	v_pk_fma_f32 v[134:135], v[8:9], v[164:165], v[134:135] op_sel_hi:[1,0,1]
	v_pk_fma_f32 v[136:137], v[10:11], v[164:165], v[136:137] op_sel_hi:[1,0,1]
	v_pk_fma_f32 v[138:139], v[12:13], v[164:165], v[138:139] op_sel_hi:[1,0,1]
	v_pk_fma_f32 v[140:141], v[14:15], v[164:165], v[140:141] op_sel_hi:[1,0,1]
	v_pk_fma_f32 v[142:143], v[16:17], v[164:165], v[142:143] op_sel_hi:[1,0,1]
	v_pk_fma_f32 v[144:145], v[18:19], v[164:165], v[150:151] op_sel_hi:[1,0,1]
	v_pk_fma_f32 v[146:147], v[20:21], v[164:165], v[152:153] op_sel_hi:[1,0,1]
	v_pk_fma_f32 v[148:149], v[22:23], v[164:165], v[154:155] op_sel_hi:[1,0,1]
	v_pk_fma_f32 v[150:151], v[24:25], v[164:165], v[156:157] op_sel_hi:[1,0,1]
	v_pk_fma_f32 v[152:153], v[26:27], v[164:165], v[158:159] op_sel_hi:[1,0,1]
	v_pk_fma_f32 v[154:155], v[28:29], v[164:165], v[160:161] op_sel_hi:[1,0,1]
	v_pk_fma_f32 v[156:157], v[30:31], v[164:165], v[162:163] op_sel_hi:[1,0,1]
	v_cndmask_b32_e64 v158, v0, v1, s[0:1]
	s_waitcnt vmcnt(6)
	v_cvt_scalef32_pk32_f32_fp6 v[0:31], v[50:55], 1.0
	v_readlane_b32 s12, v106, 21
	v_readlane_b32 s13, v109, 21
	v_pk_fma_f32 v[50:51], v[0:1], v[158:159], v[126:127] op_sel_hi:[1,0,1]
	v_mov_b32_e32 v1, s12
	v_mov_b32_e32 v0, s13
	v_pk_fma_f32 v[52:53], v[2:3], v[158:159], v[128:129] op_sel_hi:[1,0,1]
	v_pk_fma_f32 v[54:55], v[4:5], v[158:159], v[130:131] op_sel_hi:[1,0,1]
	v_pk_fma_f32 v[126:127], v[6:7], v[158:159], v[132:133] op_sel_hi:[1,0,1]
	v_pk_fma_f32 v[128:129], v[8:9], v[158:159], v[134:135] op_sel_hi:[1,0,1]
	v_pk_fma_f32 v[130:131], v[10:11], v[158:159], v[136:137] op_sel_hi:[1,0,1]
	v_pk_fma_f32 v[132:133], v[12:13], v[158:159], v[138:139] op_sel_hi:[1,0,1]
	v_pk_fma_f32 v[134:135], v[14:15], v[158:159], v[140:141] op_sel_hi:[1,0,1]
	v_pk_fma_f32 v[136:137], v[16:17], v[158:159], v[142:143] op_sel_hi:[1,0,1]
	v_pk_fma_f32 v[138:139], v[18:19], v[158:159], v[144:145] op_sel_hi:[1,0,1]
	v_pk_fma_f32 v[140:141], v[20:21], v[158:159], v[146:147] op_sel_hi:[1,0,1]
	v_pk_fma_f32 v[142:143], v[22:23], v[158:159], v[148:149] op_sel_hi:[1,0,1]
	v_pk_fma_f32 v[144:145], v[24:25], v[158:159], v[150:151] op_sel_hi:[1,0,1]
	v_pk_fma_f32 v[146:147], v[26:27], v[158:159], v[152:153] op_sel_hi:[1,0,1]
	v_pk_fma_f32 v[148:149], v[28:29], v[158:159], v[154:155] op_sel_hi:[1,0,1]
	v_pk_fma_f32 v[150:151], v[30:31], v[158:159], v[156:157] op_sel_hi:[1,0,1]
	v_cndmask_b32_e64 v152, v0, v1, s[0:1]
	s_waitcnt vmcnt(4)
; DI void phase_peer_out(const Params& p, char* lds) {
;     ...
; #pragma unroll
;     for (int kb = 0; kb < 8; ++kb) {
;       v6u qb[8];
; #pragma unroll
;       for (int k = 0; k < 8; ++k) {
;         const int e0 = __builtin_amdgcn_readlane(el[0], kb * 8 + k), e1 = __builtin_amdgcn_readlane(el[1], kb * 8 + k);
;         qb[k] = load6(V6 + (size_t)(hb ? e1 : e0) * 768);
;       }
; #pragma unroll
;       for (int k = 0; k < 8; ++k) {
;         const float c0 = __uint_as_float(__builtin_amdgcn_readlane(__float_as_uint(coefv[0]), kb * 8 + k)), c1 = __uint_as_float(__builtin_amdgcn_readlane(__float_as_uint(coefv[1]), kb * 8 + k));
;         const float cf = hb ? c1 : c0;
;         const f32x2 c2 = {cf, cf};
;         const v32f f = __builtin_amdgcn_cvt_scalef32_pk32_f32_fp6(qb[k], 1.0f);
; #pragma unroll
;         for (int i = 0; i < 16; ++i) o2[i] = f32x2{f[2 * i], f[2 * i + 1]} * c2 + o2[i];
;       }
;     }
	v_cvt_scalef32_pk32_f32_fp6 v[0:31], v[44:49], 1.0
	v_readlane_b32 s12, v106, 22
	v_readlane_b32 s13, v109, 22
	v_pk_fma_f32 v[44:45], v[0:1], v[152:153], v[50:51] op_sel_hi:[1,0,1]
	v_mov_b32_e32 v1, s12
	v_mov_b32_e32 v0, s13
	v_pk_fma_f32 v[46:47], v[2:3], v[152:153], v[52:53] op_sel_hi:[1,0,1]
	v_pk_fma_f32 v[48:49], v[4:5], v[152:153], v[54:55] op_sel_hi:[1,0,1]
	v_pk_fma_f32 v[50:51], v[6:7], v[152:153], v[126:127] op_sel_hi:[1,0,1]
	v_pk_fma_f32 v[52:53], v[8:9], v[152:153], v[128:129] op_sel_hi:[1,0,1]
	v_pk_fma_f32 v[54:55], v[10:11], v[152:153], v[130:131] op_sel_hi:[1,0,1]
	v_pk_fma_f32 v[126:127], v[12:13], v[152:153], v[132:133] op_sel_hi:[1,0,1]
	v_pk_fma_f32 v[128:129], v[14:15], v[152:153], v[134:135] op_sel_hi:[1,0,1]
	v_pk_fma_f32 v[130:131], v[16:17], v[152:153], v[136:137] op_sel_hi:[1,0,1]
	v_pk_fma_f32 v[132:133], v[18:19], v[152:153], v[138:139] op_sel_hi:[1,0,1]
	v_pk_fma_f32 v[134:135], v[20:21], v[152:153], v[140:141] op_sel_hi:[1,0,1]
	v_pk_fma_f32 v[136:137], v[22:23], v[152:153], v[142:143] op_sel_hi:[1,0,1]
	v_pk_fma_f32 v[138:139], v[24:25], v[152:153], v[144:145] op_sel_hi:[1,0,1]
	v_pk_fma_f32 v[140:141], v[26:27], v[152:153], v[146:147] op_sel_hi:[1,0,1]
	v_pk_fma_f32 v[142:143], v[28:29], v[152:153], v[148:149] op_sel_hi:[1,0,1]
	v_pk_fma_f32 v[144:145], v[30:31], v[152:153], v[150:151] op_sel_hi:[1,0,1]
	v_cndmask_b32_e64 v146, v0, v1, s[0:1]
	s_waitcnt vmcnt(1)
	v_cvt_scalef32_pk32_f32_fp6 v[0:31], v[38:43], 1.0
	v_readlane_b32 s12, v106, 23
	v_readlane_b32 s13, v109, 23
	v_pk_fma_f32 v[38:39], v[0:1], v[146:147], v[44:45] op_sel_hi:[1,0,1]
	v_mov_b32_e32 v1, s12
	v_mov_b32_e32 v0, s13
	v_readlane_b32 s12, v108, 24
	v_readlane_b32 s13, v107, 24
	v_pk_fma_f32 v[40:41], v[2:3], v[146:147], v[46:47] op_sel_hi:[1,0,1]
	v_pk_fma_f32 v[42:43], v[4:5], v[146:147], v[48:49] op_sel_hi:[1,0,1]
	v_pk_fma_f32 v[44:45], v[6:7], v[146:147], v[50:51] op_sel_hi:[1,0,1]
	v_pk_fma_f32 v[46:47], v[8:9], v[146:147], v[52:53] op_sel_hi:[1,0,1]
	v_pk_fma_f32 v[48:49], v[10:11], v[146:147], v[54:55] op_sel_hi:[1,0,1]
	v_pk_fma_f32 v[50:51], v[12:13], v[146:147], v[126:127] op_sel_hi:[1,0,1]
	v_pk_fma_f32 v[52:53], v[14:15], v[146:147], v[128:129] op_sel_hi:[1,0,1]
	v_pk_fma_f32 v[54:55], v[16:17], v[146:147], v[130:131] op_sel_hi:[1,0,1]
	v_pk_fma_f32 v[132:133], v[18:19], v[146:147], v[132:133] op_sel_hi:[1,0,1]
	v_pk_fma_f32 v[134:135], v[20:21], v[146:147], v[134:135] op_sel_hi:[1,0,1]
	v_pk_fma_f32 v[136:137], v[22:23], v[146:147], v[136:137] op_sel_hi:[1,0,1]
	v_pk_fma_f32 v[138:139], v[24:25], v[146:147], v[138:139] op_sel_hi:[1,0,1]
	v_pk_fma_f32 v[140:141], v[26:27], v[146:147], v[140:141] op_sel_hi:[1,0,1]
	v_pk_fma_f32 v[142:143], v[28:29], v[146:147], v[142:143] op_sel_hi:[1,0,1]
	v_pk_fma_f32 v[144:145], v[30:31], v[146:147], v[144:145] op_sel_hi:[1,0,1]
	v_cndmask_b32_e64 v146, v0, v1, s[0:1]
	v_mov_b32_e32 v0, s13
	v_mov_b32_e32 v1, s12
	v_cndmask_b32_e64 v0, v0, v1, s[0:1]
	v_mad_i64_i32 v[130:131], s[12:13], v0, s23, v[64:65]
	s_waitcnt vmcnt(0)
	v_cvt_scalef32_pk32_f32_fp6 v[0:31], v[32:37], 1.0
	v_readlane_b32 s12, v108, 25
	v_readlane_b32 s13, v107, 25
	v_pk_fma_f32 v[150:151], v[0:1], v[146:147], v[38:39] op_sel_hi:[1,0,1]
	v_mov_b32_e32 v1, s12
	v_mov_b32_e32 v0, s13
	v_cndmask_b32_e64 v0, v0, v1, s[0:1]
	v_mad_i64_i32 v[0:1], s[12:13], v0, s23, v[64:65]
	v_readlane_b32 s12, v108, 26
	v_readlane_b32 s13, v107, 26
	global_load_dwordx4 v[126:129], v[130:131], off
	v_pk_fma_f32 v[168:169], v[18:19], v[146:147], v[132:133] op_sel_hi:[1,0,1]
	global_load_dwordx2 v[130:131], v[130:131], off offset:16
	v_pk_fma_f32 v[170:171], v[20:21], v[146:147], v[134:135] op_sel_hi:[1,0,1]
	v_pk_fma_f32 v[172:173], v[22:23], v[146:147], v[136:137] op_sel_hi:[1,0,1]
	global_load_dwordx2 v[136:137], v[0:1], off offset:16
	global_load_dwordx4 v[132:135], v[0:1], off
	v_mov_b32_e32 v0, s13
	v_mov_b32_e32 v1, s12
	v_cndmask_b32_e64 v0, v0, v1, s[0:1]
	v_mad_i64_i32 v[0:1], s[12:13], v0, s23, v[64:65]
	v_readlane_b32 s12, v108, 27
	v_readlane_b32 s13, v107, 27
	v_pk_fma_f32 v[152:153], v[2:3], v[146:147], v[40:41] op_sel_hi:[1,0,1]
	v_mov_b32_e32 v3, s12
	v_mov_b32_e32 v2, s13
	v_cndmask_b32_e64 v2, v2, v3, s[0:1]
	v_mad_i64_i32 v[2:3], s[12:13], v2, s23, v[64:65]
	v_readlane_b32 s12, v108, 28
	v_readlane_b32 s13, v107, 28
	v_pk_fma_f32 v[154:155], v[4:5], v[146:147], v[42:43] op_sel_hi:[1,0,1]
	v_pk_fma_f32 v[156:157], v[6:7], v[146:147], v[44:45] op_sel_hi:[1,0,1]
	v_pk_fma_f32 v[158:159], v[8:9], v[146:147], v[46:47] op_sel_hi:[1,0,1]
	v_pk_fma_f32 v[160:161], v[10:11], v[146:147], v[48:49] op_sel_hi:[1,0,1]
	v_pk_fma_f32 v[162:163], v[12:13], v[146:147], v[50:51] op_sel_hi:[1,0,1]
	v_pk_fma_f32 v[164:165], v[14:15], v[146:147], v[52:53] op_sel_hi:[1,0,1]
	v_pk_fma_f32 v[166:167], v[16:17], v[146:147], v[54:55] op_sel_hi:[1,0,1]
	v_pk_fma_f32 v[174:175], v[24:25], v[146:147], v[138:139] op_sel_hi:[1,0,1]
	v_pk_fma_f32 v[176:177], v[26:27], v[146:147], v[140:141] op_sel_hi:[1,0,1]
	v_pk_fma_f32 v[178:179], v[28:29], v[146:147], v[142:143] op_sel_hi:[1,0,1]
	v_pk_fma_f32 v[180:181], v[30:31], v[146:147], v[144:145] op_sel_hi:[1,0,1]
	global_load_dwordx4 v[138:141], v[0:1], off
	global_load_dwordx2 v[142:143], v[0:1], off offset:16
	global_load_dwordx4 v[144:147], v[2:3], off
	v_mov_b32_e32 v0, s13
	v_mov_b32_e32 v1, s12
	v_cndmask_b32_e64 v0, v0, v1, s[0:1]
	v_mad_i64_i32 v[0:1], s[12:13], v0, s23, v[64:65]
	v_readlane_b32 s12, v108, 29
	v_readlane_b32 s13, v107, 29
	global_load_dwordx2 v[148:149], v[2:3], off offset:16
	global_load_dwordx4 v[50:53], v[0:1], off
	v_mov_b32_e32 v2, s13
	v_mov_b32_e32 v3, s12
	v_cndmask_b32_e64 v2, v2, v3, s[0:1]
	v_mad_i64_i32 v[2:3], s[12:13], v2, s23, v[64:65]
	v_readlane_b32 s12, v108, 30
	v_readlane_b32 s13, v107, 30
	global_load_dwordx2 v[54:55], v[0:1], off offset:16
	global_load_dwordx4 v[44:47], v[2:3], off
	v_mov_b32_e32 v0, s13
	v_mov_b32_e32 v1, s12
	v_cndmask_b32_e64 v0, v0, v1, s[0:1]
	v_mad_i64_i32 v[0:1], s[12:13], v0, s23, v[64:65]
	v_readlane_b32 s12, v108, 31
	v_readlane_b32 s13, v107, 31
	global_load_dwordx2 v[48:49], v[2:3], off offset:16
	global_load_dwordx4 v[38:41], v[0:1], off
	v_mov_b32_e32 v2, s13
	v_mov_b32_e32 v3, s12
	v_cndmask_b32_e64 v2, v2, v3, s[0:1]
	v_mad_i64_i32 v[2:3], s[12:13], v2, s23, v[64:65]
	global_load_dwordx2 v[36:37], v[2:3], off offset:16
	global_load_dwordx2 v[42:43], v[0:1], off offset:16
	global_load_dwordx4 v[32:35], v[2:3], off
	v_readlane_b32 s12, v106, 24
	v_readlane_b32 s13, v109, 24
	s_nop 0
	v_mov_b32_e32 v1, s12
	v_mov_b32_e32 v0, s13
	v_cndmask_b32_e64 v182, v0, v1, s[0:1]
	v_readlane_b32 s12, v106, 25
	v_readlane_b32 s13, v109, 25
	s_waitcnt vmcnt(14)
; DI void phase_peer_out(const Params& p, char* lds) {
;     ...
; #pragma unroll
;     for (int kb = 0; kb < 8; ++kb) {
;       v6u qb[8];
; #pragma unroll
;       for (int k = 0; k < 8; ++k) {
;         const int e0 = __builtin_amdgcn_readlane(el[0], kb * 8 + k), e1 = __builtin_amdgcn_readlane(el[1], kb * 8 + k);
;         qb[k] = load6(V6 + (size_t)(hb ? e1 : e0) * 768);
;       }
; #pragma unroll
;       for (int k = 0; k < 8; ++k) {
;         const float c0 = __uint_as_float(__builtin_amdgcn_readlane(__float_as_uint(coefv[0]), kb * 8 + k)), c1 = __uint_as_float(__builtin_amdgcn_readlane(__float_as_uint(coefv[1]), kb * 8 + k));
;         const float cf = hb ? c1 : c0;
;         const f32x2 c2 = {cf, cf};
;         const v32f f = __builtin_amdgcn_cvt_scalef32_pk32_f32_fp6(qb[k], 1.0f);
; #pragma unroll
;         for (int i = 0; i < 16; ++i) o2[i] = f32x2{f[2 * i], f[2 * i + 1]} * c2 + o2[i];
;       }
;     }
	v_cvt_scalef32_pk32_f32_fp6 v[0:31], v[126:131], 1.0
	v_pk_fma_f32 v[126:127], v[0:1], v[182:183], v[150:151] op_sel_hi:[1,0,1]
	v_mov_b32_e32 v0, s13
	v_mov_b32_e32 v1, s12
	v_pk_fma_f32 v[128:129], v[2:3], v[182:183], v[152:153] op_sel_hi:[1,0,1]
	v_pk_fma_f32 v[130:131], v[4:5], v[182:183], v[154:155] op_sel_hi:[1,0,1]
	v_pk_fma_f32 v[150:151], v[6:7], v[182:183], v[156:157] op_sel_hi:[1,0,1]
	v_pk_fma_f32 v[152:153], v[8:9], v[182:183], v[158:159] op_sel_hi:[1,0,1]
	v_pk_fma_f32 v[154:155], v[10:11], v[182:183], v[160:161] op_sel_hi:[1,0,1]
	v_pk_fma_f32 v[156:157], v[12:13], v[182:183], v[162:163] op_sel_hi:[1,0,1]
	v_pk_fma_f32 v[158:159], v[14:15], v[182:183], v[164:165] op_sel_hi:[1,0,1]
	v_pk_fma_f32 v[160:161], v[16:17], v[182:183], v[166:167] op_sel_hi:[1,0,1]
	v_pk_fma_f32 v[162:163], v[18:19], v[182:183], v[168:169] op_sel_hi:[1,0,1]
	v_pk_fma_f32 v[164:165], v[20:21], v[182:183], v[170:171] op_sel_hi:[1,0,1]
	v_pk_fma_f32 v[166:167], v[22:23], v[182:183], v[172:173] op_sel_hi:[1,0,1]
	v_pk_fma_f32 v[168:169], v[24:25], v[182:183], v[174:175] op_sel_hi:[1,0,1]
	v_pk_fma_f32 v[170:171], v[26:27], v[182:183], v[176:177] op_sel_hi:[1,0,1]
	v_pk_fma_f32 v[172:173], v[28:29], v[182:183], v[178:179] op_sel_hi:[1,0,1]
	v_pk_fma_f32 v[174:175], v[30:31], v[182:183], v[180:181] op_sel_hi:[1,0,1]
	v_cndmask_b32_e64 v176, v0, v1, s[0:1]
	s_waitcnt vmcnt(12)
	v_cvt_scalef32_pk32_f32_fp6 v[0:31], v[132:137], 1.0
	v_readlane_b32 s12, v106, 26
	v_readlane_b32 s13, v109, 26
	v_pk_fma_f32 v[126:127], v[0:1], v[176:177], v[126:127] op_sel_hi:[1,0,1]
	v_mov_b32_e32 v1, s12
	v_mov_b32_e32 v0, s13
	v_pk_fma_f32 v[128:129], v[2:3], v[176:177], v[128:129] op_sel_hi:[1,0,1]
	v_pk_fma_f32 v[130:131], v[4:5], v[176:177], v[130:131] op_sel_hi:[1,0,1]
	v_pk_fma_f32 v[132:133], v[6:7], v[176:177], v[150:151] op_sel_hi:[1,0,1]
	v_pk_fma_f32 v[134:135], v[8:9], v[176:177], v[152:153] op_sel_hi:[1,0,1]
	v_pk_fma_f32 v[136:137], v[10:11], v[176:177], v[154:155] op_sel_hi:[1,0,1]
	v_pk_fma_f32 v[150:151], v[12:13], v[176:177], v[156:157] op_sel_hi:[1,0,1]
	v_pk_fma_f32 v[152:153], v[14:15], v[176:177], v[158:159] op_sel_hi:[1,0,1]
	v_pk_fma_f32 v[154:155], v[16:17], v[176:177], v[160:161] op_sel_hi:[1,0,1]
	v_pk_fma_f32 v[156:157], v[18:19], v[176:177], v[162:163] op_sel_hi:[1,0,1]
	v_pk_fma_f32 v[158:159], v[20:21], v[176:177], v[164:165] op_sel_hi:[1,0,1]
	v_pk_fma_f32 v[160:161], v[22:23], v[176:177], v[166:167] op_sel_hi:[1,0,1]
	v_pk_fma_f32 v[162:163], v[24:25], v[176:177], v[168:169] op_sel_hi:[1,0,1]
	v_pk_fma_f32 v[164:165], v[26:27], v[176:177], v[170:171] op_sel_hi:[1,0,1]
	v_pk_fma_f32 v[166:167], v[28:29], v[176:177], v[172:173] op_sel_hi:[1,0,1]
	v_pk_fma_f32 v[168:169], v[30:31], v[176:177], v[174:175] op_sel_hi:[1,0,1]
	v_cndmask_b32_e64 v170, v0, v1, s[0:1]
	s_waitcnt vmcnt(10)
	v_cvt_scalef32_pk32_f32_fp6 v[0:31], v[138:143], 1.0
	v_readlane_b32 s12, v106, 27
	v_readlane_b32 s13, v109, 27
	v_pk_fma_f32 v[126:127], v[0:1], v[170:171], v[126:127] op_sel_hi:[1,0,1]
	v_mov_b32_e32 v1, s12
	v_mov_b32_e32 v0, s13
	v_pk_fma_f32 v[128:129], v[2:3], v[170:171], v[128:129] op_sel_hi:[1,0,1]
	v_pk_fma_f32 v[130:131], v[4:5], v[170:171], v[130:131] op_sel_hi:[1,0,1]
	v_pk_fma_f32 v[132:133], v[6:7], v[170:171], v[132:133] op_sel_hi:[1,0,1]
	v_pk_fma_f32 v[134:135], v[8:9], v[170:171], v[134:135] op_sel_hi:[1,0,1]
	v_pk_fma_f32 v[136:137], v[10:11], v[170:171], v[136:137] op_sel_hi:[1,0,1]
	v_pk_fma_f32 v[138:139], v[12:13], v[170:171], v[150:151] op_sel_hi:[1,0,1]
	v_pk_fma_f32 v[140:141], v[14:15], v[170:171], v[152:153] op_sel_hi:[1,0,1]
	v_pk_fma_f32 v[142:143], v[16:17], v[170:171], v[154:155] op_sel_hi:[1,0,1]
	v_pk_fma_f32 v[150:151], v[18:19], v[170:171], v[156:157] op_sel_hi:[1,0,1]
	v_pk_fma_f32 v[152:153], v[20:21], v[170:171], v[158:159] op_sel_hi:[1,0,1]
	v_pk_fma_f32 v[154:155], v[22:23], v[170:171], v[160:161] op_sel_hi:[1,0,1]
	v_pk_fma_f32 v[156:157], v[24:25], v[170:171], v[162:163] op_sel_hi:[1,0,1]
	v_pk_fma_f32 v[158:159], v[26:27], v[170:171], v[164:165] op_sel_hi:[1,0,1]
	v_pk_fma_f32 v[160:161], v[28:29], v[170:171], v[166:167] op_sel_hi:[1,0,1]
	v_pk_fma_f32 v[162:163], v[30:31], v[170:171], v[168:169] op_sel_hi:[1,0,1]
	v_cndmask_b32_e64 v164, v0, v1, s[0:1]
	s_waitcnt vmcnt(8)
	v_cvt_scalef32_pk32_f32_fp6 v[0:31], v[144:149], 1.0
	v_readlane_b32 s12, v106, 28
	v_readlane_b32 s13, v109, 28
	v_pk_fma_f32 v[126:127], v[0:1], v[164:165], v[126:127] op_sel_hi:[1,0,1]
	v_mov_b32_e32 v1, s12
	v_mov_b32_e32 v0, s13
	v_pk_fma_f32 v[128:129], v[2:3], v[164:165], v[128:129] op_sel_hi:[1,0,1]
	v_pk_fma_f32 v[130:131], v[4:5], v[164:165], v[130:131] op_sel_hi:[1,0,1]
	v_pk_fma_f32 v[132:133], v[6:7], v[164:165], v[132:133] op_sel_hi:[1,0,1]
	v_pk_fma_f32 v[134:135], v[8:9], v[164:165], v[134:135] op_sel_hi:[1,0,1]
	v_pk_fma_f32 v[136:137], v[10:11], v[164:165], v[136:137] op_sel_hi:[1,0,1]
	v_pk_fma_f32 v[138:139], v[12:13], v[164:165], v[138:139] op_sel_hi:[1,0,1]
	v_pk_fma_f32 v[140:141], v[14:15], v[164:165], v[140:141] op_sel_hi:[1,0,1]
	v_pk_fma_f32 v[142:143], v[16:17], v[164:165], v[142:143] op_sel_hi:[1,0,1]
	v_pk_fma_f32 v[144:145], v[18:19], v[164:165], v[150:151] op_sel_hi:[1,0,1]
	v_pk_fma_f32 v[146:147], v[20:21], v[164:165], v[152:153] op_sel_hi:[1,0,1]
	v_pk_fma_f32 v[148:149], v[22:23], v[164:165], v[154:155] op_sel_hi:[1,0,1]
	v_pk_fma_f32 v[150:151], v[24:25], v[164:165], v[156:157] op_sel_hi:[1,0,1]
	v_pk_fma_f32 v[152:153], v[26:27], v[164:165], v[158:159] op_sel_hi:[1,0,1]
	v_pk_fma_f32 v[154:155], v[28:29], v[164:165], v[160:161] op_sel_hi:[1,0,1]
	v_pk_fma_f32 v[156:157], v[30:31], v[164:165], v[162:163] op_sel_hi:[1,0,1]
	v_cndmask_b32_e64 v158, v0, v1, s[0:1]
	s_waitcnt vmcnt(6)
; DI void phase_peer_out(const Params& p, char* lds) {
;     ...
; #pragma unroll
;     for (int kb = 0; kb < 8; ++kb) {
;       v6u qb[8];
; #pragma unroll
;       for (int k = 0; k < 8; ++k) {
;         const int e0 = __builtin_amdgcn_readlane(el[0], kb * 8 + k), e1 = __builtin_amdgcn_readlane(el[1], kb * 8 + k);
;         qb[k] = load6(V6 + (size_t)(hb ? e1 : e0) * 768);
;       }
; #pragma unroll
;       for (int k = 0; k < 8; ++k) {
;         const float c0 = __uint_as_float(__builtin_amdgcn_readlane(__float_as_uint(coefv[0]), kb * 8 + k)), c1 = __uint_as_float(__builtin_amdgcn_readlane(__float_as_uint(coefv[1]), kb * 8 + k));
;         const float cf = hb ? c1 : c0;
;         const f32x2 c2 = {cf, cf};
;         const v32f f = __builtin_amdgcn_cvt_scalef32_pk32_f32_fp6(qb[k], 1.0f);
; #pragma unroll
;         for (int i = 0; i < 16; ++i) o2[i] = f32x2{f[2 * i], f[2 * i + 1]} * c2 + o2[i];
;       }
;     }
	v_cvt_scalef32_pk32_f32_fp6 v[0:31], v[50:55], 1.0
	v_readlane_b32 s12, v106, 29
	v_readlane_b32 s13, v109, 29
	v_pk_fma_f32 v[50:51], v[0:1], v[158:159], v[126:127] op_sel_hi:[1,0,1]
	v_mov_b32_e32 v1, s12
	v_mov_b32_e32 v0, s13
	v_pk_fma_f32 v[52:53], v[2:3], v[158:159], v[128:129] op_sel_hi:[1,0,1]
	v_pk_fma_f32 v[54:55], v[4:5], v[158:159], v[130:131] op_sel_hi:[1,0,1]
	v_pk_fma_f32 v[126:127], v[6:7], v[158:159], v[132:133] op_sel_hi:[1,0,1]
	v_pk_fma_f32 v[128:129], v[8:9], v[158:159], v[134:135] op_sel_hi:[1,0,1]
	v_pk_fma_f32 v[130:131], v[10:11], v[158:159], v[136:137] op_sel_hi:[1,0,1]
	v_pk_fma_f32 v[132:133], v[12:13], v[158:159], v[138:139] op_sel_hi:[1,0,1]
	v_pk_fma_f32 v[134:135], v[14:15], v[158:159], v[140:141] op_sel_hi:[1,0,1]
	v_pk_fma_f32 v[136:137], v[16:17], v[158:159], v[142:143] op_sel_hi:[1,0,1]
	v_pk_fma_f32 v[138:139], v[18:19], v[158:159], v[144:145] op_sel_hi:[1,0,1]
	v_pk_fma_f32 v[140:141], v[20:21], v[158:159], v[146:147] op_sel_hi:[1,0,1]
	v_pk_fma_f32 v[142:143], v[22:23], v[158:159], v[148:149] op_sel_hi:[1,0,1]
	v_pk_fma_f32 v[144:145], v[24:25], v[158:159], v[150:151] op_sel_hi:[1,0,1]
	v_pk_fma_f32 v[146:147], v[26:27], v[158:159], v[152:153] op_sel_hi:[1,0,1]
	v_pk_fma_f32 v[148:149], v[28:29], v[158:159], v[154:155] op_sel_hi:[1,0,1]
	v_pk_fma_f32 v[150:151], v[30:31], v[158:159], v[156:157] op_sel_hi:[1,0,1]
	v_cndmask_b32_e64 v152, v0, v1, s[0:1]
	s_waitcnt vmcnt(4)
	v_cvt_scalef32_pk32_f32_fp6 v[0:31], v[44:49], 1.0
	v_readlane_b32 s12, v106, 30
	v_readlane_b32 s13, v109, 30
	v_pk_fma_f32 v[44:45], v[0:1], v[152:153], v[50:51] op_sel_hi:[1,0,1]
	v_mov_b32_e32 v1, s12
	v_mov_b32_e32 v0, s13
	v_pk_fma_f32 v[46:47], v[2:3], v[152:153], v[52:53] op_sel_hi:[1,0,1]
	v_pk_fma_f32 v[48:49], v[4:5], v[152:153], v[54:55] op_sel_hi:[1,0,1]
	v_pk_fma_f32 v[50:51], v[6:7], v[152:153], v[126:127] op_sel_hi:[1,0,1]
	v_pk_fma_f32 v[52:53], v[8:9], v[152:153], v[128:129] op_sel_hi:[1,0,1]
	v_pk_fma_f32 v[54:55], v[10:11], v[152:153], v[130:131] op_sel_hi:[1,0,1]
	v_pk_fma_f32 v[126:127], v[12:13], v[152:153], v[132:133] op_sel_hi:[1,0,1]
	v_pk_fma_f32 v[128:129], v[14:15], v[152:153], v[134:135] op_sel_hi:[1,0,1]
	v_pk_fma_f32 v[130:131], v[16:17], v[152:153], v[136:137] op_sel_hi:[1,0,1]
	v_pk_fma_f32 v[132:133], v[18:19], v[152:153], v[138:139] op_sel_hi:[1,0,1]
	v_pk_fma_f32 v[134:135], v[20:21], v[152:153], v[140:141] op_sel_hi:[1,0,1]
	v_pk_fma_f32 v[136:137], v[22:23], v[152:153], v[142:143] op_sel_hi:[1,0,1]
	v_pk_fma_f32 v[138:139], v[24:25], v[152:153], v[144:145] op_sel_hi:[1,0,1]
	v_pk_fma_f32 v[140:141], v[26:27], v[152:153], v[146:147] op_sel_hi:[1,0,1]
	v_pk_fma_f32 v[142:143], v[28:29], v[152:153], v[148:149] op_sel_hi:[1,0,1]
	v_pk_fma_f32 v[144:145], v[30:31], v[152:153], v[150:151] op_sel_hi:[1,0,1]
	v_cndmask_b32_e64 v146, v0, v1, s[0:1]
	s_waitcnt vmcnt(1)
	v_cvt_scalef32_pk32_f32_fp6 v[0:31], v[38:43], 1.0
	v_readlane_b32 s12, v106, 31
	v_readlane_b32 s13, v109, 31
	v_pk_fma_f32 v[38:39], v[0:1], v[146:147], v[44:45] op_sel_hi:[1,0,1]
	v_mov_b32_e32 v1, s12
	v_mov_b32_e32 v0, s13
	v_readlane_b32 s12, v108, 32
	v_readlane_b32 s13, v107, 32
	v_pk_fma_f32 v[40:41], v[2:3], v[146:147], v[46:47] op_sel_hi:[1,0,1]
	v_pk_fma_f32 v[42:43], v[4:5], v[146:147], v[48:49] op_sel_hi:[1,0,1]
	v_pk_fma_f32 v[44:45], v[6:7], v[146:147], v[50:51] op_sel_hi:[1,0,1]
	v_pk_fma_f32 v[46:47], v[8:9], v[146:147], v[52:53] op_sel_hi:[1,0,1]
	v_pk_fma_f32 v[48:49], v[10:11], v[146:147], v[54:55] op_sel_hi:[1,0,1]
	v_pk_fma_f32 v[50:51], v[12:13], v[146:147], v[126:127] op_sel_hi:[1,0,1]
	v_pk_fma_f32 v[52:53], v[14:15], v[146:147], v[128:129] op_sel_hi:[1,0,1]
	v_pk_fma_f32 v[54:55], v[16:17], v[146:147], v[130:131] op_sel_hi:[1,0,1]
	v_pk_fma_f32 v[132:133], v[18:19], v[146:147], v[132:133] op_sel_hi:[1,0,1]
	v_pk_fma_f32 v[134:135], v[20:21], v[146:147], v[134:135] op_sel_hi:[1,0,1]
	v_pk_fma_f32 v[136:137], v[22:23], v[146:147], v[136:137] op_sel_hi:[1,0,1]
	v_pk_fma_f32 v[138:139], v[24:25], v[146:147], v[138:139] op_sel_hi:[1,0,1]
	v_pk_fma_f32 v[140:141], v[26:27], v[146:147], v[140:141] op_sel_hi:[1,0,1]
	v_pk_fma_f32 v[142:143], v[28:29], v[146:147], v[142:143] op_sel_hi:[1,0,1]
	v_pk_fma_f32 v[144:145], v[30:31], v[146:147], v[144:145] op_sel_hi:[1,0,1]
	v_cndmask_b32_e64 v146, v0, v1, s[0:1]
	v_mov_b32_e32 v0, s13
	v_mov_b32_e32 v1, s12
	v_cndmask_b32_e64 v0, v0, v1, s[0:1]
	v_mad_i64_i32 v[130:131], s[12:13], v0, s23, v[64:65]
	s_waitcnt vmcnt(0)
; DI void phase_peer_out(const Params& p, char* lds) {
;     ...
; #pragma unroll
;     for (int kb = 0; kb < 8; ++kb) {
;       v6u qb[8];
; #pragma unroll
;       for (int k = 0; k < 8; ++k) {
;         const int e0 = __builtin_amdgcn_readlane(el[0], kb * 8 + k), e1 = __builtin_amdgcn_readlane(el[1], kb * 8 + k);
;         qb[k] = load6(V6 + (size_t)(hb ? e1 : e0) * 768);
;       }
; #pragma unroll
;       for (int k = 0; k < 8; ++k) {
;         const float c0 = __uint_as_float(__builtin_amdgcn_readlane(__float_as_uint(coefv[0]), kb * 8 + k)), c1 = __uint_as_float(__builtin_amdgcn_readlane(__float_as_uint(coefv[1]), kb * 8 + k));
;         const float cf = hb ? c1 : c0;
;         const f32x2 c2 = {cf, cf};
;         const v32f f = __builtin_amdgcn_cvt_scalef32_pk32_f32_fp6(qb[k], 1.0f);
; #pragma unroll
;         for (int i = 0; i < 16; ++i) o2[i] = f32x2{f[2 * i], f[2 * i + 1]} * c2 + o2[i];
;       }
;     }
	v_cvt_scalef32_pk32_f32_fp6 v[0:31], v[32:37], 1.0
	v_readlane_b32 s12, v108, 33
	v_readlane_b32 s13, v107, 33
	v_pk_fma_f32 v[150:151], v[0:1], v[146:147], v[38:39] op_sel_hi:[1,0,1]
	v_mov_b32_e32 v1, s12
	v_mov_b32_e32 v0, s13
	v_cndmask_b32_e64 v0, v0, v1, s[0:1]
	v_mad_i64_i32 v[0:1], s[12:13], v0, s23, v[64:65]
	v_readlane_b32 s12, v108, 34
	v_readlane_b32 s13, v107, 34
	global_load_dwordx4 v[126:129], v[130:131], off
	v_pk_fma_f32 v[168:169], v[18:19], v[146:147], v[132:133] op_sel_hi:[1,0,1]
	global_load_dwordx2 v[130:131], v[130:131], off offset:16
	v_pk_fma_f32 v[170:171], v[20:21], v[146:147], v[134:135] op_sel_hi:[1,0,1]
	v_pk_fma_f32 v[172:173], v[22:23], v[146:147], v[136:137] op_sel_hi:[1,0,1]
	global_load_dwordx2 v[136:137], v[0:1], off offset:16
	global_load_dwordx4 v[132:135], v[0:1], off
	v_mov_b32_e32 v0, s13
	v_mov_b32_e32 v1, s12
	v_cndmask_b32_e64 v0, v0, v1, s[0:1]
	v_mad_i64_i32 v[0:1], s[12:13], v0, s23, v[64:65]
	v_readlane_b32 s12, v108, 35
	v_readlane_b32 s13, v107, 35
	v_pk_fma_f32 v[152:153], v[2:3], v[146:147], v[40:41] op_sel_hi:[1,0,1]
	v_mov_b32_e32 v3, s12
	v_mov_b32_e32 v2, s13
	v_cndmask_b32_e64 v2, v2, v3, s[0:1]
	v_mad_i64_i32 v[2:3], s[12:13], v2, s23, v[64:65]
	v_readlane_b32 s12, v108, 36
	v_readlane_b32 s13, v107, 36
	v_pk_fma_f32 v[154:155], v[4:5], v[146:147], v[42:43] op_sel_hi:[1,0,1]
	v_pk_fma_f32 v[156:157], v[6:7], v[146:147], v[44:45] op_sel_hi:[1,0,1]
	v_pk_fma_f32 v[158:159], v[8:9], v[146:147], v[46:47] op_sel_hi:[1,0,1]
	v_pk_fma_f32 v[160:161], v[10:11], v[146:147], v[48:49] op_sel_hi:[1,0,1]
	v_pk_fma_f32 v[162:163], v[12:13], v[146:147], v[50:51] op_sel_hi:[1,0,1]
	v_pk_fma_f32 v[164:165], v[14:15], v[146:147], v[52:53] op_sel_hi:[1,0,1]
	v_pk_fma_f32 v[166:167], v[16:17], v[146:147], v[54:55] op_sel_hi:[1,0,1]
	v_pk_fma_f32 v[174:175], v[24:25], v[146:147], v[138:139] op_sel_hi:[1,0,1]
	v_pk_fma_f32 v[176:177], v[26:27], v[146:147], v[140:141] op_sel_hi:[1,0,1]
	v_pk_fma_f32 v[178:179], v[28:29], v[146:147], v[142:143] op_sel_hi:[1,0,1]
	v_pk_fma_f32 v[180:181], v[30:31], v[146:147], v[144:145] op_sel_hi:[1,0,1]
	global_load_dwordx4 v[138:141], v[0:1], off
	global_load_dwordx2 v[142:143], v[0:1], off offset:16
	global_load_dwordx4 v[144:147], v[2:3], off
	v_mov_b32_e32 v0, s13
	v_mov_b32_e32 v1, s12
	v_cndmask_b32_e64 v0, v0, v1, s[0:1]
	v_mad_i64_i32 v[0:1], s[12:13], v0, s23, v[64:65]
	v_readlane_b32 s12, v108, 37
	v_readlane_b32 s13, v107, 37
	global_load_dwordx2 v[148:149], v[2:3], off offset:16
	global_load_dwordx4 v[50:53], v[0:1], off
	v_mov_b32_e32 v2, s13
	v_mov_b32_e32 v3, s12
	v_cndmask_b32_e64 v2, v2, v3, s[0:1]
	v_mad_i64_i32 v[2:3], s[12:13], v2, s23, v[64:65]
	v_readlane_b32 s12, v108, 38
	v_readlane_b32 s13, v107, 38
	global_load_dwordx2 v[54:55], v[0:1], off offset:16
	global_load_dwordx4 v[44:47], v[2:3], off
	v_mov_b32_e32 v0, s13
	v_mov_b32_e32 v1, s12
	v_cndmask_b32_e64 v0, v0, v1, s[0:1]
	v_mad_i64_i32 v[0:1], s[12:13], v0, s23, v[64:65]
	v_readlane_b32 s12, v108, 39
	v_readlane_b32 s13, v107, 39
	global_load_dwordx2 v[48:49], v[2:3], off offset:16
	global_load_dwordx4 v[38:41], v[0:1], off
	v_mov_b32_e32 v2, s13
	v_mov_b32_e32 v3, s12
	v_cndmask_b32_e64 v2, v2, v3, s[0:1]
	v_mad_i64_i32 v[2:3], s[12:13], v2, s23, v[64:65]
	global_load_dwordx2 v[36:37], v[2:3], off offset:16
	global_load_dwordx2 v[42:43], v[0:1], off offset:16
	global_load_dwordx4 v[32:35], v[2:3], off
	v_readlane_b32 s12, v106, 32
	v_readlane_b32 s13, v109, 32
	s_nop 0
	v_mov_b32_e32 v1, s12
	v_mov_b32_e32 v0, s13
	v_cndmask_b32_e64 v182, v0, v1, s[0:1]
	v_readlane_b32 s12, v106, 33
	v_readlane_b32 s13, v109, 33
	s_waitcnt vmcnt(14)
	v_cvt_scalef32_pk32_f32_fp6 v[0:31], v[126:131], 1.0
	v_pk_fma_f32 v[126:127], v[0:1], v[182:183], v[150:151] op_sel_hi:[1,0,1]
	v_mov_b32_e32 v0, s13
	v_mov_b32_e32 v1, s12
	v_pk_fma_f32 v[128:129], v[2:3], v[182:183], v[152:153] op_sel_hi:[1,0,1]
	v_pk_fma_f32 v[130:131], v[4:5], v[182:183], v[154:155] op_sel_hi:[1,0,1]
	v_pk_fma_f32 v[150:151], v[6:7], v[182:183], v[156:157] op_sel_hi:[1,0,1]
	v_pk_fma_f32 v[152:153], v[8:9], v[182:183], v[158:159] op_sel_hi:[1,0,1]
	v_pk_fma_f32 v[154:155], v[10:11], v[182:183], v[160:161] op_sel_hi:[1,0,1]
	v_pk_fma_f32 v[156:157], v[12:13], v[182:183], v[162:163] op_sel_hi:[1,0,1]
	v_pk_fma_f32 v[158:159], v[14:15], v[182:183], v[164:165] op_sel_hi:[1,0,1]
	v_pk_fma_f32 v[160:161], v[16:17], v[182:183], v[166:167] op_sel_hi:[1,0,1]
	v_pk_fma_f32 v[162:163], v[18:19], v[182:183], v[168:169] op_sel_hi:[1,0,1]
	v_pk_fma_f32 v[164:165], v[20:21], v[182:183], v[170:171] op_sel_hi:[1,0,1]
	v_pk_fma_f32 v[166:167], v[22:23], v[182:183], v[172:173] op_sel_hi:[1,0,1]
	v_pk_fma_f32 v[168:169], v[24:25], v[182:183], v[174:175] op_sel_hi:[1,0,1]
	v_pk_fma_f32 v[170:171], v[26:27], v[182:183], v[176:177] op_sel_hi:[1,0,1]
	v_pk_fma_f32 v[172:173], v[28:29], v[182:183], v[178:179] op_sel_hi:[1,0,1]
	v_pk_fma_f32 v[174:175], v[30:31], v[182:183], v[180:181] op_sel_hi:[1,0,1]
	v_cndmask_b32_e64 v176, v0, v1, s[0:1]
	s_waitcnt vmcnt(12)
; DI void phase_peer_out(const Params& p, char* lds) {
;     ...
; #pragma unroll
;     for (int kb = 0; kb < 8; ++kb) {
;       v6u qb[8];
; #pragma unroll
;       for (int k = 0; k < 8; ++k) {
;         const int e0 = __builtin_amdgcn_readlane(el[0], kb * 8 + k), e1 = __builtin_amdgcn_readlane(el[1], kb * 8 + k);
;         qb[k] = load6(V6 + (size_t)(hb ? e1 : e0) * 768);
;       }
; #pragma unroll
;       for (int k = 0; k < 8; ++k) {
;         const float c0 = __uint_as_float(__builtin_amdgcn_readlane(__float_as_uint(coefv[0]), kb * 8 + k)), c1 = __uint_as_float(__builtin_amdgcn_readlane(__float_as_uint(coefv[1]), kb * 8 + k));
;         const float cf = hb ? c1 : c0;
;         const f32x2 c2 = {cf, cf};
;         const v32f f = __builtin_amdgcn_cvt_scalef32_pk32_f32_fp6(qb[k], 1.0f);
; #pragma unroll
;         for (int i = 0; i < 16; ++i) o2[i] = f32x2{f[2 * i], f[2 * i + 1]} * c2 + o2[i];
;       }
;     }
	v_cvt_scalef32_pk32_f32_fp6 v[0:31], v[132:137], 1.0
	v_readlane_b32 s12, v106, 34
	v_readlane_b32 s13, v109, 34
	v_pk_fma_f32 v[126:127], v[0:1], v[176:177], v[126:127] op_sel_hi:[1,0,1]
	v_mov_b32_e32 v1, s12
	v_mov_b32_e32 v0, s13
	v_pk_fma_f32 v[128:129], v[2:3], v[176:177], v[128:129] op_sel_hi:[1,0,1]
	v_pk_fma_f32 v[130:131], v[4:5], v[176:177], v[130:131] op_sel_hi:[1,0,1]
	v_pk_fma_f32 v[132:133], v[6:7], v[176:177], v[150:151] op_sel_hi:[1,0,1]
	v_pk_fma_f32 v[134:135], v[8:9], v[176:177], v[152:153] op_sel_hi:[1,0,1]
	v_pk_fma_f32 v[136:137], v[10:11], v[176:177], v[154:155] op_sel_hi:[1,0,1]
	v_pk_fma_f32 v[150:151], v[12:13], v[176:177], v[156:157] op_sel_hi:[1,0,1]
	v_pk_fma_f32 v[152:153], v[14:15], v[176:177], v[158:159] op_sel_hi:[1,0,1]
	v_pk_fma_f32 v[154:155], v[16:17], v[176:177], v[160:161] op_sel_hi:[1,0,1]
	v_pk_fma_f32 v[156:157], v[18:19], v[176:177], v[162:163] op_sel_hi:[1,0,1]
	v_pk_fma_f32 v[158:159], v[20:21], v[176:177], v[164:165] op_sel_hi:[1,0,1]
	v_pk_fma_f32 v[160:161], v[22:23], v[176:177], v[166:167] op_sel_hi:[1,0,1]
	v_pk_fma_f32 v[162:163], v[24:25], v[176:177], v[168:169] op_sel_hi:[1,0,1]
	v_pk_fma_f32 v[164:165], v[26:27], v[176:177], v[170:171] op_sel_hi:[1,0,1]
	v_pk_fma_f32 v[166:167], v[28:29], v[176:177], v[172:173] op_sel_hi:[1,0,1]
	v_pk_fma_f32 v[168:169], v[30:31], v[176:177], v[174:175] op_sel_hi:[1,0,1]
	v_cndmask_b32_e64 v170, v0, v1, s[0:1]
	s_waitcnt vmcnt(10)
	v_cvt_scalef32_pk32_f32_fp6 v[0:31], v[138:143], 1.0
	v_readlane_b32 s12, v106, 35
	v_readlane_b32 s13, v109, 35
	v_pk_fma_f32 v[126:127], v[0:1], v[170:171], v[126:127] op_sel_hi:[1,0,1]
	v_mov_b32_e32 v1, s12
	v_mov_b32_e32 v0, s13
	v_pk_fma_f32 v[128:129], v[2:3], v[170:171], v[128:129] op_sel_hi:[1,0,1]
	v_pk_fma_f32 v[130:131], v[4:5], v[170:171], v[130:131] op_sel_hi:[1,0,1]
	v_pk_fma_f32 v[132:133], v[6:7], v[170:171], v[132:133] op_sel_hi:[1,0,1]
	v_pk_fma_f32 v[134:135], v[8:9], v[170:171], v[134:135] op_sel_hi:[1,0,1]
	v_pk_fma_f32 v[136:137], v[10:11], v[170:171], v[136:137] op_sel_hi:[1,0,1]
	v_pk_fma_f32 v[138:139], v[12:13], v[170:171], v[150:151] op_sel_hi:[1,0,1]
	v_pk_fma_f32 v[140:141], v[14:15], v[170:171], v[152:153] op_sel_hi:[1,0,1]
	v_pk_fma_f32 v[142:143], v[16:17], v[170:171], v[154:155] op_sel_hi:[1,0,1]
	v_pk_fma_f32 v[150:151], v[18:19], v[170:171], v[156:157] op_sel_hi:[1,0,1]
	v_pk_fma_f32 v[152:153], v[20:21], v[170:171], v[158:159] op_sel_hi:[1,0,1]
	v_pk_fma_f32 v[154:155], v[22:23], v[170:171], v[160:161] op_sel_hi:[1,0,1]
	v_pk_fma_f32 v[156:157], v[24:25], v[170:171], v[162:163] op_sel_hi:[1,0,1]
	v_pk_fma_f32 v[158:159], v[26:27], v[170:171], v[164:165] op_sel_hi:[1,0,1]
	v_pk_fma_f32 v[160:161], v[28:29], v[170:171], v[166:167] op_sel_hi:[1,0,1]
	v_pk_fma_f32 v[162:163], v[30:31], v[170:171], v[168:169] op_sel_hi:[1,0,1]
	v_cndmask_b32_e64 v164, v0, v1, s[0:1]
	s_waitcnt vmcnt(8)
	v_cvt_scalef32_pk32_f32_fp6 v[0:31], v[144:149], 1.0
	v_readlane_b32 s12, v106, 36
	v_readlane_b32 s13, v109, 36
	v_pk_fma_f32 v[126:127], v[0:1], v[164:165], v[126:127] op_sel_hi:[1,0,1]
	v_mov_b32_e32 v1, s12
	v_mov_b32_e32 v0, s13
	v_pk_fma_f32 v[128:129], v[2:3], v[164:165], v[128:129] op_sel_hi:[1,0,1]
	v_pk_fma_f32 v[130:131], v[4:5], v[164:165], v[130:131] op_sel_hi:[1,0,1]
	v_pk_fma_f32 v[132:133], v[6:7], v[164:165], v[132:133] op_sel_hi:[1,0,1]
	v_pk_fma_f32 v[134:135], v[8:9], v[164:165], v[134:135] op_sel_hi:[1,0,1]
	v_pk_fma_f32 v[136:137], v[10:11], v[164:165], v[136:137] op_sel_hi:[1,0,1]
	v_pk_fma_f32 v[138:139], v[12:13], v[164:165], v[138:139] op_sel_hi:[1,0,1]
	v_pk_fma_f32 v[140:141], v[14:15], v[164:165], v[140:141] op_sel_hi:[1,0,1]
	v_pk_fma_f32 v[142:143], v[16:17], v[164:165], v[142:143] op_sel_hi:[1,0,1]
	v_pk_fma_f32 v[144:145], v[18:19], v[164:165], v[150:151] op_sel_hi:[1,0,1]
	v_pk_fma_f32 v[146:147], v[20:21], v[164:165], v[152:153] op_sel_hi:[1,0,1]
	v_pk_fma_f32 v[148:149], v[22:23], v[164:165], v[154:155] op_sel_hi:[1,0,1]
	v_pk_fma_f32 v[150:151], v[24:25], v[164:165], v[156:157] op_sel_hi:[1,0,1]
	v_pk_fma_f32 v[152:153], v[26:27], v[164:165], v[158:159] op_sel_hi:[1,0,1]
	v_pk_fma_f32 v[154:155], v[28:29], v[164:165], v[160:161] op_sel_hi:[1,0,1]
	v_pk_fma_f32 v[156:157], v[30:31], v[164:165], v[162:163] op_sel_hi:[1,0,1]
	v_cndmask_b32_e64 v158, v0, v1, s[0:1]
	s_waitcnt vmcnt(6)
	v_cvt_scalef32_pk32_f32_fp6 v[0:31], v[50:55], 1.0
	v_readlane_b32 s12, v106, 37
	v_readlane_b32 s13, v109, 37
	v_pk_fma_f32 v[50:51], v[0:1], v[158:159], v[126:127] op_sel_hi:[1,0,1]
	v_mov_b32_e32 v1, s12
	v_mov_b32_e32 v0, s13
	v_pk_fma_f32 v[52:53], v[2:3], v[158:159], v[128:129] op_sel_hi:[1,0,1]
	v_pk_fma_f32 v[54:55], v[4:5], v[158:159], v[130:131] op_sel_hi:[1,0,1]
	v_pk_fma_f32 v[126:127], v[6:7], v[158:159], v[132:133] op_sel_hi:[1,0,1]
	v_pk_fma_f32 v[128:129], v[8:9], v[158:159], v[134:135] op_sel_hi:[1,0,1]
	v_pk_fma_f32 v[130:131], v[10:11], v[158:159], v[136:137] op_sel_hi:[1,0,1]
	v_pk_fma_f32 v[132:133], v[12:13], v[158:159], v[138:139] op_sel_hi:[1,0,1]
	v_pk_fma_f32 v[134:135], v[14:15], v[158:159], v[140:141] op_sel_hi:[1,0,1]
	v_pk_fma_f32 v[136:137], v[16:17], v[158:159], v[142:143] op_sel_hi:[1,0,1]
	v_pk_fma_f32 v[138:139], v[18:19], v[158:159], v[144:145] op_sel_hi:[1,0,1]
	v_pk_fma_f32 v[140:141], v[20:21], v[158:159], v[146:147] op_sel_hi:[1,0,1]
	v_pk_fma_f32 v[142:143], v[22:23], v[158:159], v[148:149] op_sel_hi:[1,0,1]
	v_pk_fma_f32 v[144:145], v[24:25], v[158:159], v[150:151] op_sel_hi:[1,0,1]
	v_pk_fma_f32 v[146:147], v[26:27], v[158:159], v[152:153] op_sel_hi:[1,0,1]
	v_pk_fma_f32 v[148:149], v[28:29], v[158:159], v[154:155] op_sel_hi:[1,0,1]
	v_pk_fma_f32 v[150:151], v[30:31], v[158:159], v[156:157] op_sel_hi:[1,0,1]
	v_cndmask_b32_e64 v152, v0, v1, s[0:1]
	s_waitcnt vmcnt(4)
; DI void phase_peer_out(const Params& p, char* lds) {
;     ...
; #pragma unroll
;     for (int kb = 0; kb < 8; ++kb) {
;       v6u qb[8];
; #pragma unroll
;       for (int k = 0; k < 8; ++k) {
;         const int e0 = __builtin_amdgcn_readlane(el[0], kb * 8 + k), e1 = __builtin_amdgcn_readlane(el[1], kb * 8 + k);
;         qb[k] = load6(V6 + (size_t)(hb ? e1 : e0) * 768);
;       }
; #pragma unroll
;       for (int k = 0; k < 8; ++k) {
;         const float c0 = __uint_as_float(__builtin_amdgcn_readlane(__float_as_uint(coefv[0]), kb * 8 + k)), c1 = __uint_as_float(__builtin_amdgcn_readlane(__float_as_uint(coefv[1]), kb * 8 + k));
;         const float cf = hb ? c1 : c0;
;         const f32x2 c2 = {cf, cf};
;         const v32f f = __builtin_amdgcn_cvt_scalef32_pk32_f32_fp6(qb[k], 1.0f);
; #pragma unroll
;         for (int i = 0; i < 16; ++i) o2[i] = f32x2{f[2 * i], f[2 * i + 1]} * c2 + o2[i];
;       }
;     }
	v_cvt_scalef32_pk32_f32_fp6 v[0:31], v[44:49], 1.0
	v_readlane_b32 s12, v106, 38
	v_readlane_b32 s13, v109, 38
	v_pk_fma_f32 v[44:45], v[0:1], v[152:153], v[50:51] op_sel_hi:[1,0,1]
	v_mov_b32_e32 v1, s12
	v_mov_b32_e32 v0, s13
	v_pk_fma_f32 v[46:47], v[2:3], v[152:153], v[52:53] op_sel_hi:[1,0,1]
	v_pk_fma_f32 v[48:49], v[4:5], v[152:153], v[54:55] op_sel_hi:[1,0,1]
	v_pk_fma_f32 v[50:51], v[6:7], v[152:153], v[126:127] op_sel_hi:[1,0,1]
	v_pk_fma_f32 v[52:53], v[8:9], v[152:153], v[128:129] op_sel_hi:[1,0,1]
	v_pk_fma_f32 v[54:55], v[10:11], v[152:153], v[130:131] op_sel_hi:[1,0,1]
	v_pk_fma_f32 v[126:127], v[12:13], v[152:153], v[132:133] op_sel_hi:[1,0,1]
	v_pk_fma_f32 v[128:129], v[14:15], v[152:153], v[134:135] op_sel_hi:[1,0,1]
	v_pk_fma_f32 v[130:131], v[16:17], v[152:153], v[136:137] op_sel_hi:[1,0,1]
	v_pk_fma_f32 v[132:133], v[18:19], v[152:153], v[138:139] op_sel_hi:[1,0,1]
	v_pk_fma_f32 v[134:135], v[20:21], v[152:153], v[140:141] op_sel_hi:[1,0,1]
	v_pk_fma_f32 v[136:137], v[22:23], v[152:153], v[142:143] op_sel_hi:[1,0,1]
	v_pk_fma_f32 v[138:139], v[24:25], v[152:153], v[144:145] op_sel_hi:[1,0,1]
	v_pk_fma_f32 v[140:141], v[26:27], v[152:153], v[146:147] op_sel_hi:[1,0,1]
	v_pk_fma_f32 v[142:143], v[28:29], v[152:153], v[148:149] op_sel_hi:[1,0,1]
	v_pk_fma_f32 v[144:145], v[30:31], v[152:153], v[150:151] op_sel_hi:[1,0,1]
	v_cndmask_b32_e64 v146, v0, v1, s[0:1]
	s_waitcnt vmcnt(1)
	v_cvt_scalef32_pk32_f32_fp6 v[0:31], v[38:43], 1.0
	v_readlane_b32 s12, v106, 39
	v_readlane_b32 s13, v109, 39
	v_pk_fma_f32 v[38:39], v[0:1], v[146:147], v[44:45] op_sel_hi:[1,0,1]
	v_mov_b32_e32 v1, s12
	v_mov_b32_e32 v0, s13
	v_readlane_b32 s12, v108, 40
	v_readlane_b32 s13, v107, 40
	v_pk_fma_f32 v[40:41], v[2:3], v[146:147], v[46:47] op_sel_hi:[1,0,1]
	v_pk_fma_f32 v[42:43], v[4:5], v[146:147], v[48:49] op_sel_hi:[1,0,1]
	v_pk_fma_f32 v[44:45], v[6:7], v[146:147], v[50:51] op_sel_hi:[1,0,1]
	v_pk_fma_f32 v[46:47], v[8:9], v[146:147], v[52:53] op_sel_hi:[1,0,1]
	v_pk_fma_f32 v[48:49], v[10:11], v[146:147], v[54:55] op_sel_hi:[1,0,1]
	v_pk_fma_f32 v[50:51], v[12:13], v[146:147], v[126:127] op_sel_hi:[1,0,1]
	v_pk_fma_f32 v[52:53], v[14:15], v[146:147], v[128:129] op_sel_hi:[1,0,1]
	v_pk_fma_f32 v[54:55], v[16:17], v[146:147], v[130:131] op_sel_hi:[1,0,1]
	v_pk_fma_f32 v[132:133], v[18:19], v[146:147], v[132:133] op_sel_hi:[1,0,1]
	v_pk_fma_f32 v[134:135], v[20:21], v[146:147], v[134:135] op_sel_hi:[1,0,1]
	v_pk_fma_f32 v[136:137], v[22:23], v[146:147], v[136:137] op_sel_hi:[1,0,1]
	v_pk_fma_f32 v[138:139], v[24:25], v[146:147], v[138:139] op_sel_hi:[1,0,1]
	v_pk_fma_f32 v[140:141], v[26:27], v[146:147], v[140:141] op_sel_hi:[1,0,1]
	v_pk_fma_f32 v[142:143], v[28:29], v[146:147], v[142:143] op_sel_hi:[1,0,1]
	v_pk_fma_f32 v[144:145], v[30:31], v[146:147], v[144:145] op_sel_hi:[1,0,1]
	v_cndmask_b32_e64 v146, v0, v1, s[0:1]
	v_mov_b32_e32 v0, s13
	v_mov_b32_e32 v1, s12
	v_cndmask_b32_e64 v0, v0, v1, s[0:1]
	v_mad_i64_i32 v[130:131], s[12:13], v0, s23, v[64:65]
	s_waitcnt vmcnt(0)
	v_cvt_scalef32_pk32_f32_fp6 v[0:31], v[32:37], 1.0
	v_readlane_b32 s12, v108, 41
	v_readlane_b32 s13, v107, 41
	v_pk_fma_f32 v[150:151], v[0:1], v[146:147], v[38:39] op_sel_hi:[1,0,1]
	v_mov_b32_e32 v1, s12
	v_mov_b32_e32 v0, s13
	v_cndmask_b32_e64 v0, v0, v1, s[0:1]
	v_mad_i64_i32 v[0:1], s[12:13], v0, s23, v[64:65]
	v_readlane_b32 s12, v108, 42
	v_readlane_b32 s13, v107, 42
	global_load_dwordx4 v[126:129], v[130:131], off
	v_pk_fma_f32 v[168:169], v[18:19], v[146:147], v[132:133] op_sel_hi:[1,0,1]
	global_load_dwordx2 v[130:131], v[130:131], off offset:16
	v_pk_fma_f32 v[170:171], v[20:21], v[146:147], v[134:135] op_sel_hi:[1,0,1]
	v_pk_fma_f32 v[172:173], v[22:23], v[146:147], v[136:137] op_sel_hi:[1,0,1]
	global_load_dwordx2 v[136:137], v[0:1], off offset:16
	global_load_dwordx4 v[132:135], v[0:1], off
	v_mov_b32_e32 v0, s13
	v_mov_b32_e32 v1, s12
	v_cndmask_b32_e64 v0, v0, v1, s[0:1]
	v_mad_i64_i32 v[0:1], s[12:13], v0, s23, v[64:65]
	v_readlane_b32 s12, v108, 43
	v_readlane_b32 s13, v107, 43
	v_pk_fma_f32 v[152:153], v[2:3], v[146:147], v[40:41] op_sel_hi:[1,0,1]
	v_mov_b32_e32 v3, s12
	v_mov_b32_e32 v2, s13
	v_cndmask_b32_e64 v2, v2, v3, s[0:1]
	v_mad_i64_i32 v[2:3], s[12:13], v2, s23, v[64:65]
	v_readlane_b32 s12, v108, 44
	v_readlane_b32 s13, v107, 44
	v_pk_fma_f32 v[154:155], v[4:5], v[146:147], v[42:43] op_sel_hi:[1,0,1]
	v_pk_fma_f32 v[156:157], v[6:7], v[146:147], v[44:45] op_sel_hi:[1,0,1]
	v_pk_fma_f32 v[158:159], v[8:9], v[146:147], v[46:47] op_sel_hi:[1,0,1]
	v_pk_fma_f32 v[160:161], v[10:11], v[146:147], v[48:49] op_sel_hi:[1,0,1]
	v_pk_fma_f32 v[162:163], v[12:13], v[146:147], v[50:51] op_sel_hi:[1,0,1]
	v_pk_fma_f32 v[164:165], v[14:15], v[146:147], v[52:53] op_sel_hi:[1,0,1]
	v_pk_fma_f32 v[166:167], v[16:17], v[146:147], v[54:55] op_sel_hi:[1,0,1]
	v_pk_fma_f32 v[174:175], v[24:25], v[146:147], v[138:139] op_sel_hi:[1,0,1]
	v_pk_fma_f32 v[176:177], v[26:27], v[146:147], v[140:141] op_sel_hi:[1,0,1]
	v_pk_fma_f32 v[178:179], v[28:29], v[146:147], v[142:143] op_sel_hi:[1,0,1]
	v_pk_fma_f32 v[180:181], v[30:31], v[146:147], v[144:145] op_sel_hi:[1,0,1]
	global_load_dwordx4 v[138:141], v[0:1], off
	global_load_dwordx2 v[142:143], v[0:1], off offset:16
	global_load_dwordx4 v[144:147], v[2:3], off
	v_mov_b32_e32 v0, s13
	v_mov_b32_e32 v1, s12
	v_cndmask_b32_e64 v0, v0, v1, s[0:1]
	v_mad_i64_i32 v[0:1], s[12:13], v0, s23, v[64:65]
	v_readlane_b32 s12, v108, 45
	v_readlane_b32 s13, v107, 45
	global_load_dwordx2 v[148:149], v[2:3], off offset:16
	global_load_dwordx4 v[50:53], v[0:1], off
	v_mov_b32_e32 v2, s13
	v_mov_b32_e32 v3, s12
	v_cndmask_b32_e64 v2, v2, v3, s[0:1]
	v_mad_i64_i32 v[2:3], s[12:13], v2, s23, v[64:65]
	v_readlane_b32 s12, v108, 46
	v_readlane_b32 s13, v107, 46
	global_load_dwordx2 v[54:55], v[0:1], off offset:16
	global_load_dwordx4 v[44:47], v[2:3], off
	v_mov_b32_e32 v0, s13
	v_mov_b32_e32 v1, s12
	v_cndmask_b32_e64 v0, v0, v1, s[0:1]
	v_mad_i64_i32 v[0:1], s[12:13], v0, s23, v[64:65]
	v_readlane_b32 s12, v108, 47
	v_readlane_b32 s13, v107, 47
	global_load_dwordx2 v[48:49], v[2:3], off offset:16
	global_load_dwordx4 v[38:41], v[0:1], off
	v_mov_b32_e32 v2, s13
	v_mov_b32_e32 v3, s12
	v_cndmask_b32_e64 v2, v2, v3, s[0:1]
	v_mad_i64_i32 v[2:3], s[12:13], v2, s23, v[64:65]
	global_load_dwordx2 v[36:37], v[2:3], off offset:16
	global_load_dwordx2 v[42:43], v[0:1], off offset:16
	global_load_dwordx4 v[32:35], v[2:3], off
	v_readlane_b32 s12, v106, 40
	v_readlane_b32 s13, v109, 40
	s_nop 0
	v_mov_b32_e32 v1, s12
	v_mov_b32_e32 v0, s13
	v_cndmask_b32_e64 v182, v0, v1, s[0:1]
	v_readlane_b32 s12, v106, 41
	v_readlane_b32 s13, v109, 41
	s_waitcnt vmcnt(14)
; DI void phase_peer_out(const Params& p, char* lds) {
;     ...
; #pragma unroll
;     for (int kb = 0; kb < 8; ++kb) {
;       v6u qb[8];
; #pragma unroll
;       for (int k = 0; k < 8; ++k) {
;         const int e0 = __builtin_amdgcn_readlane(el[0], kb * 8 + k), e1 = __builtin_amdgcn_readlane(el[1], kb * 8 + k);
;         qb[k] = load6(V6 + (size_t)(hb ? e1 : e0) * 768);
;       }
; #pragma unroll
;       for (int k = 0; k < 8; ++k) {
;         const float c0 = __uint_as_float(__builtin_amdgcn_readlane(__float_as_uint(coefv[0]), kb * 8 + k)), c1 = __uint_as_float(__builtin_amdgcn_readlane(__float_as_uint(coefv[1]), kb * 8 + k));
;         const float cf = hb ? c1 : c0;
;         const f32x2 c2 = {cf, cf};
;         const v32f f = __builtin_amdgcn_cvt_scalef32_pk32_f32_fp6(qb[k], 1.0f);
; #pragma unroll
;         for (int i = 0; i < 16; ++i) o2[i] = f32x2{f[2 * i], f[2 * i + 1]} * c2 + o2[i];
;       }
;     }
	v_cvt_scalef32_pk32_f32_fp6 v[0:31], v[126:131], 1.0
	v_pk_fma_f32 v[126:127], v[0:1], v[182:183], v[150:151] op_sel_hi:[1,0,1]
	v_mov_b32_e32 v0, s13
	v_mov_b32_e32 v1, s12
	v_pk_fma_f32 v[128:129], v[2:3], v[182:183], v[152:153] op_sel_hi:[1,0,1]
	v_pk_fma_f32 v[130:131], v[4:5], v[182:183], v[154:155] op_sel_hi:[1,0,1]
	v_pk_fma_f32 v[150:151], v[6:7], v[182:183], v[156:157] op_sel_hi:[1,0,1]
	v_pk_fma_f32 v[152:153], v[8:9], v[182:183], v[158:159] op_sel_hi:[1,0,1]
	v_pk_fma_f32 v[154:155], v[10:11], v[182:183], v[160:161] op_sel_hi:[1,0,1]
	v_pk_fma_f32 v[156:157], v[12:13], v[182:183], v[162:163] op_sel_hi:[1,0,1]
	v_pk_fma_f32 v[158:159], v[14:15], v[182:183], v[164:165] op_sel_hi:[1,0,1]
	v_pk_fma_f32 v[160:161], v[16:17], v[182:183], v[166:167] op_sel_hi:[1,0,1]
	v_pk_fma_f32 v[162:163], v[18:19], v[182:183], v[168:169] op_sel_hi:[1,0,1]
	v_pk_fma_f32 v[164:165], v[20:21], v[182:183], v[170:171] op_sel_hi:[1,0,1]
	v_pk_fma_f32 v[166:167], v[22:23], v[182:183], v[172:173] op_sel_hi:[1,0,1]
	v_pk_fma_f32 v[168:169], v[24:25], v[182:183], v[174:175] op_sel_hi:[1,0,1]
	v_pk_fma_f32 v[170:171], v[26:27], v[182:183], v[176:177] op_sel_hi:[1,0,1]
	v_pk_fma_f32 v[172:173], v[28:29], v[182:183], v[178:179] op_sel_hi:[1,0,1]
	v_pk_fma_f32 v[174:175], v[30:31], v[182:183], v[180:181] op_sel_hi:[1,0,1]
	v_cndmask_b32_e64 v176, v0, v1, s[0:1]
	s_waitcnt vmcnt(12)
	v_cvt_scalef32_pk32_f32_fp6 v[0:31], v[132:137], 1.0
	v_readlane_b32 s12, v106, 42
	v_readlane_b32 s13, v109, 42
	v_pk_fma_f32 v[126:127], v[0:1], v[176:177], v[126:127] op_sel_hi:[1,0,1]
	v_mov_b32_e32 v1, s12
	v_mov_b32_e32 v0, s13
	v_pk_fma_f32 v[128:129], v[2:3], v[176:177], v[128:129] op_sel_hi:[1,0,1]
	v_pk_fma_f32 v[130:131], v[4:5], v[176:177], v[130:131] op_sel_hi:[1,0,1]
	v_pk_fma_f32 v[132:133], v[6:7], v[176:177], v[150:151] op_sel_hi:[1,0,1]
	v_pk_fma_f32 v[134:135], v[8:9], v[176:177], v[152:153] op_sel_hi:[1,0,1]
	v_pk_fma_f32 v[136:137], v[10:11], v[176:177], v[154:155] op_sel_hi:[1,0,1]
	v_pk_fma_f32 v[150:151], v[12:13], v[176:177], v[156:157] op_sel_hi:[1,0,1]
	v_pk_fma_f32 v[152:153], v[14:15], v[176:177], v[158:159] op_sel_hi:[1,0,1]
	v_pk_fma_f32 v[154:155], v[16:17], v[176:177], v[160:161] op_sel_hi:[1,0,1]
	v_pk_fma_f32 v[156:157], v[18:19], v[176:177], v[162:163] op_sel_hi:[1,0,1]
	v_pk_fma_f32 v[158:159], v[20:21], v[176:177], v[164:165] op_sel_hi:[1,0,1]
	v_pk_fma_f32 v[160:161], v[22:23], v[176:177], v[166:167] op_sel_hi:[1,0,1]
	v_pk_fma_f32 v[162:163], v[24:25], v[176:177], v[168:169] op_sel_hi:[1,0,1]
	v_pk_fma_f32 v[164:165], v[26:27], v[176:177], v[170:171] op_sel_hi:[1,0,1]
	v_pk_fma_f32 v[166:167], v[28:29], v[176:177], v[172:173] op_sel_hi:[1,0,1]
	v_pk_fma_f32 v[168:169], v[30:31], v[176:177], v[174:175] op_sel_hi:[1,0,1]
	v_cndmask_b32_e64 v170, v0, v1, s[0:1]
	s_waitcnt vmcnt(10)
	v_cvt_scalef32_pk32_f32_fp6 v[0:31], v[138:143], 1.0
	v_readlane_b32 s12, v106, 43
	v_readlane_b32 s13, v109, 43
	v_pk_fma_f32 v[126:127], v[0:1], v[170:171], v[126:127] op_sel_hi:[1,0,1]
	v_mov_b32_e32 v1, s12
	v_mov_b32_e32 v0, s13
	v_pk_fma_f32 v[128:129], v[2:3], v[170:171], v[128:129] op_sel_hi:[1,0,1]
	v_pk_fma_f32 v[130:131], v[4:5], v[170:171], v[130:131] op_sel_hi:[1,0,1]
	v_pk_fma_f32 v[132:133], v[6:7], v[170:171], v[132:133] op_sel_hi:[1,0,1]
	v_pk_fma_f32 v[134:135], v[8:9], v[170:171], v[134:135] op_sel_hi:[1,0,1]
	v_pk_fma_f32 v[136:137], v[10:11], v[170:171], v[136:137] op_sel_hi:[1,0,1]
	v_pk_fma_f32 v[138:139], v[12:13], v[170:171], v[150:151] op_sel_hi:[1,0,1]
	v_pk_fma_f32 v[140:141], v[14:15], v[170:171], v[152:153] op_sel_hi:[1,0,1]
	v_pk_fma_f32 v[142:143], v[16:17], v[170:171], v[154:155] op_sel_hi:[1,0,1]
	v_pk_fma_f32 v[150:151], v[18:19], v[170:171], v[156:157] op_sel_hi:[1,0,1]
	v_pk_fma_f32 v[152:153], v[20:21], v[170:171], v[158:159] op_sel_hi:[1,0,1]
	v_pk_fma_f32 v[154:155], v[22:23], v[170:171], v[160:161] op_sel_hi:[1,0,1]
	v_pk_fma_f32 v[156:157], v[24:25], v[170:171], v[162:163] op_sel_hi:[1,0,1]
	v_pk_fma_f32 v[158:159], v[26:27], v[170:171], v[164:165] op_sel_hi:[1,0,1]
	v_pk_fma_f32 v[160:161], v[28:29], v[170:171], v[166:167] op_sel_hi:[1,0,1]
	v_pk_fma_f32 v[162:163], v[30:31], v[170:171], v[168:169] op_sel_hi:[1,0,1]
	v_cndmask_b32_e64 v164, v0, v1, s[0:1]
	s_waitcnt vmcnt(8)
	v_cvt_scalef32_pk32_f32_fp6 v[0:31], v[144:149], 1.0
	v_readlane_b32 s12, v106, 44
	v_readlane_b32 s13, v109, 44
	v_pk_fma_f32 v[126:127], v[0:1], v[164:165], v[126:127] op_sel_hi:[1,0,1]
	v_mov_b32_e32 v1, s12
	v_mov_b32_e32 v0, s13
	v_pk_fma_f32 v[128:129], v[2:3], v[164:165], v[128:129] op_sel_hi:[1,0,1]
	v_pk_fma_f32 v[130:131], v[4:5], v[164:165], v[130:131] op_sel_hi:[1,0,1]
	v_pk_fma_f32 v[132:133], v[6:7], v[164:165], v[132:133] op_sel_hi:[1,0,1]
	v_pk_fma_f32 v[134:135], v[8:9], v[164:165], v[134:135] op_sel_hi:[1,0,1]
	v_pk_fma_f32 v[136:137], v[10:11], v[164:165], v[136:137] op_sel_hi:[1,0,1]
	v_pk_fma_f32 v[138:139], v[12:13], v[164:165], v[138:139] op_sel_hi:[1,0,1]
	v_pk_fma_f32 v[140:141], v[14:15], v[164:165], v[140:141] op_sel_hi:[1,0,1]
	v_pk_fma_f32 v[142:143], v[16:17], v[164:165], v[142:143] op_sel_hi:[1,0,1]
	v_pk_fma_f32 v[144:145], v[18:19], v[164:165], v[150:151] op_sel_hi:[1,0,1]
	v_pk_fma_f32 v[146:147], v[20:21], v[164:165], v[152:153] op_sel_hi:[1,0,1]
	v_pk_fma_f32 v[148:149], v[22:23], v[164:165], v[154:155] op_sel_hi:[1,0,1]
	v_pk_fma_f32 v[150:151], v[24:25], v[164:165], v[156:157] op_sel_hi:[1,0,1]
	v_pk_fma_f32 v[152:153], v[26:27], v[164:165], v[158:159] op_sel_hi:[1,0,1]
	v_pk_fma_f32 v[154:155], v[28:29], v[164:165], v[160:161] op_sel_hi:[1,0,1]
	v_pk_fma_f32 v[156:157], v[30:31], v[164:165], v[162:163] op_sel_hi:[1,0,1]
	v_cndmask_b32_e64 v158, v0, v1, s[0:1]
	s_waitcnt vmcnt(6)
; DI void phase_peer_out(const Params& p, char* lds) {
;     ...
;     for (int kb = 0; kb < 8; ++kb) {
;       v6u qb[8];
; #pragma unroll
;       for (int k = 0; k < 8; ++k) {
;         const int e0 = __builtin_amdgcn_readlane(el[0], kb * 8 + k), e1 = __builtin_amdgcn_readlane(el[1], kb * 8 + k);
;         qb[k] = load6(V6 + (size_t)(hb ? e1 : e0) * 768);
;       }
; #pragma unroll
;       for (int k = 0; k < 8; ++k) {
;         const float c0 = __uint_as_float(__builtin_amdgcn_readlane(__float_as_uint(coefv[0]), kb * 8 + k)), c1 = __uint_as_float(__builtin_amdgcn_readlane(__float_as_uint(coefv[1]), kb * 8 + k));
;         const float cf = hb ? c1 : c0;
;         const f32x2 c2 = {cf, cf};
;         const v32f f = __builtin_amdgcn_cvt_scalef32_pk32_f32_fp6(qb[k], 1.0f);
; #pragma unroll
;         for (int i = 0; i < 16; ++i) o2[i] = f32x2{f[2 * i], f[2 * i + 1]} * c2 + o2[i];
;       }
;     }
	v_cvt_scalef32_pk32_f32_fp6 v[0:31], v[50:55], 1.0
	v_readlane_b32 s12, v106, 45
	v_readlane_b32 s13, v109, 45
	v_pk_fma_f32 v[50:51], v[0:1], v[158:159], v[126:127] op_sel_hi:[1,0,1]
	v_mov_b32_e32 v1, s12
	v_mov_b32_e32 v0, s13
	v_pk_fma_f32 v[52:53], v[2:3], v[158:159], v[128:129] op_sel_hi:[1,0,1]
	v_pk_fma_f32 v[54:55], v[4:5], v[158:159], v[130:131] op_sel_hi:[1,0,1]
	v_pk_fma_f32 v[126:127], v[6:7], v[158:159], v[132:133] op_sel_hi:[1,0,1]
	v_pk_fma_f32 v[128:129], v[8:9], v[158:159], v[134:135] op_sel_hi:[1,0,1]
	v_pk_fma_f32 v[130:131], v[10:11], v[158:159], v[136:137] op_sel_hi:[1,0,1]
	v_pk_fma_f32 v[132:133], v[12:13], v[158:159], v[138:139] op_sel_hi:[1,0,1]
	v_pk_fma_f32 v[134:135], v[14:15], v[158:159], v[140:141] op_sel_hi:[1,0,1]
	v_pk_fma_f32 v[136:137], v[16:17], v[158:159], v[142:143] op_sel_hi:[1,0,1]
	v_pk_fma_f32 v[138:139], v[18:19], v[158:159], v[144:145] op_sel_hi:[1,0,1]
	v_pk_fma_f32 v[140:141], v[20:21], v[158:159], v[146:147] op_sel_hi:[1,0,1]
	v_pk_fma_f32 v[142:143], v[22:23], v[158:159], v[148:149] op_sel_hi:[1,0,1]
	v_pk_fma_f32 v[144:145], v[24:25], v[158:159], v[150:151] op_sel_hi:[1,0,1]
	v_pk_fma_f32 v[146:147], v[26:27], v[158:159], v[152:153] op_sel_hi:[1,0,1]
	v_pk_fma_f32 v[148:149], v[28:29], v[158:159], v[154:155] op_sel_hi:[1,0,1]
	v_pk_fma_f32 v[150:151], v[30:31], v[158:159], v[156:157] op_sel_hi:[1,0,1]
	v_cndmask_b32_e64 v152, v0, v1, s[0:1]
	s_waitcnt vmcnt(4)
	v_cvt_scalef32_pk32_f32_fp6 v[0:31], v[44:49], 1.0
	v_readlane_b32 s12, v106, 46
	v_readlane_b32 s13, v109, 46
	v_pk_fma_f32 v[44:45], v[0:1], v[152:153], v[50:51] op_sel_hi:[1,0,1]
	v_mov_b32_e32 v1, s12
	v_mov_b32_e32 v0, s13
	v_pk_fma_f32 v[46:47], v[2:3], v[152:153], v[52:53] op_sel_hi:[1,0,1]
	v_pk_fma_f32 v[48:49], v[4:5], v[152:153], v[54:55] op_sel_hi:[1,0,1]
	v_pk_fma_f32 v[50:51], v[6:7], v[152:153], v[126:127] op_sel_hi:[1,0,1]
	v_pk_fma_f32 v[52:53], v[8:9], v[152:153], v[128:129] op_sel_hi:[1,0,1]
	v_pk_fma_f32 v[54:55], v[10:11], v[152:153], v[130:131] op_sel_hi:[1,0,1]
	v_pk_fma_f32 v[126:127], v[12:13], v[152:153], v[132:133] op_sel_hi:[1,0,1]
	v_pk_fma_f32 v[128:129], v[14:15], v[152:153], v[134:135] op_sel_hi:[1,0,1]
	v_pk_fma_f32 v[130:131], v[16:17], v[152:153], v[136:137] op_sel_hi:[1,0,1]
	v_pk_fma_f32 v[132:133], v[18:19], v[152:153], v[138:139] op_sel_hi:[1,0,1]
	v_pk_fma_f32 v[134:135], v[20:21], v[152:153], v[140:141] op_sel_hi:[1,0,1]
	v_pk_fma_f32 v[136:137], v[22:23], v[152:153], v[142:143] op_sel_hi:[1,0,1]
	v_pk_fma_f32 v[138:139], v[24:25], v[152:153], v[144:145] op_sel_hi:[1,0,1]
	v_pk_fma_f32 v[140:141], v[26:27], v[152:153], v[146:147] op_sel_hi:[1,0,1]
	v_pk_fma_f32 v[142:143], v[28:29], v[152:153], v[148:149] op_sel_hi:[1,0,1]
	v_pk_fma_f32 v[144:145], v[30:31], v[152:153], v[150:151] op_sel_hi:[1,0,1]
	v_cndmask_b32_e64 v146, v0, v1, s[0:1]
	s_waitcnt vmcnt(1)
	v_cvt_scalef32_pk32_f32_fp6 v[0:31], v[38:43], 1.0
	v_readlane_b32 s12, v106, 47
	v_readlane_b32 s13, v109, 47
	v_pk_fma_f32 v[38:39], v[0:1], v[146:147], v[44:45] op_sel_hi:[1,0,1]
	v_mov_b32_e32 v1, s12
	v_mov_b32_e32 v0, s13
	v_readlane_b32 s12, v108, 48
	v_readlane_b32 s13, v107, 48
	v_pk_fma_f32 v[40:41], v[2:3], v[146:147], v[46:47] op_sel_hi:[1,0,1]
	v_pk_fma_f32 v[42:43], v[4:5], v[146:147], v[48:49] op_sel_hi:[1,0,1]
	v_pk_fma_f32 v[44:45], v[6:7], v[146:147], v[50:51] op_sel_hi:[1,0,1]
	v_pk_fma_f32 v[46:47], v[8:9], v[146:147], v[52:53] op_sel_hi:[1,0,1]
	v_pk_fma_f32 v[48:49], v[10:11], v[146:147], v[54:55] op_sel_hi:[1,0,1]
	v_pk_fma_f32 v[50:51], v[12:13], v[146:147], v[126:127] op_sel_hi:[1,0,1]
	v_pk_fma_f32 v[52:53], v[14:15], v[146:147], v[128:129] op_sel_hi:[1,0,1]
	v_pk_fma_f32 v[54:55], v[16:17], v[146:147], v[130:131] op_sel_hi:[1,0,1]
	v_pk_fma_f32 v[132:133], v[18:19], v[146:147], v[132:133] op_sel_hi:[1,0,1]
	v_pk_fma_f32 v[134:135], v[20:21], v[146:147], v[134:135] op_sel_hi:[1,0,1]
	v_pk_fma_f32 v[136:137], v[22:23], v[146:147], v[136:137] op_sel_hi:[1,0,1]
	v_pk_fma_f32 v[138:139], v[24:25], v[146:147], v[138:139] op_sel_hi:[1,0,1]
	v_pk_fma_f32 v[140:141], v[26:27], v[146:147], v[140:141] op_sel_hi:[1,0,1]
	v_pk_fma_f32 v[142:143], v[28:29], v[146:147], v[142:143] op_sel_hi:[1,0,1]
	v_pk_fma_f32 v[144:145], v[30:31], v[146:147], v[144:145] op_sel_hi:[1,0,1]
	v_cndmask_b32_e64 v146, v0, v1, s[0:1]
	v_mov_b32_e32 v0, s13
	v_mov_b32_e32 v1, s12
	v_cndmask_b32_e64 v0, v0, v1, s[0:1]
	v_mad_i64_i32 v[130:131], s[12:13], v0, s23, v[64:65]
	s_waitcnt vmcnt(0)
; DI void phase_peer_out(const Params& p, char* lds) {
;     ...
;     for (int kb = 0; kb < 8; ++kb) {
;       v6u qb[8];
; #pragma unroll
;       for (int k = 0; k < 8; ++k) {
;         const int e0 = __builtin_amdgcn_readlane(el[0], kb * 8 + k), e1 = __builtin_amdgcn_readlane(el[1], kb * 8 + k);
;         qb[k] = load6(V6 + (size_t)(hb ? e1 : e0) * 768);
;       }
; #pragma unroll
;       for (int k = 0; k < 8; ++k) {
;         const float c0 = __uint_as_float(__builtin_amdgcn_readlane(__float_as_uint(coefv[0]), kb * 8 + k)), c1 = __uint_as_float(__builtin_amdgcn_readlane(__float_as_uint(coefv[1]), kb * 8 + k));
;         const float cf = hb ? c1 : c0;
;         const f32x2 c2 = {cf, cf};
;         const v32f f = __builtin_amdgcn_cvt_scalef32_pk32_f32_fp6(qb[k], 1.0f);
; #pragma unroll
;         for (int i = 0; i < 16; ++i) o2[i] = f32x2{f[2 * i], f[2 * i + 1]} * c2 + o2[i];
;       }
;     }
	v_cvt_scalef32_pk32_f32_fp6 v[0:31], v[32:37], 1.0
	v_readlane_b32 s12, v108, 49
	v_readlane_b32 s13, v107, 49
	v_pk_fma_f32 v[150:151], v[0:1], v[146:147], v[38:39] op_sel_hi:[1,0,1]
	v_mov_b32_e32 v1, s12
	v_mov_b32_e32 v0, s13
	v_cndmask_b32_e64 v0, v0, v1, s[0:1]
	v_mad_i64_i32 v[0:1], s[12:13], v0, s23, v[64:65]
	v_readlane_b32 s12, v108, 50
	v_readlane_b32 s13, v107, 50
	global_load_dwordx4 v[126:129], v[130:131], off
	v_pk_fma_f32 v[168:169], v[18:19], v[146:147], v[132:133] op_sel_hi:[1,0,1]
	global_load_dwordx2 v[130:131], v[130:131], off offset:16
	v_pk_fma_f32 v[170:171], v[20:21], v[146:147], v[134:135] op_sel_hi:[1,0,1]
	v_pk_fma_f32 v[172:173], v[22:23], v[146:147], v[136:137] op_sel_hi:[1,0,1]
	global_load_dwordx2 v[136:137], v[0:1], off offset:16
	global_load_dwordx4 v[132:135], v[0:1], off
	v_mov_b32_e32 v0, s13
	v_mov_b32_e32 v1, s12
	v_cndmask_b32_e64 v0, v0, v1, s[0:1]
	v_mad_i64_i32 v[0:1], s[12:13], v0, s23, v[64:65]
	v_readlane_b32 s12, v108, 51
	v_readlane_b32 s13, v107, 51
	v_pk_fma_f32 v[152:153], v[2:3], v[146:147], v[40:41] op_sel_hi:[1,0,1]
	v_mov_b32_e32 v3, s12
	v_mov_b32_e32 v2, s13
	v_cndmask_b32_e64 v2, v2, v3, s[0:1]
	v_mad_i64_i32 v[2:3], s[12:13], v2, s23, v[64:65]
	v_readlane_b32 s12, v108, 52
	v_readlane_b32 s13, v107, 52
	v_pk_fma_f32 v[154:155], v[4:5], v[146:147], v[42:43] op_sel_hi:[1,0,1]
	v_pk_fma_f32 v[156:157], v[6:7], v[146:147], v[44:45] op_sel_hi:[1,0,1]
	v_pk_fma_f32 v[158:159], v[8:9], v[146:147], v[46:47] op_sel_hi:[1,0,1]
	v_pk_fma_f32 v[160:161], v[10:11], v[146:147], v[48:49] op_sel_hi:[1,0,1]
	v_pk_fma_f32 v[162:163], v[12:13], v[146:147], v[50:51] op_sel_hi:[1,0,1]
	v_pk_fma_f32 v[164:165], v[14:15], v[146:147], v[52:53] op_sel_hi:[1,0,1]
	v_pk_fma_f32 v[166:167], v[16:17], v[146:147], v[54:55] op_sel_hi:[1,0,1]
	v_pk_fma_f32 v[174:175], v[24:25], v[146:147], v[138:139] op_sel_hi:[1,0,1]
	v_pk_fma_f32 v[176:177], v[26:27], v[146:147], v[140:141] op_sel_hi:[1,0,1]
	v_pk_fma_f32 v[178:179], v[28:29], v[146:147], v[142:143] op_sel_hi:[1,0,1]
	v_pk_fma_f32 v[180:181], v[30:31], v[146:147], v[144:145] op_sel_hi:[1,0,1]
	global_load_dwordx4 v[138:141], v[0:1], off
	global_load_dwordx2 v[142:143], v[0:1], off offset:16
	global_load_dwordx4 v[144:147], v[2:3], off
	v_mov_b32_e32 v0, s13
	v_mov_b32_e32 v1, s12
	v_cndmask_b32_e64 v0, v0, v1, s[0:1]
	v_mad_i64_i32 v[0:1], s[12:13], v0, s23, v[64:65]
	v_readlane_b32 s12, v108, 53
	v_readlane_b32 s13, v107, 53
	global_load_dwordx2 v[148:149], v[2:3], off offset:16
	global_load_dwordx4 v[50:53], v[0:1], off
	v_mov_b32_e32 v2, s13
	v_mov_b32_e32 v3, s12
	v_cndmask_b32_e64 v2, v2, v3, s[0:1]
	v_mad_i64_i32 v[2:3], s[12:13], v2, s23, v[64:65]
	v_readlane_b32 s12, v108, 54
	v_readlane_b32 s13, v107, 54
	global_load_dwordx2 v[54:55], v[0:1], off offset:16
	global_load_dwordx4 v[44:47], v[2:3], off
	v_mov_b32_e32 v0, s13
	v_mov_b32_e32 v1, s12
	v_cndmask_b32_e64 v0, v0, v1, s[0:1]
	v_mad_i64_i32 v[0:1], s[12:13], v0, s23, v[64:65]
	v_readlane_b32 s12, v108, 55
	v_readlane_b32 s13, v107, 55
	global_load_dwordx2 v[48:49], v[2:3], off offset:16
	global_load_dwordx4 v[38:41], v[0:1], off
	v_mov_b32_e32 v2, s13
	v_mov_b32_e32 v3, s12
	v_cndmask_b32_e64 v2, v2, v3, s[0:1]
	v_mad_i64_i32 v[2:3], s[12:13], v2, s23, v[64:65]
	global_load_dwordx2 v[36:37], v[2:3], off offset:16
	global_load_dwordx2 v[42:43], v[0:1], off offset:16
	global_load_dwordx4 v[32:35], v[2:3], off
	v_readlane_b32 s12, v106, 48
	v_readlane_b32 s13, v109, 48
	s_nop 0
	v_mov_b32_e32 v1, s12
	v_mov_b32_e32 v0, s13
	v_cndmask_b32_e64 v182, v0, v1, s[0:1]
	v_readlane_b32 s12, v106, 49
	v_readlane_b32 s13, v109, 49
	s_waitcnt vmcnt(14)
	v_cvt_scalef32_pk32_f32_fp6 v[0:31], v[126:131], 1.0
	v_pk_fma_f32 v[126:127], v[0:1], v[182:183], v[150:151] op_sel_hi:[1,0,1]
	v_mov_b32_e32 v0, s13
	v_mov_b32_e32 v1, s12
	v_pk_fma_f32 v[128:129], v[2:3], v[182:183], v[152:153] op_sel_hi:[1,0,1]
	v_pk_fma_f32 v[130:131], v[4:5], v[182:183], v[154:155] op_sel_hi:[1,0,1]
	v_pk_fma_f32 v[150:151], v[6:7], v[182:183], v[156:157] op_sel_hi:[1,0,1]
	v_pk_fma_f32 v[152:153], v[8:9], v[182:183], v[158:159] op_sel_hi:[1,0,1]
	v_pk_fma_f32 v[154:155], v[10:11], v[182:183], v[160:161] op_sel_hi:[1,0,1]
	v_pk_fma_f32 v[156:157], v[12:13], v[182:183], v[162:163] op_sel_hi:[1,0,1]
	v_pk_fma_f32 v[158:159], v[14:15], v[182:183], v[164:165] op_sel_hi:[1,0,1]
	v_pk_fma_f32 v[160:161], v[16:17], v[182:183], v[166:167] op_sel_hi:[1,0,1]
	v_pk_fma_f32 v[162:163], v[18:19], v[182:183], v[168:169] op_sel_hi:[1,0,1]
	v_pk_fma_f32 v[164:165], v[20:21], v[182:183], v[170:171] op_sel_hi:[1,0,1]
	v_pk_fma_f32 v[166:167], v[22:23], v[182:183], v[172:173] op_sel_hi:[1,0,1]
	v_pk_fma_f32 v[168:169], v[24:25], v[182:183], v[174:175] op_sel_hi:[1,0,1]
	v_pk_fma_f32 v[170:171], v[26:27], v[182:183], v[176:177] op_sel_hi:[1,0,1]
	v_pk_fma_f32 v[172:173], v[28:29], v[182:183], v[178:179] op_sel_hi:[1,0,1]
	v_pk_fma_f32 v[174:175], v[30:31], v[182:183], v[180:181] op_sel_hi:[1,0,1]
	v_cndmask_b32_e64 v176, v0, v1, s[0:1]
	s_waitcnt vmcnt(12)
; DI void phase_peer_out(const Params& p, char* lds) {
;     ...
;     for (int kb = 0; kb < 8; ++kb) {
;       v6u qb[8];
; #pragma unroll
;       for (int k = 0; k < 8; ++k) {
;         const int e0 = __builtin_amdgcn_readlane(el[0], kb * 8 + k), e1 = __builtin_amdgcn_readlane(el[1], kb * 8 + k);
;         qb[k] = load6(V6 + (size_t)(hb ? e1 : e0) * 768);
;       }
; #pragma unroll
;       for (int k = 0; k < 8; ++k) {
;         const float c0 = __uint_as_float(__builtin_amdgcn_readlane(__float_as_uint(coefv[0]), kb * 8 + k)), c1 = __uint_as_float(__builtin_amdgcn_readlane(__float_as_uint(coefv[1]), kb * 8 + k));
;         const float cf = hb ? c1 : c0;
;         const f32x2 c2 = {cf, cf};
;         const v32f f = __builtin_amdgcn_cvt_scalef32_pk32_f32_fp6(qb[k], 1.0f);
; #pragma unroll
;         for (int i = 0; i < 16; ++i) o2[i] = f32x2{f[2 * i], f[2 * i + 1]} * c2 + o2[i];
;       }
;     }
	v_cvt_scalef32_pk32_f32_fp6 v[0:31], v[132:137], 1.0
	v_readlane_b32 s12, v106, 50
	v_readlane_b32 s13, v109, 50
	v_pk_fma_f32 v[126:127], v[0:1], v[176:177], v[126:127] op_sel_hi:[1,0,1]
	v_mov_b32_e32 v1, s12
	v_mov_b32_e32 v0, s13
	v_pk_fma_f32 v[128:129], v[2:3], v[176:177], v[128:129] op_sel_hi:[1,0,1]
	v_pk_fma_f32 v[130:131], v[4:5], v[176:177], v[130:131] op_sel_hi:[1,0,1]
	v_pk_fma_f32 v[132:133], v[6:7], v[176:177], v[150:151] op_sel_hi:[1,0,1]
	v_pk_fma_f32 v[134:135], v[8:9], v[176:177], v[152:153] op_sel_hi:[1,0,1]
	v_pk_fma_f32 v[136:137], v[10:11], v[176:177], v[154:155] op_sel_hi:[1,0,1]
	v_pk_fma_f32 v[150:151], v[12:13], v[176:177], v[156:157] op_sel_hi:[1,0,1]
	v_pk_fma_f32 v[152:153], v[14:15], v[176:177], v[158:159] op_sel_hi:[1,0,1]
	v_pk_fma_f32 v[154:155], v[16:17], v[176:177], v[160:161] op_sel_hi:[1,0,1]
	v_pk_fma_f32 v[156:157], v[18:19], v[176:177], v[162:163] op_sel_hi:[1,0,1]
	v_pk_fma_f32 v[158:159], v[20:21], v[176:177], v[164:165] op_sel_hi:[1,0,1]
	v_pk_fma_f32 v[160:161], v[22:23], v[176:177], v[166:167] op_sel_hi:[1,0,1]
	v_pk_fma_f32 v[162:163], v[24:25], v[176:177], v[168:169] op_sel_hi:[1,0,1]
	v_pk_fma_f32 v[164:165], v[26:27], v[176:177], v[170:171] op_sel_hi:[1,0,1]
	v_pk_fma_f32 v[166:167], v[28:29], v[176:177], v[172:173] op_sel_hi:[1,0,1]
	v_pk_fma_f32 v[168:169], v[30:31], v[176:177], v[174:175] op_sel_hi:[1,0,1]
	v_cndmask_b32_e64 v170, v0, v1, s[0:1]
	s_waitcnt vmcnt(10)
	v_cvt_scalef32_pk32_f32_fp6 v[0:31], v[138:143], 1.0
	v_readlane_b32 s12, v106, 51
	v_readlane_b32 s13, v109, 51
	v_pk_fma_f32 v[126:127], v[0:1], v[170:171], v[126:127] op_sel_hi:[1,0,1]
	v_mov_b32_e32 v1, s12
	v_mov_b32_e32 v0, s13
	v_pk_fma_f32 v[128:129], v[2:3], v[170:171], v[128:129] op_sel_hi:[1,0,1]
	v_pk_fma_f32 v[130:131], v[4:5], v[170:171], v[130:131] op_sel_hi:[1,0,1]
	v_pk_fma_f32 v[132:133], v[6:7], v[170:171], v[132:133] op_sel_hi:[1,0,1]
	v_pk_fma_f32 v[134:135], v[8:9], v[170:171], v[134:135] op_sel_hi:[1,0,1]
	v_pk_fma_f32 v[136:137], v[10:11], v[170:171], v[136:137] op_sel_hi:[1,0,1]
	v_pk_fma_f32 v[138:139], v[12:13], v[170:171], v[150:151] op_sel_hi:[1,0,1]
	v_pk_fma_f32 v[140:141], v[14:15], v[170:171], v[152:153] op_sel_hi:[1,0,1]
	v_pk_fma_f32 v[142:143], v[16:17], v[170:171], v[154:155] op_sel_hi:[1,0,1]
	v_pk_fma_f32 v[150:151], v[18:19], v[170:171], v[156:157] op_sel_hi:[1,0,1]
	v_pk_fma_f32 v[152:153], v[20:21], v[170:171], v[158:159] op_sel_hi:[1,0,1]
	v_pk_fma_f32 v[154:155], v[22:23], v[170:171], v[160:161] op_sel_hi:[1,0,1]
	v_pk_fma_f32 v[156:157], v[24:25], v[170:171], v[162:163] op_sel_hi:[1,0,1]
	v_pk_fma_f32 v[158:159], v[26:27], v[170:171], v[164:165] op_sel_hi:[1,0,1]
	v_pk_fma_f32 v[160:161], v[28:29], v[170:171], v[166:167] op_sel_hi:[1,0,1]
	v_pk_fma_f32 v[162:163], v[30:31], v[170:171], v[168:169] op_sel_hi:[1,0,1]
	v_cndmask_b32_e64 v164, v0, v1, s[0:1]
	s_waitcnt vmcnt(8)
	v_cvt_scalef32_pk32_f32_fp6 v[0:31], v[144:149], 1.0
	v_readlane_b32 s12, v106, 52
	v_readlane_b32 s13, v109, 52
	v_pk_fma_f32 v[126:127], v[0:1], v[164:165], v[126:127] op_sel_hi:[1,0,1]
	v_mov_b32_e32 v1, s12
	v_mov_b32_e32 v0, s13
	v_pk_fma_f32 v[128:129], v[2:3], v[164:165], v[128:129] op_sel_hi:[1,0,1]
	v_pk_fma_f32 v[130:131], v[4:5], v[164:165], v[130:131] op_sel_hi:[1,0,1]
	v_pk_fma_f32 v[132:133], v[6:7], v[164:165], v[132:133] op_sel_hi:[1,0,1]
	v_pk_fma_f32 v[134:135], v[8:9], v[164:165], v[134:135] op_sel_hi:[1,0,1]
	v_pk_fma_f32 v[136:137], v[10:11], v[164:165], v[136:137] op_sel_hi:[1,0,1]
	v_pk_fma_f32 v[138:139], v[12:13], v[164:165], v[138:139] op_sel_hi:[1,0,1]
	v_pk_fma_f32 v[140:141], v[14:15], v[164:165], v[140:141] op_sel_hi:[1,0,1]
	v_pk_fma_f32 v[142:143], v[16:17], v[164:165], v[142:143] op_sel_hi:[1,0,1]
	v_pk_fma_f32 v[144:145], v[18:19], v[164:165], v[150:151] op_sel_hi:[1,0,1]
	v_pk_fma_f32 v[146:147], v[20:21], v[164:165], v[152:153] op_sel_hi:[1,0,1]
	v_pk_fma_f32 v[148:149], v[22:23], v[164:165], v[154:155] op_sel_hi:[1,0,1]
	v_pk_fma_f32 v[150:151], v[24:25], v[164:165], v[156:157] op_sel_hi:[1,0,1]
	v_pk_fma_f32 v[152:153], v[26:27], v[164:165], v[158:159] op_sel_hi:[1,0,1]
	v_pk_fma_f32 v[154:155], v[28:29], v[164:165], v[160:161] op_sel_hi:[1,0,1]
	v_pk_fma_f32 v[156:157], v[30:31], v[164:165], v[162:163] op_sel_hi:[1,0,1]
	v_cndmask_b32_e64 v158, v0, v1, s[0:1]
	s_waitcnt vmcnt(6)
	v_cvt_scalef32_pk32_f32_fp6 v[0:31], v[50:55], 1.0
	v_readlane_b32 s12, v106, 53
	v_readlane_b32 s13, v109, 53
	v_pk_fma_f32 v[50:51], v[0:1], v[158:159], v[126:127] op_sel_hi:[1,0,1]
	v_mov_b32_e32 v1, s12
	v_mov_b32_e32 v0, s13
	v_pk_fma_f32 v[52:53], v[2:3], v[158:159], v[128:129] op_sel_hi:[1,0,1]
	v_pk_fma_f32 v[54:55], v[4:5], v[158:159], v[130:131] op_sel_hi:[1,0,1]
	v_pk_fma_f32 v[126:127], v[6:7], v[158:159], v[132:133] op_sel_hi:[1,0,1]
	v_pk_fma_f32 v[128:129], v[8:9], v[158:159], v[134:135] op_sel_hi:[1,0,1]
	v_pk_fma_f32 v[130:131], v[10:11], v[158:159], v[136:137] op_sel_hi:[1,0,1]
	v_pk_fma_f32 v[132:133], v[12:13], v[158:159], v[138:139] op_sel_hi:[1,0,1]
	v_pk_fma_f32 v[134:135], v[14:15], v[158:159], v[140:141] op_sel_hi:[1,0,1]
	v_pk_fma_f32 v[136:137], v[16:17], v[158:159], v[142:143] op_sel_hi:[1,0,1]
	v_pk_fma_f32 v[138:139], v[18:19], v[158:159], v[144:145] op_sel_hi:[1,0,1]
	v_pk_fma_f32 v[140:141], v[20:21], v[158:159], v[146:147] op_sel_hi:[1,0,1]
	v_pk_fma_f32 v[142:143], v[22:23], v[158:159], v[148:149] op_sel_hi:[1,0,1]
	v_pk_fma_f32 v[144:145], v[24:25], v[158:159], v[150:151] op_sel_hi:[1,0,1]
	v_pk_fma_f32 v[146:147], v[26:27], v[158:159], v[152:153] op_sel_hi:[1,0,1]
	v_pk_fma_f32 v[148:149], v[28:29], v[158:159], v[154:155] op_sel_hi:[1,0,1]
	v_pk_fma_f32 v[150:151], v[30:31], v[158:159], v[156:157] op_sel_hi:[1,0,1]
	v_cndmask_b32_e64 v152, v0, v1, s[0:1]
	s_waitcnt vmcnt(4)
; DI void phase_peer_out(const Params& p, char* lds) {
;     ...
;     for (int kb = 0; kb < 8; ++kb) {
;       v6u qb[8];
; #pragma unroll
;       for (int k = 0; k < 8; ++k) {
;         const int e0 = __builtin_amdgcn_readlane(el[0], kb * 8 + k), e1 = __builtin_amdgcn_readlane(el[1], kb * 8 + k);
;         qb[k] = load6(V6 + (size_t)(hb ? e1 : e0) * 768);
;       }
; #pragma unroll
;       for (int k = 0; k < 8; ++k) {
;         const float c0 = __uint_as_float(__builtin_amdgcn_readlane(__float_as_uint(coefv[0]), kb * 8 + k)), c1 = __uint_as_float(__builtin_amdgcn_readlane(__float_as_uint(coefv[1]), kb * 8 + k));
;         const float cf = hb ? c1 : c0;
;         const f32x2 c2 = {cf, cf};
;         const v32f f = __builtin_amdgcn_cvt_scalef32_pk32_f32_fp6(qb[k], 1.0f);
; #pragma unroll
;         for (int i = 0; i < 16; ++i) o2[i] = f32x2{f[2 * i], f[2 * i + 1]} * c2 + o2[i];
;       }
;     }
	v_cvt_scalef32_pk32_f32_fp6 v[0:31], v[44:49], 1.0
	v_readlane_b32 s12, v106, 54
	v_readlane_b32 s13, v109, 54
	v_pk_fma_f32 v[44:45], v[0:1], v[152:153], v[50:51] op_sel_hi:[1,0,1]
	v_mov_b32_e32 v1, s12
	v_mov_b32_e32 v0, s13
	v_pk_fma_f32 v[46:47], v[2:3], v[152:153], v[52:53] op_sel_hi:[1,0,1]
	v_pk_fma_f32 v[48:49], v[4:5], v[152:153], v[54:55] op_sel_hi:[1,0,1]
	v_pk_fma_f32 v[50:51], v[6:7], v[152:153], v[126:127] op_sel_hi:[1,0,1]
	v_pk_fma_f32 v[52:53], v[8:9], v[152:153], v[128:129] op_sel_hi:[1,0,1]
	v_pk_fma_f32 v[54:55], v[10:11], v[152:153], v[130:131] op_sel_hi:[1,0,1]
	v_pk_fma_f32 v[126:127], v[12:13], v[152:153], v[132:133] op_sel_hi:[1,0,1]
	v_pk_fma_f32 v[128:129], v[14:15], v[152:153], v[134:135] op_sel_hi:[1,0,1]
	v_pk_fma_f32 v[130:131], v[16:17], v[152:153], v[136:137] op_sel_hi:[1,0,1]
	v_pk_fma_f32 v[132:133], v[18:19], v[152:153], v[138:139] op_sel_hi:[1,0,1]
	v_pk_fma_f32 v[134:135], v[20:21], v[152:153], v[140:141] op_sel_hi:[1,0,1]
	v_pk_fma_f32 v[136:137], v[22:23], v[152:153], v[142:143] op_sel_hi:[1,0,1]
	v_pk_fma_f32 v[138:139], v[24:25], v[152:153], v[144:145] op_sel_hi:[1,0,1]
	v_pk_fma_f32 v[140:141], v[26:27], v[152:153], v[146:147] op_sel_hi:[1,0,1]
	v_pk_fma_f32 v[142:143], v[28:29], v[152:153], v[148:149] op_sel_hi:[1,0,1]
	v_pk_fma_f32 v[144:145], v[30:31], v[152:153], v[150:151] op_sel_hi:[1,0,1]
	v_cndmask_b32_e64 v146, v0, v1, s[0:1]
	s_waitcnt vmcnt(1)
	v_cvt_scalef32_pk32_f32_fp6 v[0:31], v[38:43], 1.0
	v_readlane_b32 s12, v106, 55
	v_readlane_b32 s13, v109, 55
	v_pk_fma_f32 v[38:39], v[0:1], v[146:147], v[44:45] op_sel_hi:[1,0,1]
	v_mov_b32_e32 v1, s12
	v_mov_b32_e32 v0, s13
	v_readlane_b32 s12, v108, 56
	v_readlane_b32 s13, v107, 56
	v_pk_fma_f32 v[40:41], v[2:3], v[146:147], v[46:47] op_sel_hi:[1,0,1]
	v_pk_fma_f32 v[42:43], v[4:5], v[146:147], v[48:49] op_sel_hi:[1,0,1]
	v_pk_fma_f32 v[44:45], v[6:7], v[146:147], v[50:51] op_sel_hi:[1,0,1]
	v_pk_fma_f32 v[46:47], v[8:9], v[146:147], v[52:53] op_sel_hi:[1,0,1]
	v_pk_fma_f32 v[48:49], v[10:11], v[146:147], v[54:55] op_sel_hi:[1,0,1]
	v_pk_fma_f32 v[50:51], v[12:13], v[146:147], v[126:127] op_sel_hi:[1,0,1]
	v_pk_fma_f32 v[52:53], v[14:15], v[146:147], v[128:129] op_sel_hi:[1,0,1]
	v_pk_fma_f32 v[54:55], v[16:17], v[146:147], v[130:131] op_sel_hi:[1,0,1]
	v_pk_fma_f32 v[132:133], v[18:19], v[146:147], v[132:133] op_sel_hi:[1,0,1]
	v_pk_fma_f32 v[134:135], v[20:21], v[146:147], v[134:135] op_sel_hi:[1,0,1]
	v_pk_fma_f32 v[136:137], v[22:23], v[146:147], v[136:137] op_sel_hi:[1,0,1]
	v_pk_fma_f32 v[138:139], v[24:25], v[146:147], v[138:139] op_sel_hi:[1,0,1]
	v_pk_fma_f32 v[140:141], v[26:27], v[146:147], v[140:141] op_sel_hi:[1,0,1]
	v_pk_fma_f32 v[142:143], v[28:29], v[146:147], v[142:143] op_sel_hi:[1,0,1]
	v_pk_fma_f32 v[144:145], v[30:31], v[146:147], v[144:145] op_sel_hi:[1,0,1]
	v_cndmask_b32_e64 v146, v0, v1, s[0:1]
	v_mov_b32_e32 v0, s13
	v_mov_b32_e32 v1, s12
	v_cndmask_b32_e64 v0, v0, v1, s[0:1]
	v_mad_i64_i32 v[130:131], s[12:13], v0, s23, v[64:65]
	s_waitcnt vmcnt(0)
	v_cvt_scalef32_pk32_f32_fp6 v[0:31], v[32:37], 1.0
	v_readlane_b32 s12, v108, 57
	v_readlane_b32 s13, v107, 57
	v_pk_fma_f32 v[150:151], v[0:1], v[146:147], v[38:39] op_sel_hi:[1,0,1]
	v_mov_b32_e32 v1, s12
	v_mov_b32_e32 v0, s13
	v_cndmask_b32_e64 v0, v0, v1, s[0:1]
	v_mad_i64_i32 v[0:1], s[12:13], v0, s23, v[64:65]
	v_readlane_b32 s12, v108, 58
	v_readlane_b32 s13, v107, 58
	global_load_dwordx4 v[126:129], v[130:131], off
	v_pk_fma_f32 v[168:169], v[18:19], v[146:147], v[132:133] op_sel_hi:[1,0,1]
	global_load_dwordx2 v[130:131], v[130:131], off offset:16
	v_pk_fma_f32 v[170:171], v[20:21], v[146:147], v[134:135] op_sel_hi:[1,0,1]
	v_pk_fma_f32 v[172:173], v[22:23], v[146:147], v[136:137] op_sel_hi:[1,0,1]
	global_load_dwordx2 v[136:137], v[0:1], off offset:16
	global_load_dwordx4 v[132:135], v[0:1], off
	v_mov_b32_e32 v0, s13
	v_mov_b32_e32 v1, s12
	v_cndmask_b32_e64 v0, v0, v1, s[0:1]
	v_mad_i64_i32 v[0:1], s[12:13], v0, s23, v[64:65]
	v_readlane_b32 s12, v108, 59
	v_readlane_b32 s13, v107, 59
	v_pk_fma_f32 v[152:153], v[2:3], v[146:147], v[40:41] op_sel_hi:[1,0,1]
	v_mov_b32_e32 v3, s12
	v_mov_b32_e32 v2, s13
	v_cndmask_b32_e64 v2, v2, v3, s[0:1]
	v_mad_i64_i32 v[2:3], s[12:13], v2, s23, v[64:65]
	v_readlane_b32 s12, v108, 60
	v_readlane_b32 s13, v107, 60
	v_pk_fma_f32 v[154:155], v[4:5], v[146:147], v[42:43] op_sel_hi:[1,0,1]
	v_pk_fma_f32 v[156:157], v[6:7], v[146:147], v[44:45] op_sel_hi:[1,0,1]
	v_pk_fma_f32 v[158:159], v[8:9], v[146:147], v[46:47] op_sel_hi:[1,0,1]
	v_pk_fma_f32 v[160:161], v[10:11], v[146:147], v[48:49] op_sel_hi:[1,0,1]
	v_pk_fma_f32 v[162:163], v[12:13], v[146:147], v[50:51] op_sel_hi:[1,0,1]
	v_pk_fma_f32 v[164:165], v[14:15], v[146:147], v[52:53] op_sel_hi:[1,0,1]
	v_pk_fma_f32 v[166:167], v[16:17], v[146:147], v[54:55] op_sel_hi:[1,0,1]
	v_pk_fma_f32 v[174:175], v[24:25], v[146:147], v[138:139] op_sel_hi:[1,0,1]
	v_pk_fma_f32 v[176:177], v[26:27], v[146:147], v[140:141] op_sel_hi:[1,0,1]
	v_pk_fma_f32 v[178:179], v[28:29], v[146:147], v[142:143] op_sel_hi:[1,0,1]
	v_pk_fma_f32 v[180:181], v[30:31], v[146:147], v[144:145] op_sel_hi:[1,0,1]
	global_load_dwordx4 v[138:141], v[0:1], off
	global_load_dwordx2 v[142:143], v[0:1], off offset:16
	global_load_dwordx4 v[144:147], v[2:3], off
	v_mov_b32_e32 v0, s13
	v_mov_b32_e32 v1, s12
	v_cndmask_b32_e64 v0, v0, v1, s[0:1]
	v_mad_i64_i32 v[0:1], s[12:13], v0, s23, v[64:65]
	v_readlane_b32 s12, v108, 61
	v_readlane_b32 s13, v107, 61
	global_load_dwordx2 v[148:149], v[2:3], off offset:16
	global_load_dwordx4 v[50:53], v[0:1], off
	v_mov_b32_e32 v2, s13
	v_mov_b32_e32 v3, s12
	v_cndmask_b32_e64 v2, v2, v3, s[0:1]
	v_mad_i64_i32 v[2:3], s[12:13], v2, s23, v[64:65]
	v_readlane_b32 s12, v108, 62
	v_readlane_b32 s13, v107, 62
	global_load_dwordx2 v[54:55], v[0:1], off offset:16
	global_load_dwordx4 v[44:47], v[2:3], off
	v_mov_b32_e32 v0, s13
	v_mov_b32_e32 v1, s12
	v_cndmask_b32_e64 v0, v0, v1, s[0:1]
	v_mad_i64_i32 v[0:1], s[12:13], v0, s23, v[64:65]
	v_readlane_b32 s12, v108, 63
	v_readlane_b32 s13, v107, 63
	global_load_dwordx2 v[48:49], v[2:3], off offset:16
	global_load_dwordx4 v[38:41], v[0:1], off
	v_mov_b32_e32 v2, s13
	v_mov_b32_e32 v3, s12
	v_cndmask_b32_e64 v2, v2, v3, s[0:1]
	v_mad_i64_i32 v[2:3], s[12:13], v2, s23, v[64:65]
	global_load_dwordx2 v[36:37], v[2:3], off offset:16
	global_load_dwordx2 v[42:43], v[0:1], off offset:16
	global_load_dwordx4 v[32:35], v[2:3], off
	v_readlane_b32 s12, v106, 56
	v_readlane_b32 s13, v109, 56
	s_nop 0
	v_mov_b32_e32 v1, s12
	v_mov_b32_e32 v0, s13
	v_cndmask_b32_e64 v108, v0, v1, s[0:1]
	v_readlane_b32 s12, v106, 57
	v_readlane_b32 s13, v109, 57
	s_waitcnt vmcnt(14)
; DI void phase_peer_out(const Params& p, char* lds) {
;     ...
;     for (int kb = 0; kb < 8; ++kb) {
;       v6u qb[8];
; #pragma unroll
;       for (int k = 0; k < 8; ++k) {
;         const int e0 = __builtin_amdgcn_readlane(el[0], kb * 8 + k), e1 = __builtin_amdgcn_readlane(el[1], kb * 8 + k);
;         qb[k] = load6(V6 + (size_t)(hb ? e1 : e0) * 768);
;       }
; #pragma unroll
;       for (int k = 0; k < 8; ++k) {
;         const float c0 = __uint_as_float(__builtin_amdgcn_readlane(__float_as_uint(coefv[0]), kb * 8 + k)), c1 = __uint_as_float(__builtin_amdgcn_readlane(__float_as_uint(coefv[1]), kb * 8 + k));
;         const float cf = hb ? c1 : c0;
;         const f32x2 c2 = {cf, cf};
;         const v32f f = __builtin_amdgcn_cvt_scalef32_pk32_f32_fp6(qb[k], 1.0f);
; #pragma unroll
;         for (int i = 0; i < 16; ++i) o2[i] = f32x2{f[2 * i], f[2 * i + 1]} * c2 + o2[i];
;       }
;     }
	v_cvt_scalef32_pk32_f32_fp6 v[0:31], v[126:131], 1.0
	v_pk_fma_f32 v[126:127], v[0:1], v[108:109], v[150:151] op_sel_hi:[1,0,1]
	v_mov_b32_e32 v0, s13
	v_mov_b32_e32 v1, s12
	v_pk_fma_f32 v[128:129], v[2:3], v[108:109], v[152:153] op_sel_hi:[1,0,1]
	v_pk_fma_f32 v[130:131], v[4:5], v[108:109], v[154:155] op_sel_hi:[1,0,1]
	v_pk_fma_f32 v[150:151], v[6:7], v[108:109], v[156:157] op_sel_hi:[1,0,1]
	v_pk_fma_f32 v[152:153], v[8:9], v[108:109], v[158:159] op_sel_hi:[1,0,1]
	v_pk_fma_f32 v[154:155], v[10:11], v[108:109], v[160:161] op_sel_hi:[1,0,1]
	v_pk_fma_f32 v[156:157], v[12:13], v[108:109], v[162:163] op_sel_hi:[1,0,1]
	v_pk_fma_f32 v[158:159], v[14:15], v[108:109], v[164:165] op_sel_hi:[1,0,1]
	v_pk_fma_f32 v[160:161], v[16:17], v[108:109], v[166:167] op_sel_hi:[1,0,1]
	v_pk_fma_f32 v[162:163], v[18:19], v[108:109], v[168:169] op_sel_hi:[1,0,1]
	v_pk_fma_f32 v[164:165], v[20:21], v[108:109], v[170:171] op_sel_hi:[1,0,1]
	v_pk_fma_f32 v[166:167], v[22:23], v[108:109], v[172:173] op_sel_hi:[1,0,1]
	v_pk_fma_f32 v[168:169], v[24:25], v[108:109], v[174:175] op_sel_hi:[1,0,1]
	v_pk_fma_f32 v[170:171], v[26:27], v[108:109], v[176:177] op_sel_hi:[1,0,1]
	v_pk_fma_f32 v[172:173], v[28:29], v[108:109], v[178:179] op_sel_hi:[1,0,1]
	v_pk_fma_f32 v[174:175], v[30:31], v[108:109], v[180:181] op_sel_hi:[1,0,1]
	v_cndmask_b32_e64 v108, v0, v1, s[0:1]
	s_waitcnt vmcnt(12)
	v_cvt_scalef32_pk32_f32_fp6 v[0:31], v[132:137], 1.0
	v_readlane_b32 s12, v106, 58
	v_readlane_b32 s13, v109, 58
	v_pk_fma_f32 v[126:127], v[0:1], v[108:109], v[126:127] op_sel_hi:[1,0,1]
	v_mov_b32_e32 v1, s12
	v_mov_b32_e32 v0, s13
	v_pk_fma_f32 v[128:129], v[2:3], v[108:109], v[128:129] op_sel_hi:[1,0,1]
	v_pk_fma_f32 v[130:131], v[4:5], v[108:109], v[130:131] op_sel_hi:[1,0,1]
	v_pk_fma_f32 v[132:133], v[6:7], v[108:109], v[150:151] op_sel_hi:[1,0,1]
	v_pk_fma_f32 v[134:135], v[8:9], v[108:109], v[152:153] op_sel_hi:[1,0,1]
	v_pk_fma_f32 v[136:137], v[10:11], v[108:109], v[154:155] op_sel_hi:[1,0,1]
	v_pk_fma_f32 v[150:151], v[12:13], v[108:109], v[156:157] op_sel_hi:[1,0,1]
	v_pk_fma_f32 v[152:153], v[14:15], v[108:109], v[158:159] op_sel_hi:[1,0,1]
	v_pk_fma_f32 v[154:155], v[16:17], v[108:109], v[160:161] op_sel_hi:[1,0,1]
	v_pk_fma_f32 v[156:157], v[18:19], v[108:109], v[162:163] op_sel_hi:[1,0,1]
	v_pk_fma_f32 v[158:159], v[20:21], v[108:109], v[164:165] op_sel_hi:[1,0,1]
	v_pk_fma_f32 v[160:161], v[22:23], v[108:109], v[166:167] op_sel_hi:[1,0,1]
	v_pk_fma_f32 v[162:163], v[24:25], v[108:109], v[168:169] op_sel_hi:[1,0,1]
	v_pk_fma_f32 v[164:165], v[26:27], v[108:109], v[170:171] op_sel_hi:[1,0,1]
	v_pk_fma_f32 v[166:167], v[28:29], v[108:109], v[172:173] op_sel_hi:[1,0,1]
	v_pk_fma_f32 v[168:169], v[30:31], v[108:109], v[174:175] op_sel_hi:[1,0,1]
	v_cndmask_b32_e64 v108, v0, v1, s[0:1]
	s_waitcnt vmcnt(10)
	v_cvt_scalef32_pk32_f32_fp6 v[0:31], v[138:143], 1.0
	v_readlane_b32 s12, v106, 59
	v_readlane_b32 s13, v109, 59
	v_pk_fma_f32 v[126:127], v[0:1], v[108:109], v[126:127] op_sel_hi:[1,0,1]
	v_mov_b32_e32 v1, s12
	v_mov_b32_e32 v0, s13
	v_pk_fma_f32 v[128:129], v[2:3], v[108:109], v[128:129] op_sel_hi:[1,0,1]
	v_pk_fma_f32 v[130:131], v[4:5], v[108:109], v[130:131] op_sel_hi:[1,0,1]
	v_pk_fma_f32 v[132:133], v[6:7], v[108:109], v[132:133] op_sel_hi:[1,0,1]
	v_pk_fma_f32 v[134:135], v[8:9], v[108:109], v[134:135] op_sel_hi:[1,0,1]
	v_pk_fma_f32 v[136:137], v[10:11], v[108:109], v[136:137] op_sel_hi:[1,0,1]
	v_pk_fma_f32 v[138:139], v[12:13], v[108:109], v[150:151] op_sel_hi:[1,0,1]
	v_pk_fma_f32 v[140:141], v[14:15], v[108:109], v[152:153] op_sel_hi:[1,0,1]
	v_pk_fma_f32 v[142:143], v[16:17], v[108:109], v[154:155] op_sel_hi:[1,0,1]
	v_pk_fma_f32 v[150:151], v[18:19], v[108:109], v[156:157] op_sel_hi:[1,0,1]
	v_pk_fma_f32 v[152:153], v[20:21], v[108:109], v[158:159] op_sel_hi:[1,0,1]
	v_pk_fma_f32 v[154:155], v[22:23], v[108:109], v[160:161] op_sel_hi:[1,0,1]
	v_pk_fma_f32 v[156:157], v[24:25], v[108:109], v[162:163] op_sel_hi:[1,0,1]
	v_pk_fma_f32 v[158:159], v[26:27], v[108:109], v[164:165] op_sel_hi:[1,0,1]
	v_pk_fma_f32 v[160:161], v[28:29], v[108:109], v[166:167] op_sel_hi:[1,0,1]
	v_pk_fma_f32 v[162:163], v[30:31], v[108:109], v[168:169] op_sel_hi:[1,0,1]
	v_cndmask_b32_e64 v108, v0, v1, s[0:1]
	s_waitcnt vmcnt(8)
	v_cvt_scalef32_pk32_f32_fp6 v[0:31], v[144:149], 1.0
	v_readlane_b32 s12, v106, 60
	v_readlane_b32 s13, v109, 60
	v_pk_fma_f32 v[126:127], v[0:1], v[108:109], v[126:127] op_sel_hi:[1,0,1]
	v_mov_b32_e32 v1, s12
	v_mov_b32_e32 v0, s13
	v_pk_fma_f32 v[128:129], v[2:3], v[108:109], v[128:129] op_sel_hi:[1,0,1]
	v_pk_fma_f32 v[130:131], v[4:5], v[108:109], v[130:131] op_sel_hi:[1,0,1]
	v_pk_fma_f32 v[132:133], v[6:7], v[108:109], v[132:133] op_sel_hi:[1,0,1]
	v_pk_fma_f32 v[134:135], v[8:9], v[108:109], v[134:135] op_sel_hi:[1,0,1]
	v_pk_fma_f32 v[136:137], v[10:11], v[108:109], v[136:137] op_sel_hi:[1,0,1]
	v_pk_fma_f32 v[138:139], v[12:13], v[108:109], v[138:139] op_sel_hi:[1,0,1]
	v_pk_fma_f32 v[140:141], v[14:15], v[108:109], v[140:141] op_sel_hi:[1,0,1]
	v_pk_fma_f32 v[142:143], v[16:17], v[108:109], v[142:143] op_sel_hi:[1,0,1]
	v_pk_fma_f32 v[144:145], v[18:19], v[108:109], v[150:151] op_sel_hi:[1,0,1]
	v_pk_fma_f32 v[146:147], v[20:21], v[108:109], v[152:153] op_sel_hi:[1,0,1]
	v_pk_fma_f32 v[148:149], v[22:23], v[108:109], v[154:155] op_sel_hi:[1,0,1]
	v_pk_fma_f32 v[150:151], v[24:25], v[108:109], v[156:157] op_sel_hi:[1,0,1]
	v_pk_fma_f32 v[152:153], v[26:27], v[108:109], v[158:159] op_sel_hi:[1,0,1]
	v_pk_fma_f32 v[154:155], v[28:29], v[108:109], v[160:161] op_sel_hi:[1,0,1]
	v_pk_fma_f32 v[156:157], v[30:31], v[108:109], v[162:163] op_sel_hi:[1,0,1]
	v_cndmask_b32_e64 v108, v0, v1, s[0:1]
	s_waitcnt vmcnt(6)
; DI void phase_peer_out(const Params& p, char* lds) {
;     ...
;     for (int kb = 0; kb < 8; ++kb) {
;       v6u qb[8];
; #pragma unroll
;       for (int k = 0; k < 8; ++k) {
;         const int e0 = __builtin_amdgcn_readlane(el[0], kb * 8 + k), e1 = __builtin_amdgcn_readlane(el[1], kb * 8 + k);
;         qb[k] = load6(V6 + (size_t)(hb ? e1 : e0) * 768);
;       }
; #pragma unroll
;       for (int k = 0; k < 8; ++k) {
;         const float c0 = __uint_as_float(__builtin_amdgcn_readlane(__float_as_uint(coefv[0]), kb * 8 + k)), c1 = __uint_as_float(__builtin_amdgcn_readlane(__float_as_uint(coefv[1]), kb * 8 + k));
;         const float cf = hb ? c1 : c0;
;         const f32x2 c2 = {cf, cf};
;         const v32f f = __builtin_amdgcn_cvt_scalef32_pk32_f32_fp6(qb[k], 1.0f);
; #pragma unroll
;         for (int i = 0; i < 16; ++i) o2[i] = f32x2{f[2 * i], f[2 * i + 1]} * c2 + o2[i];
;       }
;     }
;     float s = 0.f;
; #pragma unroll
;     for (int i = 0; i < 16; ++i) {
;       o2[i].x += __shfl_xor(o2[i].x, 32); o2[i].y += __shfl_xor(o2[i].y, 32);
;       o2[i] = x2[i] * f32x2{ALPHA, ALPHA} + o2[i]; s += o2[i].x + o2[i].y;
;     }
	v_cvt_scalef32_pk32_f32_fp6 v[0:31], v[50:55], 1.0
	v_readlane_b32 s12, v106, 61
	v_readlane_b32 s13, v109, 61
	v_pk_fma_f32 v[50:51], v[0:1], v[108:109], v[126:127] op_sel_hi:[1,0,1]
	v_mov_b32_e32 v1, s12
	v_mov_b32_e32 v0, s13
	v_pk_fma_f32 v[52:53], v[2:3], v[108:109], v[128:129] op_sel_hi:[1,0,1]
	v_pk_fma_f32 v[54:55], v[4:5], v[108:109], v[130:131] op_sel_hi:[1,0,1]
	v_pk_fma_f32 v[126:127], v[6:7], v[108:109], v[132:133] op_sel_hi:[1,0,1]
	v_pk_fma_f32 v[128:129], v[8:9], v[108:109], v[134:135] op_sel_hi:[1,0,1]
	v_pk_fma_f32 v[130:131], v[10:11], v[108:109], v[136:137] op_sel_hi:[1,0,1]
	v_pk_fma_f32 v[132:133], v[12:13], v[108:109], v[138:139] op_sel_hi:[1,0,1]
	v_pk_fma_f32 v[134:135], v[14:15], v[108:109], v[140:141] op_sel_hi:[1,0,1]
	v_pk_fma_f32 v[136:137], v[16:17], v[108:109], v[142:143] op_sel_hi:[1,0,1]
	v_pk_fma_f32 v[138:139], v[18:19], v[108:109], v[144:145] op_sel_hi:[1,0,1]
	v_pk_fma_f32 v[140:141], v[20:21], v[108:109], v[146:147] op_sel_hi:[1,0,1]
	v_pk_fma_f32 v[142:143], v[22:23], v[108:109], v[148:149] op_sel_hi:[1,0,1]
	v_pk_fma_f32 v[144:145], v[24:25], v[108:109], v[150:151] op_sel_hi:[1,0,1]
	v_pk_fma_f32 v[146:147], v[26:27], v[108:109], v[152:153] op_sel_hi:[1,0,1]
	v_pk_fma_f32 v[148:149], v[28:29], v[108:109], v[154:155] op_sel_hi:[1,0,1]
	v_pk_fma_f32 v[150:151], v[30:31], v[108:109], v[156:157] op_sel_hi:[1,0,1]
	v_cndmask_b32_e64 v108, v0, v1, s[0:1]
	s_waitcnt vmcnt(4)
	v_cvt_scalef32_pk32_f32_fp6 v[0:31], v[44:49], 1.0
	v_readlane_b32 s12, v106, 62
	v_readlane_b32 s13, v109, 62
	v_pk_fma_f32 v[44:45], v[0:1], v[108:109], v[50:51] op_sel_hi:[1,0,1]
	v_mov_b32_e32 v1, s12
	v_mov_b32_e32 v0, s13
	v_pk_fma_f32 v[46:47], v[2:3], v[108:109], v[52:53] op_sel_hi:[1,0,1]
	v_pk_fma_f32 v[48:49], v[4:5], v[108:109], v[54:55] op_sel_hi:[1,0,1]
	v_pk_fma_f32 v[50:51], v[6:7], v[108:109], v[126:127] op_sel_hi:[1,0,1]
	v_pk_fma_f32 v[52:53], v[8:9], v[108:109], v[128:129] op_sel_hi:[1,0,1]
	v_pk_fma_f32 v[54:55], v[10:11], v[108:109], v[130:131] op_sel_hi:[1,0,1]
	v_pk_fma_f32 v[126:127], v[12:13], v[108:109], v[132:133] op_sel_hi:[1,0,1]
	v_pk_fma_f32 v[128:129], v[14:15], v[108:109], v[134:135] op_sel_hi:[1,0,1]
	v_pk_fma_f32 v[130:131], v[16:17], v[108:109], v[136:137] op_sel_hi:[1,0,1]
	v_pk_fma_f32 v[132:133], v[18:19], v[108:109], v[138:139] op_sel_hi:[1,0,1]
	v_pk_fma_f32 v[134:135], v[20:21], v[108:109], v[140:141] op_sel_hi:[1,0,1]
	v_pk_fma_f32 v[136:137], v[22:23], v[108:109], v[142:143] op_sel_hi:[1,0,1]
	v_pk_fma_f32 v[138:139], v[24:25], v[108:109], v[144:145] op_sel_hi:[1,0,1]
	v_pk_fma_f32 v[140:141], v[26:27], v[108:109], v[146:147] op_sel_hi:[1,0,1]
	v_pk_fma_f32 v[142:143], v[28:29], v[108:109], v[148:149] op_sel_hi:[1,0,1]
	v_pk_fma_f32 v[144:145], v[30:31], v[108:109], v[150:151] op_sel_hi:[1,0,1]
	v_cndmask_b32_e64 v108, v0, v1, s[0:1]
	s_waitcnt vmcnt(1)
	v_cvt_scalef32_pk32_f32_fp6 v[0:31], v[38:43], 1.0
	v_readlane_b32 s12, v106, 63
	v_readlane_b32 s13, v109, 63
	v_pk_fma_f32 v[38:39], v[0:1], v[108:109], v[44:45] op_sel_hi:[1,0,1]
	v_mov_b32_e32 v1, s12
	v_mov_b32_e32 v0, s13
	v_pk_fma_f32 v[40:41], v[2:3], v[108:109], v[46:47] op_sel_hi:[1,0,1]
	v_pk_fma_f32 v[42:43], v[4:5], v[108:109], v[48:49] op_sel_hi:[1,0,1]
	v_pk_fma_f32 v[44:45], v[6:7], v[108:109], v[50:51] op_sel_hi:[1,0,1]
	v_pk_fma_f32 v[46:47], v[8:9], v[108:109], v[52:53] op_sel_hi:[1,0,1]
	v_pk_fma_f32 v[48:49], v[10:11], v[108:109], v[54:55] op_sel_hi:[1,0,1]
	v_pk_fma_f32 v[50:51], v[12:13], v[108:109], v[126:127] op_sel_hi:[1,0,1]
	v_pk_fma_f32 v[52:53], v[14:15], v[108:109], v[128:129] op_sel_hi:[1,0,1]
	v_pk_fma_f32 v[54:55], v[16:17], v[108:109], v[130:131] op_sel_hi:[1,0,1]
	v_pk_fma_f32 v[126:127], v[18:19], v[108:109], v[132:133] op_sel_hi:[1,0,1]
	v_pk_fma_f32 v[128:129], v[20:21], v[108:109], v[134:135] op_sel_hi:[1,0,1]
	v_pk_fma_f32 v[130:131], v[22:23], v[108:109], v[136:137] op_sel_hi:[1,0,1]
	v_pk_fma_f32 v[132:133], v[24:25], v[108:109], v[138:139] op_sel_hi:[1,0,1]
	v_pk_fma_f32 v[134:135], v[26:27], v[108:109], v[140:141] op_sel_hi:[1,0,1]
	v_pk_fma_f32 v[136:137], v[28:29], v[108:109], v[142:143] op_sel_hi:[1,0,1]
	v_pk_fma_f32 v[138:139], v[30:31], v[108:109], v[144:145] op_sel_hi:[1,0,1]
	v_cndmask_b32_e64 v106, v0, v1, s[0:1]
	s_waitcnt vmcnt(0)
	v_cvt_scalef32_pk32_f32_fp6 v[0:31], v[32:37], 1.0
	v_pk_fma_f32 v[0:1], v[0:1], v[106:107], v[38:39] op_sel_hi:[1,0,1]
	v_pk_fma_f32 v[32:33], v[8:9], v[106:107], v[46:47] op_sel_hi:[1,0,1]
	ds_bpermute_b32 v8, v113, v0
	ds_bpermute_b32 v9, v113, v1
	v_pk_fma_f32 v[2:3], v[2:3], v[106:107], v[40:41] op_sel_hi:[1,0,1]
	v_pk_fma_f32 v[34:35], v[10:11], v[106:107], v[48:49] op_sel_hi:[1,0,1]
	ds_bpermute_b32 v10, v113, v2
	ds_bpermute_b32 v11, v113, v3
	s_waitcnt lgkmcnt(2)
	v_pk_add_f32 v[0:1], v[0:1], v[8:9]
	v_pk_fma_f32 v[36:37], v[12:13], v[106:107], v[50:51] op_sel_hi:[1,0,1]
	v_pk_fma_f32 v[12:13], v[94:95], s[20:21], v[0:1] op_sel_hi:[1,0,1]
	v_pk_fma_f32 v[4:5], v[4:5], v[106:107], v[42:43] op_sel_hi:[1,0,1]
	v_add_f32_e32 v0, v12, v13
	v_add_f32_e32 v8, 0, v0
	s_waitcnt lgkmcnt(0)
	v_pk_add_f32 v[0:1], v[2:3], v[10:11]
	v_pk_fma_f32 v[38:39], v[14:15], v[106:107], v[52:53] op_sel_hi:[1,0,1]
	v_pk_fma_f32 v[14:15], v[92:93], s[20:21], v[0:1] op_sel_hi:[1,0,1]
	ds_bpermute_b32 v0, v113, v4
	ds_bpermute_b32 v1, v113, v5
	v_pk_fma_f32 v[6:7], v[6:7], v[106:107], v[44:45] op_sel_hi:[1,0,1]
	v_add_f32_e32 v2, v14, v15
	v_add_f32_e32 v10, v2, v8
	ds_bpermute_b32 v2, v113, v6
	ds_bpermute_b32 v3, v113, v7
	s_waitcnt lgkmcnt(2)
; DI void phase_peer_out(const Params& p, char* lds) {
;     ...
;     float s = 0.f;
; #pragma unroll
;     for (int i = 0; i < 16; ++i) {
;       o2[i].x += __shfl_xor(o2[i].x, 32); o2[i].y += __shfl_xor(o2[i].y, 32);
;       o2[i] = x2[i] * f32x2{ALPHA, ALPHA} + o2[i]; s += o2[i].x + o2[i].y;
;     }
;     for (int o = 16; o; o >>= 1) s += __shfl_xor(s, o);
;     const float mu = s * (1.f / 1024.f);
;     float q = 0.f;
; #pragma unroll
;     for (int i = 0; i < 16; ++i) { const float a = o2[i].x - mu, bq = o2[i].y - mu; q += a * a + bq * bq; }
;     for (int o = 16; o; o >>= 1) q += __shfl_xor(q, o);
	v_pk_add_f32 v[0:1], v[4:5], v[0:1]
	v_pk_fma_f32 v[40:41], v[22:23], v[106:107], v[130:131] op_sel_hi:[1,0,1]
	v_pk_fma_f32 v[8:9], v[86:87], s[20:21], v[0:1] op_sel_hi:[1,0,1]
	v_pk_fma_f32 v[16:17], v[16:17], v[106:107], v[54:55] op_sel_hi:[1,0,1]
	v_add_f32_e32 v0, v8, v9
	v_add_f32_e32 v4, v0, v10
	s_waitcnt lgkmcnt(0)
	v_pk_add_f32 v[0:1], v[6:7], v[2:3]
	ds_bpermute_b32 v3, v113, v35
	v_pk_fma_f32 v[10:11], v[100:101], s[20:21], v[0:1] op_sel_hi:[1,0,1]
	ds_bpermute_b32 v0, v113, v32
	ds_bpermute_b32 v1, v113, v33
	v_add_f32_e32 v2, v10, v11
	v_add_f32_e32 v6, v2, v4
	ds_bpermute_b32 v2, v113, v34
	v_pk_fma_f32 v[42:43], v[26:27], v[106:107], v[134:135] op_sel_hi:[1,0,1]
	s_waitcnt lgkmcnt(1)
	v_pk_add_f32 v[0:1], v[32:33], v[0:1]
	v_pk_fma_f32 v[18:19], v[18:19], v[106:107], v[126:127] op_sel_hi:[1,0,1]
	v_pk_fma_f32 v[4:5], v[104:105], s[20:21], v[0:1] op_sel_hi:[1,0,1]
	v_pk_fma_f32 v[46:47], v[30:31], v[106:107], v[138:139] op_sel_hi:[1,0,1]
	v_add_f32_e32 v0, v4, v5
	v_add_f32_e32 v22, v0, v6
	s_waitcnt lgkmcnt(0)
	v_pk_add_f32 v[0:1], v[34:35], v[2:3]
	ds_bpermute_b32 v3, v113, v39
	v_pk_fma_f32 v[6:7], v[102:103], s[20:21], v[0:1] op_sel_hi:[1,0,1]
	ds_bpermute_b32 v0, v113, v36
	ds_bpermute_b32 v1, v113, v37
	v_add_f32_e32 v2, v6, v7
	v_add_f32_e32 v22, v2, v22
	ds_bpermute_b32 v2, v113, v38
	v_pk_fma_f32 v[44:45], v[28:29], v[106:107], v[136:137] op_sel_hi:[1,0,1]
	s_waitcnt lgkmcnt(1)
	v_pk_add_f32 v[0:1], v[36:37], v[0:1]
	v_pk_fma_f32 v[20:21], v[20:21], v[106:107], v[128:129] op_sel_hi:[1,0,1]
	v_pk_fma_f32 v[0:1], v[98:99], s[20:21], v[0:1] op_sel_hi:[1,0,1]
	s_waitcnt lgkmcnt(0)
	v_pk_add_f32 v[2:3], v[38:39], v[2:3]
	v_add_f32_e32 v23, v0, v1
	v_add_f32_e32 v26, v22, v23
	ds_bpermute_b32 v22, v113, v16
	ds_bpermute_b32 v23, v113, v17
	v_pk_fma_f32 v[2:3], v[96:97], s[20:21], v[2:3] op_sel_hi:[1,0,1]
	v_pk_fma_f32 v[24:25], v[24:25], v[106:107], v[132:133] op_sel_hi:[1,0,1]
	v_add_f32_e32 v27, v2, v3
	v_add_f32_e32 v30, v26, v27
	ds_bpermute_b32 v26, v113, v18
	ds_bpermute_b32 v27, v113, v19
	s_waitcnt lgkmcnt(2)
	v_pk_add_f32 v[16:17], v[16:17], v[22:23]
	ds_bpermute_b32 v33, v113, v47
	v_pk_fma_f32 v[28:29], v[90:91], s[20:21], v[16:17] op_sel_hi:[1,0,1]
	s_nop 0
	v_add_f32_e32 v16, v28, v29
	v_add_f32_e32 v22, v30, v16
	s_waitcnt lgkmcnt(1)
	v_pk_add_f32 v[16:17], v[18:19], v[26:27]
	ds_bpermute_b32 v18, v113, v40
	v_pk_fma_f32 v[30:31], v[88:89], s[20:21], v[16:17] op_sel_hi:[1,0,1]
	ds_bpermute_b32 v16, v113, v20
	ds_bpermute_b32 v17, v113, v21
	ds_bpermute_b32 v19, v113, v41
	v_add_f32_e32 v23, v30, v31
	v_add_f32_e32 v32, v22, v23
	s_waitcnt lgkmcnt(1)
	v_pk_add_f32 v[16:17], v[20:21], v[16:17]
	s_nop 0
	v_pk_fma_f32 v[22:23], v[84:85], s[20:21], v[16:17] op_sel_hi:[1,0,1]
	s_waitcnt lgkmcnt(0)
	v_pk_add_f32 v[16:17], v[40:41], v[18:19]
	v_mov_b32_e32 v18, v23
	v_pk_fma_f32 v[26:27], v[82:83], s[20:21], v[16:17] op_sel_hi:[1,0,1]
	v_mov_b32_e32 v16, v22
	v_mov_b32_e32 v17, v26
	v_mov_b32_e32 v19, v27
	v_pk_add_f32 v[16:17], v[16:17], v[18:19]
	ds_bpermute_b32 v18, v113, v24
	ds_bpermute_b32 v19, v113, v25
	ds_bpermute_b32 v20, v113, v42
	ds_bpermute_b32 v21, v113, v43
	v_add_f32_e32 v16, v32, v16
	v_add_f32_e32 v34, v16, v17
	s_waitcnt lgkmcnt(2)
	v_pk_add_f32 v[16:17], v[24:25], v[18:19]
	ds_bpermute_b32 v32, v113, v46
	v_pk_fma_f32 v[18:19], v[78:79], s[20:21], v[16:17] op_sel_hi:[1,0,1]
	s_waitcnt lgkmcnt(1)
	v_pk_add_f32 v[16:17], v[42:43], v[20:21]
	v_mov_b32_e32 v20, v19
	v_pk_fma_f32 v[24:25], v[76:77], s[20:21], v[16:17] op_sel_hi:[1,0,1]
	v_mov_b32_e32 v16, v18
	v_mov_b32_e32 v17, v24
	v_mov_b32_e32 v21, v25
	v_pk_add_f32 v[16:17], v[16:17], v[20:21]
	ds_bpermute_b32 v20, v113, v44
	ds_bpermute_b32 v21, v113, v45
	v_add_f32_e32 v16, v34, v16
	v_add_f32_e32 v36, v16, v17
	v_mov_b32_e32 v43, v22
	s_waitcnt lgkmcnt(0)
	v_pk_add_f32 v[16:17], v[44:45], v[20:21]
	v_pk_add_f32 v[20:21], v[46:47], v[32:33]
	v_pk_fma_f32 v[16:17], v[74:75], s[20:21], v[16:17] op_sel_hi:[1,0,1]
	v_pk_fma_f32 v[20:21], v[80:81], s[20:21], v[20:21] op_sel_hi:[1,0,1]
	v_mov_b32_e32 v32, v16
	v_mov_b32_e32 v33, v20
	v_mov_b32_e32 v34, v17
	v_mov_b32_e32 v35, v21
	v_pk_add_f32 v[32:33], v[32:33], v[34:35]
	v_mov_b32_e32 v44, v27
	v_add_f32_e32 v32, v36, v32
	v_add_f32_e32 v32, v32, v33
	v_mov_b32_e32 v45, v23
	s_nop 1
	v_add_f32_dpp v32, v32, v32 row_shr:1 row_mask:0xf bank_mask:0xf
	s_nop 1
	v_add_f32_dpp v32, v32, v32 row_shr:2 row_mask:0xf bank_mask:0xf
	s_nop 1
	v_add_f32_dpp v32, v32, v32 row_shr:4 row_mask:0xf bank_mask:0xf
	s_nop 1
	v_add_f32_dpp v32, v32, v32 row_shr:8 row_mask:0xf bank_mask:0xf
	s_nop 1
	v_add_f32_dpp v32, v32, v32 row_bcast:15 row_mask:0xa bank_mask:0xf
	s_nop 0
	v_readlane_b32 s90, v32, 63
	s_nop 1
	v_mov_b32_e32 v33, s90
	v_fmamk_f32 v35, v33, 0xba800000, v13
	v_fmamk_f32 v34, v33, 0xba800000, v12
	v_mul_f32_e32 v35, v35, v35
	v_fmamk_f32 v36, v33, 0xba800000, v15
	v_fmac_f32_e32 v35, v34, v34
	v_fmamk_f32 v34, v33, 0xba800000, v14
	v_mul_f32_e32 v36, v36, v36
	v_fmac_f32_e32 v36, v34, v34
	v_add_f32_e32 v34, v35, v36
	v_fmamk_f32 v36, v33, 0xba800000, v9
	v_fmamk_f32 v35, v33, 0xba800000, v8
	v_mul_f32_e32 v36, v36, v36
	v_fmac_f32_e32 v36, v35, v35
	v_add_f32_e32 v34, v36, v34
	v_fmamk_f32 v36, v33, 0xba800000, v11
	v_fmamk_f32 v35, v33, 0xba800000, v10
	v_mul_f32_e32 v36, v36, v36
	v_fmac_f32_e32 v36, v35, v35
	v_add_f32_e32 v34, v36, v34
	v_fmamk_f32 v36, v33, 0xba800000, v5
	v_fmamk_f32 v35, v33, 0xba800000, v4
	v_mul_f32_e32 v36, v36, v36
; DI void phase_peer_out(const Params& p, char* lds) {
;     ...
; #pragma unroll
;     for (int i = 0; i < 16; ++i) { const float a = o2[i].x - mu, bq = o2[i].y - mu; q += a * a + bq * bq; }
;     for (int o = 16; o; o >>= 1) q += __shfl_xor(q, o);
;     const float rstd = rsqrtf(q * (1.f / 1024.f) + LN_EPS);
;     float* orow = p.out + (size_t)t * 1024 + 32 * l5 + 16 * hb;
; #pragma unroll
;     for (int q4 = 0; q4 < 4; ++q4) {
;       const float4 gg = *(const float4*)(g3 + 32 * l5 + 16 * hb + 4 * q4), bb = *(const float4*)(b3 + 32 * l5 + 16 * hb + 4 * q4);
;       const f32x2 a0 = hb ? o2[8 + 2 * q4] : o2[2 * q4], a1 = hb ? o2[8 + 2 * q4 + 1] : o2[2 * q4 + 1];
;       float4 o;
;       o.x = (a0.x - mu) * rstd * gg.x + bb.x; o.y = (a0.y - mu) * rstd * gg.y + bb.y;
;       o.z = (a1.x - mu) * rstd * gg.z + bb.z; o.w = (a1.y - mu) * rstd * gg.w + bb.w;
;       *(float4*)(orow + 4 * q4) = o;
;     }
	v_fmac_f32_e32 v36, v35, v35
	v_add_f32_e32 v34, v36, v34
	v_fmamk_f32 v36, v33, 0xba800000, v7
	v_fmamk_f32 v35, v33, 0xba800000, v6
	v_mul_f32_e32 v36, v36, v36
	v_fmac_f32_e32 v36, v35, v35
	v_add_f32_e32 v34, v36, v34
	v_fmamk_f32 v36, v33, 0xba800000, v1
	v_fmamk_f32 v35, v33, 0xba800000, v0
	v_mul_f32_e32 v36, v36, v36
	v_fmac_f32_e32 v36, v35, v35
	v_add_f32_e32 v34, v36, v34
	v_fmamk_f32 v36, v33, 0xba800000, v3
	v_fmamk_f32 v35, v33, 0xba800000, v2
	v_mul_f32_e32 v36, v36, v36
	v_fmac_f32_e32 v36, v35, v35
	v_add_f32_e32 v34, v36, v34
	v_fmamk_f32 v36, v33, 0xba800000, v29
	v_fmamk_f32 v35, v33, 0xba800000, v28
	v_mul_f32_e32 v36, v36, v36
	v_fmac_f32_e32 v36, v35, v35
	v_mul_f32_e32 v32, 0x3a800000, v33
	v_add_f32_e32 v42, v36, v34
	v_fmamk_f32 v34, v33, 0xba800000, v30
	v_fmamk_f32 v33, v33, 0xba800000, v31
	v_mul_f32_e32 v33, v33, v33
	v_fmac_f32_e32 v33, v34, v34
	v_add_f32_e32 v33, v33, v42
	v_mov_b32_e32 v42, v26
	v_pk_add_f32 v[44:45], v[44:45], v[32:33] op_sel_hi:[1,0] neg_lo:[0,1] neg_hi:[0,1]
	v_pk_add_f32 v[42:43], v[42:43], v[32:33] op_sel_hi:[1,0] neg_lo:[0,1] neg_hi:[0,1]
	v_pk_mul_f32 v[44:45], v[44:45], v[44:45]
	v_cndmask_b32_e64 v13, v29, v13, s[0:1]
	v_pk_fma_f32 v[42:43], v[42:43], v[42:43], v[44:45]
	v_mov_b32_e32 v44, v25
	v_add_f32_e32 v33, v43, v33
	v_add_f32_e32 v33, v42, v33
	v_mov_b32_e32 v45, v19
	v_mov_b32_e32 v42, v24
	v_mov_b32_e32 v43, v18
	v_pk_add_f32 v[44:45], v[44:45], v[32:33] op_sel_hi:[1,0] neg_lo:[0,1] neg_hi:[0,1]
	v_pk_add_f32 v[42:43], v[42:43], v[32:33] op_sel_hi:[1,0] neg_lo:[0,1] neg_hi:[0,1]
	v_pk_mul_f32 v[44:45], v[44:45], v[44:45]
	v_cndmask_b32_e64 v12, v28, v12, s[0:1]
	v_pk_fma_f32 v[42:43], v[42:43], v[42:43], v[44:45]
	v_mov_b32_e32 v44, v21
	v_add_f32_e32 v33, v43, v33
	v_add_f32_e32 v33, v42, v33
	v_mov_b32_e32 v45, v17
	v_mov_b32_e32 v42, v20
	v_mov_b32_e32 v43, v16
	v_pk_add_f32 v[44:45], v[44:45], v[32:33] op_sel_hi:[1,0] neg_lo:[0,1] neg_hi:[0,1]
	v_pk_add_f32 v[42:43], v[42:43], v[32:33] op_sel_hi:[1,0] neg_lo:[0,1] neg_hi:[0,1]
	v_pk_mul_f32 v[44:45], v[44:45], v[44:45]
	v_cndmask_b32_e64 v15, v31, v15, s[0:1]
	v_pk_fma_f32 v[42:43], v[42:43], v[42:43], v[44:45]
	v_cndmask_b32_e64 v14, v30, v14, s[0:1]
	v_add_f32_e32 v33, v43, v33
	v_add_f32_e32 v33, v42, v33
	v_lshlrev_b64 v[44:45], 12, v[60:61]
	v_lshl_add_u64 v[44:45], v[72:73], 0, v[44:45]
	v_cndmask_b32_e64 v9, v23, v9, s[0:1]
	v_cndmask_b32_e64 v8, v22, v8, s[0:1]
	v_cndmask_b32_e64 v11, v27, v11, s[0:1]
	v_cndmask_b32_e64 v10, v26, v10, s[0:1]
	v_cndmask_b32_e64 v5, v19, v5, s[0:1]
	v_cndmask_b32_e64 v4, v18, v4, s[0:1]
	v_cndmask_b32_e64 v7, v25, v7, s[0:1]
	v_cndmask_b32_e64 v6, v24, v6, s[0:1]
	v_cndmask_b32_e64 v1, v17, v1, s[0:1]
	v_cndmask_b32_e64 v0, v16, v0, s[0:1]
	v_cndmask_b32_e64 v3, v21, v3, s[0:1]
	v_cndmask_b32_e64 v2, v20, v2, s[0:1]
	v_add_u32_e32 v60, s53, v60
	s_nop 1
	v_add_f32_dpp v33, v33, v33 row_shr:1 row_mask:0xf bank_mask:0xf
	s_nop 1
	v_add_f32_dpp v33, v33, v33 row_shr:2 row_mask:0xf bank_mask:0xf
	s_nop 1
	v_add_f32_dpp v33, v33, v33 row_shr:4 row_mask:0xf bank_mask:0xf
	s_nop 1
	v_add_f32_dpp v33, v33, v33 row_shr:8 row_mask:0xf bank_mask:0xf
	s_nop 1
	v_add_f32_dpp v33, v33, v33 row_bcast:15 row_mask:0xa bank_mask:0xf
	s_nop 0
	v_readlane_b32 s90, v33, 63
	s_nop 1
	v_mov_b32_e32 v33, s90
	v_fmamk_f32 v33, v33, 0x3a800000, v123
	v_mul_f32_e32 v42, 0x4b800000, v33
	v_cmp_gt_f32_e64 s[12:13], s35, v33
	s_nop 1
	v_cndmask_b32_e64 v33, v33, v42, s[12:13]
	v_rsq_f32_e32 v33, v33
	s_nop 0
	v_mul_f32_e32 v42, 0x45800000, v33
	v_cndmask_b32_e64 v42, v33, v42, s[12:13]
	v_pk_add_f32 v[12:13], v[12:13], v[32:33] op_sel_hi:[1,0] neg_lo:[0,1] neg_hi:[0,1]
	v_pk_add_f32 v[14:15], v[14:15], v[32:33] op_sel_hi:[1,0] neg_lo:[0,1] neg_hi:[0,1]
	v_pk_mul_f32 v[12:13], v[12:13], v[42:43] op_sel_hi:[1,0]
	v_pk_mul_f32 v[14:15], v[14:15], v[42:43] op_sel_hi:[1,0]
	v_pk_add_f32 v[8:9], v[8:9], v[32:33] op_sel_hi:[1,0] neg_lo:[0,1] neg_hi:[0,1]
	v_pk_fma_f32 v[12:13], v[184:185], v[12:13], v[200:201]
	v_pk_fma_f32 v[14:15], v[186:187], v[14:15], v[202:203]
	global_store_dwordx4 v[44:45], v[12:15], off
	v_pk_add_f32 v[10:11], v[10:11], v[32:33] op_sel_hi:[1,0] neg_lo:[0,1] neg_hi:[0,1]
	v_pk_mul_f32 v[8:9], v[8:9], v[42:43] op_sel_hi:[1,0]
	v_pk_mul_f32 v[10:11], v[10:11], v[42:43] op_sel_hi:[1,0]
	v_pk_add_f32 v[4:5], v[4:5], v[32:33] op_sel_hi:[1,0] neg_lo:[0,1] neg_hi:[0,1]
	v_pk_add_f32 v[6:7], v[6:7], v[32:33] op_sel_hi:[1,0] neg_lo:[0,1] neg_hi:[0,1]
	v_pk_mul_f32 v[4:5], v[4:5], v[42:43] op_sel_hi:[1,0]
	v_pk_mul_f32 v[6:7], v[6:7], v[42:43] op_sel_hi:[1,0]
	v_pk_add_f32 v[0:1], v[0:1], v[32:33] op_sel_hi:[1,0] neg_lo:[0,1] neg_hi:[0,1]
	v_pk_add_f32 v[2:3], v[2:3], v[32:33] op_sel_hi:[1,0] neg_lo:[0,1] neg_hi:[0,1]
	v_pk_mul_f32 v[0:1], v[0:1], v[42:43] op_sel_hi:[1,0]
	v_pk_mul_f32 v[2:3], v[2:3], v[42:43] op_sel_hi:[1,0]
	v_cmp_lt_i32_e64 s[12:13], s36, v60
	s_or_b64 s[18:19], s[12:13], s[18:19]
	v_pk_fma_f32 v[8:9], v[188:189], v[8:9], v[204:205]
	v_pk_fma_f32 v[10:11], v[190:191], v[10:11], v[206:207]
	global_store_dwordx4 v[44:45], v[8:11], off offset:16
	v_pk_fma_f32 v[4:5], v[192:193], v[4:5], v[208:209]
	v_pk_fma_f32 v[6:7], v[194:195], v[6:7], v[210:211]
	global_store_dwordx4 v[44:45], v[4:7], off offset:32
	v_pk_fma_f32 v[0:1], v[0:1], v[196:197], v[212:213]
	v_pk_fma_f32 v[2:3], v[2:3], v[198:199], v[214:215]
	global_store_dwordx4 v[44:45], v[0:3], off offset:48
	s_andn2_b64 exec, exec, s[18:19]
	s_cbranch_execz .LBB0_1211
